# ATT: boundary units (first/last block of a sequence) also use the hand-written path with a per-block validity select; old compiler rb loop removed
# speedup vs baseline: 1.0810x; 1.0142x over previous
; __device__ void att_phase(int wv, const Params& p, unsigned char* lds) {
;     ...
; #pragma unroll
;         for (int ps = 0; ps < 6; ++ps) { const int idx = tid + ps * NTHR, s = idx >> 3, c8 = (idx & 7) * 8; const int kb = B - 1 + (s >> 7);
;             bf16x8 kv = {0, 0, 0, 0, 0, 0, 0, 0}, vv = {0, 0, 0, 0, 0, 0, 0, 0};
;             if (kb >= sb && kb < se) { const bf16_t* rp = qkv + (size_t)(kb * 128 + (s & 127)) * 1536 + 64 * kh + c8; kv = *(const bf16x8*)(rp + 1024); vv = *(const bf16x8*)(rp + 1280); }
;             *(bf16x8*)(KL + s * KP + c8) = kv;
; #pragma unroll
;             for (int e = 0; e < 8; ++e) VTL[(c8 + e) * VP + s] = (bf16_t)vv[e]; }
;         __syncthreads();
;         const int gq = w >> 1, h = 4 * kh + gq;
;         const float slope = exp2f(-0.5f * (float)(h + 1)), sink = p.b_sinks[h];
;         for (int rb = 0; rb < 4; ++rb) {
;             const int qrow = 64 * (w & 1) + 16 * rb + lr;
;             const size_t tokq = (size_t)B * 128 + qrow;
;             bf16x8 qf[2];
; #pragma unroll
;             for (int kk = 0; kk < 2; ++kk) qf[kk] = *(const bf16x8*)(qkv + tokq * 1536 + 64 * h + 32 * kk + 8 * lq);
.Latt_ld_5:
	s_or_b64 exec, exec, s[0:1]
	s_mov_b32 s22, 0
	s_lshl_b32 s6, s6, 2
	s_add_i32 s6, s6, s16
	s_add_i32 s7, s6, 1
	s_waitcnt vmcnt(0)
	ds_write_b128 v129, v[180:183]
	ds_write_b16 v130, v184 offset:55296
	ds_write_b16_d16_hi v130, v184 offset:56080
	ds_write_b16 v130, v185 offset:56864
	ds_write_b16_d16_hi v130, v185 offset:57648
	ds_write_b16 v130, v186 offset:58432
	ds_write_b16_d16_hi v130, v186 offset:59216
	ds_write_b16 v130, v187 offset:60000
	ds_write_b16_d16_hi v130, v187 offset:60784
	ds_write_b128 v131, v[188:191]
	ds_write_b16 v132, v192 offset:55296
	ds_write_b16_d16_hi v132, v192 offset:56080
	ds_write_b16 v132, v193 offset:56864
	ds_write_b16_d16_hi v132, v193 offset:57648
	ds_write_b16 v132, v194 offset:58432
	ds_write_b16_d16_hi v132, v194 offset:59216
	ds_write_b16 v132, v195 offset:60000
	ds_write_b16_d16_hi v132, v195 offset:60784
	ds_write_b128 v133, v[196:199]
	ds_write_b16 v134, v200 offset:55296
	ds_write_b16_d16_hi v134, v200 offset:56080
	ds_write_b16 v134, v201 offset:56864
	ds_write_b16_d16_hi v134, v201 offset:57648
	ds_write_b16 v134, v202 offset:58432
	ds_write_b16_d16_hi v134, v202 offset:59216
	ds_write_b16 v134, v203 offset:60000
	ds_write_b16_d16_hi v134, v203 offset:60784
	ds_write_b128 v135, v[204:207]
	ds_write_b16 v136, v208 offset:55296
	ds_write_b16_d16_hi v136, v208 offset:56080
	ds_write_b16 v136, v209 offset:56864
	ds_write_b16_d16_hi v136, v209 offset:57648
	ds_write_b16 v136, v210 offset:58432
	ds_write_b16_d16_hi v136, v210 offset:59216
	ds_write_b16 v136, v211 offset:60000
	ds_write_b16_d16_hi v136, v211 offset:60784
	ds_write_b128 v137, v[212:215]
	ds_write_b16 v138, v216 offset:55296
	ds_write_b16_d16_hi v138, v216 offset:56080
	ds_write_b16 v138, v217 offset:56864
	ds_write_b16_d16_hi v138, v217 offset:57648
	ds_write_b16 v138, v218 offset:58432
	ds_write_b16_d16_hi v138, v218 offset:59216
	ds_write_b16 v138, v219 offset:60000
	ds_write_b16_d16_hi v138, v219 offset:60784
	ds_write_b128 v139, v[220:223]
	ds_write_b16 v140, v224 offset:55296
	ds_write_b16_d16_hi v140, v224 offset:56080
	ds_write_b16 v140, v225 offset:56864
	ds_write_b16_d16_hi v140, v225 offset:57648
	ds_write_b16 v140, v226 offset:58432
	ds_write_b16_d16_hi v140, v226 offset:59216
	ds_write_b16 v140, v227 offset:60000
	ds_write_b16_d16_hi v140, v227 offset:60784
	v_cvt_f32_i32_e32 v2, s7
	s_and_b32 s0, s20, 3
	s_lshl_b32 s0, s0, 8
	s_add_i32 s0, s17, s0
	s_ashr_i32 s1, s0, 31
	v_mul_f32_e32 v3, -0.5, v2
	s_mov_b32 s7, 0xc2fc0000
	s_lshl_b64 s[0:1], s[0:1], 1
	v_cmp_gt_f32_e32 vcc, s7, v3
	s_and_b64 s[14:15], vcc, exec
	s_cselect_b32 s14, 0xffffffc0, 0
	s_ashr_i32 s7, s6, 31
	s_lshl_b64 s[6:7], s[6:7], 2
	s_add_u32 s6, s58, s6
	s_addc_u32 s7, s59, s7
	s_waitcnt lgkmcnt(0)
	s_barrier
	global_load_dword v146, v0, s[6:7]
	v_mov_b32_e32 v3, 0x42800000
	v_cndmask_b32_e32 v3, 0, v3, vcc
	v_fmac_f32_e32 v3, -0.5, v2
	v_exp_f32_e32 v2, v3
	s_cmp_gt_i32 s23, s11
	s_cselect_b64 s[6:7], -1, 0
	s_cmp_le_i32 s23, s10
	v_ldexp_f32 v109, v2, s14
	s_cselect_b64 s[14:15], -1, 0
	s_and_b64 s[6:7], s[6:7], s[14:15]
	s_cmp_ge_i32 s23, s11
	s_cselect_b64 s[14:15], -1, 0
	s_cmp_lt_i32 s23, s10
	s_cselect_b64 s[46:47], -1, 0
	s_and_b64 s[14:15], s[14:15], s[46:47]
	s_add_i32 s36, s23, 1
	s_cmp_ge_i32 s36, s11
	s_cselect_b64 s[46:47], -1, 0
	s_cmp_lt_i32 s36, s10
	s_cselect_b64 s[10:11], -1, 0
	v_mov_b32_e32 v2, 0x60000
	s_and_b64 s[10:11], s[46:47], s[10:11]
	v_mad_i64_i32 v[110:111], s[46:47], s23, v2, v[104:105]
	v_mad_i64_i32 v[112:113], s[46:47], s23, v2, v[106:107]
	v_mov_b32_e32 v147, v128
	s_mov_b64 s[48:49], 0xc000
	v_lshl_add_u64 v[174:175], v[110:111], 0, s[0:1]
	v_add_co_u32_e32 v174, vcc, 0x83ec000, v174
	s_nop 1
	v_addc_co_u32_e32 v175, vcc, 0, v175, vcc
	global_load_dwordx4 v[180:183], v[174:175], off offset:1536
	global_load_dwordx4 v[184:187], v[174:175], off offset:1600
	v_lshl_add_u64 v[174:175], v[174:175], 0, s[48:49]
	global_load_dwordx4 v[188:191], v[174:175], off offset:1536
	global_load_dwordx4 v[192:195], v[174:175], off offset:1600
	v_lshl_add_u64 v[174:175], v[174:175], 0, s[48:49]
	global_load_dwordx4 v[196:199], v[174:175], off offset:1536
	global_load_dwordx4 v[200:203], v[174:175], off offset:1600
	v_lshl_add_u64 v[174:175], v[174:175], 0, s[48:49]
	global_load_dwordx4 v[204:207], v[174:175], off offset:1536
	global_load_dwordx4 v[208:211], v[174:175], off offset:1600
	s_and_b64 vcc, s[6:7], s[10:11]
	s_cbranch_vccz .Latt_general
; __device__ __forceinline__ f32x4 mfma16(bf16x8 a, bf16x8 b, f32x4 c) { return __builtin_amdgcn_mfma_f32_16x16x32_bf16(a, b, c, 0, 0, 0); }
; __device__ void att_phase(int wv, const Params& p, unsigned char* lds) {
;     ...
;         const int gq = w >> 1, h = 4 * kh + gq;
;         const float slope = exp2f(-0.5f * (float)(h + 1)), sink = p.b_sinks[h];
;         for (int rb = 0; rb < 4; ++rb) {
;             const int qrow = 64 * (w & 1) + 16 * rb + lr;
;             const size_t tokq = (size_t)B * 128 + qrow;
;             bf16x8 qf[2];
; #pragma unroll
;             for (int kk = 0; kk < 2; ++kk) qf[kk] = *(const bf16x8*)(qkv + tokq * 1536 + 64 * h + 32 * kk + 8 * lq);
;             f32x4 sc[24];
; #pragma unroll
;             for (int cb = 0; cb < 24; ++cb) { f32x4 a = {0, 0, 0, 0};
; #pragma unroll
;                 for (int kk = 0; kk < 2; ++kk) { const bf16x8 kf = *(const bf16x8*)(KL + (16 * cb + lr) * KP + 32 * kk + 8 * lq); a = mfma16(kf, qf[kk], a); }
;                 sc[cb] = a; }
;             float mx = sink;
; #pragma unroll
;             for (int cb = 0; cb < 24; ++cb) { const int kb = B - 1 + (cb >> 3); const bool bval = (kb >= sb && kb < se);
; #pragma unroll
;                 for (int j = 0; j < 4; ++j) { const int krel = 16 * cb + 4 * lq + j - 128;
;                     int dist = qrow - krel; dist = dist < 0 ? -dist : dist;
;                     const float v = (bval && dist <= 128) ? sc[cb][j] * 0.125f - slope * (float)dist : -1e30f;
;                     sc[cb][j] = v; mx = fmaxf(mx, v); } }
	s_waitcnt vmcnt(0)
	s_mov_b32 s46, 0x3e38aa3b
	s_and_b32 s47, s33, 1
	s_mul_i32 s22, s47, 0x2400
	v_add_u32_e32 v164, s22, v141
	s_lshl_b32 s22, s47, 7
	s_add_i32 s22, s22, 0xd800
	v_add_u32_e32 v165, s22, v142
	v_add_u32_e32 v166, s22, v143
	v_add_u32_e32 v167, s22, v144
	v_add_u32_e32 v168, s22, v145
	s_lshl_b32 s47, s47, 2
	v_and_b32_e32 v172, 15, v250
	v_lshrrev_b32_e32 v173, 4, v250
	v_lshlrev_b32_e32 v173, 2, v173
	v_sub_u32_e32 v108, v172, v173
	v_subrev_u32_e32 v110, 1, v108
	v_subrev_u32_e32 v111, 2, v108
	v_subrev_u32_e32 v177, 3, v108
	v_mul_f32_e32 v147, 0xc1000000, v109
	v_mul_f32_e32 v174, 0x43000000, v109
	v_mul_f32_e32 v176, 0x44800000, v109
	v_cvt_f32_i32_e32 v179, v108
	v_mul_f32_e32 v94, v147, v179
	v_mul_f32_e64 v98, v147, |v179|
	v_cvt_f32_i32_e32 v179, v110
	v_mul_f32_e32 v95, v147, v179
	v_mul_f32_e64 v99, v147, |v179|
	v_cvt_f32_i32_e32 v179, v111
	v_mul_f32_e32 v96, v147, v179
	v_mul_f32_e64 v100, v147, |v179|
	v_cvt_f32_i32_e32 v179, v177
	v_mul_f32_e32 v97, v147, v179
	v_mul_f32_e64 v101, v147, |v179|
	v_lshl_add_u64 v[248:249], v[112:113], 0, s[0:1]
	v_sub_f32_e32 v86, v94, v176
	v_sub_f32_e32 v87, v95, v176
	v_sub_f32_e32 v88, v96, v176
	v_sub_f32_e32 v89, v97, v176
	v_cmp_ge_i32_e32 vcc, 0, v108
	s_nop 1
	v_cndmask_b32_e32 v212, v252, v86, vcc
	v_cmp_ge_i32_e32 vcc, 0, v110
	s_nop 1
	v_cndmask_b32_e32 v213, v252, v87, vcc
	v_cmp_ge_i32_e32 vcc, 0, v111
	s_nop 1
	v_cndmask_b32_e32 v214, v252, v88, vcc
	v_cmp_ge_i32_e32 vcc, 0, v177
	s_nop 1
	v_cndmask_b32_e32 v215, v252, v89, vcc
	ds_read_b128 v[148:151], v164 offset:0
	ds_read_b128 v[152:155], v164 offset:64
	ds_read_b128 v[156:159], v164 offset:2304
	ds_read_b128 v[160:163], v164 offset:2368
	v_add_f32_e32 v90, v86, v174
	v_add_f32_e32 v91, v87, v174
	v_add_f32_e32 v92, v88, v174
	v_add_f32_e32 v93, v89, v174
	s_waitcnt lgkmcnt(2)
	v_mfma_f32_16x16x32_bf16 v[2:5], v[148:151], v[180:183], v[212:215]
	v_mfma_f32_16x16x32_bf16 v[2:5], v[152:155], v[184:187], v[2:5]
	ds_read_b128 v[148:151], v164 offset:4608
	ds_read_b128 v[152:155], v164 offset:4672
	v_add_f32_e32 v86, v90, v174
	v_add_f32_e32 v87, v91, v174
	v_add_f32_e32 v88, v92, v174
	v_add_f32_e32 v89, v93, v174
	s_waitcnt lgkmcnt(2)
	v_mfma_f32_16x16x32_bf16 v[6:9], v[156:159], v[180:183], v[90:93]
	v_mfma_f32_16x16x32_bf16 v[6:9], v[160:163], v[184:187], v[6:9]
	ds_read_b128 v[156:159], v164 offset:6912
	ds_read_b128 v[160:163], v164 offset:6976
	v_add_f32_e32 v90, v86, v174
	v_add_f32_e32 v91, v87, v174
	v_add_f32_e32 v92, v88, v174
	v_add_f32_e32 v93, v89, v174
	s_waitcnt lgkmcnt(2)
	v_mfma_f32_16x16x32_bf16 v[10:13], v[148:151], v[180:183], v[86:89]
	v_mfma_f32_16x16x32_bf16 v[10:13], v[152:155], v[184:187], v[10:13]
	ds_read_b128 v[148:151], v164 offset:9216
	ds_read_b128 v[152:155], v164 offset:9280
	v_add_f32_e32 v86, v90, v174
	v_add_f32_e32 v87, v91, v174
	v_add_f32_e32 v88, v92, v174
	v_add_f32_e32 v89, v93, v174
	s_waitcnt lgkmcnt(2)
	v_mfma_f32_16x16x32_bf16 v[14:17], v[156:159], v[180:183], v[90:93]
	v_mfma_f32_16x16x32_bf16 v[14:17], v[160:163], v[184:187], v[14:17]
	ds_read_b128 v[156:159], v164 offset:11520
	ds_read_b128 v[160:163], v164 offset:11584
	v_add_f32_e32 v90, v86, v174
	v_add_f32_e32 v91, v87, v174
	v_add_f32_e32 v92, v88, v174
	v_add_f32_e32 v93, v89, v174
	s_waitcnt lgkmcnt(2)
	v_mfma_f32_16x16x32_bf16 v[18:21], v[148:151], v[180:183], v[86:89]
	v_mfma_f32_16x16x32_bf16 v[18:21], v[152:155], v[184:187], v[18:21]
	ds_read_b128 v[148:151], v164 offset:13824
	ds_read_b128 v[152:155], v164 offset:13888
	v_add_f32_e32 v86, v90, v174
	v_add_f32_e32 v87, v91, v174
	v_add_f32_e32 v88, v92, v174
	v_add_f32_e32 v89, v93, v174
	s_waitcnt lgkmcnt(2)
	v_mfma_f32_16x16x32_bf16 v[22:25], v[156:159], v[180:183], v[90:93]
	v_mfma_f32_16x16x32_bf16 v[22:25], v[160:163], v[184:187], v[22:25]
	ds_read_b128 v[156:159], v164 offset:16128
	ds_read_b128 v[160:163], v164 offset:16192
	v_add_f32_e32 v90, v86, v174
	v_add_f32_e32 v91, v87, v174
	v_add_f32_e32 v92, v88, v174
	v_add_f32_e32 v93, v89, v174
	s_waitcnt lgkmcnt(2)
	v_mfma_f32_16x16x32_bf16 v[26:29], v[148:151], v[180:183], v[86:89]
	v_mfma_f32_16x16x32_bf16 v[26:29], v[152:155], v[184:187], v[26:29]
	ds_read_b128 v[148:151], v164 offset:18432
	ds_read_b128 v[152:155], v164 offset:18496
	s_waitcnt lgkmcnt(2)
	v_mfma_f32_16x16x32_bf16 v[30:33], v[156:159], v[180:183], v[90:93]
	v_mfma_f32_16x16x32_bf16 v[30:33], v[160:163], v[184:187], v[30:33]
	ds_read_b128 v[156:159], v164 offset:20736
	ds_read_b128 v[160:163], v164 offset:20800
	v_sub_f32_e64 v86, -v94, v174
	v_sub_f32_e64 v87, -v95, v174
	v_sub_f32_e64 v88, -v96, v174
	v_sub_f32_e64 v89, -v97, v174
	s_waitcnt lgkmcnt(2)
	v_mfma_f32_16x16x32_bf16 v[34:37], v[148:151], v[180:183], v[98:101]
	v_mfma_f32_16x16x32_bf16 v[34:37], v[152:155], v[184:187], v[34:37]
	ds_read_b128 v[148:151], v164 offset:23040
	ds_read_b128 v[152:155], v164 offset:23104
	v_sub_f32_e32 v90, v86, v174
	v_sub_f32_e32 v91, v87, v174
	v_sub_f32_e32 v92, v88, v174
	v_sub_f32_e32 v93, v89, v174
	s_waitcnt lgkmcnt(2)
	v_mfma_f32_16x16x32_bf16 v[38:41], v[156:159], v[180:183], v[86:89]
	v_mfma_f32_16x16x32_bf16 v[38:41], v[160:163], v[184:187], v[38:41]
	ds_read_b128 v[156:159], v164 offset:25344
	ds_read_b128 v[160:163], v164 offset:25408
	v_sub_f32_e32 v86, v90, v174
	v_sub_f32_e32 v87, v91, v174
	v_sub_f32_e32 v88, v92, v174
	v_sub_f32_e32 v89, v93, v174
	s_waitcnt lgkmcnt(2)
	v_mfma_f32_16x16x32_bf16 v[42:45], v[148:151], v[180:183], v[90:93]
	v_mfma_f32_16x16x32_bf16 v[42:45], v[152:155], v[184:187], v[42:45]
	ds_read_b128 v[148:151], v164 offset:27648
	ds_read_b128 v[152:155], v164 offset:27712
	v_sub_f32_e32 v90, v86, v174
	v_sub_f32_e32 v91, v87, v174
	v_sub_f32_e32 v92, v88, v174
	v_sub_f32_e32 v93, v89, v174
	s_waitcnt lgkmcnt(2)
; __device__ __forceinline__ f32x4 mfma16(bf16x8 a, bf16x8 b, f32x4 c) { return __builtin_amdgcn_mfma_f32_16x16x32_bf16(a, b, c, 0, 0, 0); }
; __device__ void att_phase(int wv, const Params& p, unsigned char* lds) {
;     ...
;             for (int cb = 0; cb < 24; ++cb) { f32x4 a = {0, 0, 0, 0};
; #pragma unroll
;                 for (int kk = 0; kk < 2; ++kk) { const bf16x8 kf = *(const bf16x8*)(KL + (16 * cb + lr) * KP + 32 * kk + 8 * lq); a = mfma16(kf, qf[kk], a); }
;                 sc[cb] = a; }
;             float mx = sink;
; #pragma unroll
;             for (int cb = 0; cb < 24; ++cb) { const int kb = B - 1 + (cb >> 3); const bool bval = (kb >= sb && kb < se);
; #pragma unroll
;                 for (int j = 0; j < 4; ++j) { const int krel = 16 * cb + 4 * lq + j - 128;
;                     int dist = qrow - krel; dist = dist < 0 ? -dist : dist;
;                     const float v = (bval && dist <= 128) ? sc[cb][j] * 0.125f - slope * (float)dist : -1e30f;
;                     sc[cb][j] = v; mx = fmaxf(mx, v); } }
;             mx = fmaxf(mx, __shfl_xor(mx, 16)); mx = fmaxf(mx, __shfl_xor(mx, 32));
;             float sum = 0.f;
; #pragma unroll
;             for (int cb = 0; cb < 24; ++cb)
; #pragma unroll
;                 for (int j = 0; j < 4; ++j) { const float e = __expf(sc[cb][j] - mx); sc[cb][j] = e; sum += e; }
	v_mfma_f32_16x16x32_bf16 v[46:49], v[156:159], v[180:183], v[86:89]
	v_mfma_f32_16x16x32_bf16 v[46:49], v[160:163], v[184:187], v[46:49]
	ds_read_b128 v[156:159], v164 offset:29952
	ds_read_b128 v[160:163], v164 offset:30016
	v_sub_f32_e32 v86, v90, v174
	v_sub_f32_e32 v87, v91, v174
	v_sub_f32_e32 v88, v92, v174
	v_sub_f32_e32 v89, v93, v174
	s_waitcnt lgkmcnt(2)
	v_mfma_f32_16x16x32_bf16 v[50:53], v[148:151], v[180:183], v[90:93]
	v_mfma_f32_16x16x32_bf16 v[50:53], v[152:155], v[184:187], v[50:53]
	ds_read_b128 v[148:151], v164 offset:32256
	ds_read_b128 v[152:155], v164 offset:32320
	v_sub_f32_e32 v90, v86, v174
	v_sub_f32_e32 v91, v87, v174
	v_sub_f32_e32 v92, v88, v174
	v_sub_f32_e32 v93, v89, v174
	s_waitcnt lgkmcnt(2)
	v_mfma_f32_16x16x32_bf16 v[54:57], v[156:159], v[180:183], v[86:89]
	v_mfma_f32_16x16x32_bf16 v[54:57], v[160:163], v[184:187], v[54:57]
	ds_read_b128 v[156:159], v164 offset:34560
	ds_read_b128 v[160:163], v164 offset:34624
	v_sub_f32_e32 v86, v90, v174
	v_sub_f32_e32 v87, v91, v174
	v_sub_f32_e32 v88, v92, v174
	v_sub_f32_e32 v89, v93, v174
	s_waitcnt lgkmcnt(2)
	v_mfma_f32_16x16x32_bf16 v[58:61], v[148:151], v[180:183], v[90:93]
	v_mfma_f32_16x16x32_bf16 v[58:61], v[152:155], v[184:187], v[58:61]
	ds_read_b128 v[148:151], v164 offset:36864
	ds_read_b128 v[152:155], v164 offset:36928
	v_sub_f32_e32 v90, v86, v174
	v_sub_f32_e32 v91, v87, v174
	v_sub_f32_e32 v92, v88, v174
	v_sub_f32_e32 v93, v89, v174
	v_cmp_le_i32_e32 vcc, 0, v108
	s_nop 1
	v_cndmask_b32_e32 v212, v252, v90, vcc
	v_cmp_le_i32_e32 vcc, 0, v110
	s_nop 1
	v_cndmask_b32_e32 v213, v252, v91, vcc
	v_cmp_le_i32_e32 vcc, 0, v111
	s_nop 1
	v_cndmask_b32_e32 v214, v252, v92, vcc
	v_cmp_le_i32_e32 vcc, 0, v177
	s_nop 1
	v_cndmask_b32_e32 v215, v252, v93, vcc
	s_waitcnt lgkmcnt(2)
	v_mfma_f32_16x16x32_bf16 v[62:65], v[156:159], v[180:183], v[86:89]
	v_mfma_f32_16x16x32_bf16 v[62:65], v[160:163], v[184:187], v[62:65]
	s_waitcnt lgkmcnt(0)
	v_mfma_f32_16x16x32_bf16 v[66:69], v[148:151], v[180:183], v[212:215]
	v_mfma_f32_16x16x32_bf16 v[66:69], v[152:155], v[184:187], v[66:69]
	ds_read2_b64 v[216:219], v165 offset0:0 offset1:4
	ds_read2_b64 v[220:223], v166 offset0:0 offset1:4
	ds_read2_b64 v[224:227], v167 offset0:0 offset1:4
	ds_read2_b64 v[228:231], v168 offset0:0 offset1:4
	v_max3_f32 v169, v2, v3, v4
	v_max3_f32 v172, v5, v6, v7
	v_max3_f32 v169, v8, v9, v169
	v_max3_f32 v172, v10, v11, v172
	v_max3_f32 v169, v12, v13, v169
	v_max3_f32 v172, v14, v15, v172
	v_max3_f32 v169, v16, v17, v169
	v_max3_f32 v172, v18, v19, v172
	v_max3_f32 v169, v20, v21, v169
	v_max3_f32 v172, v22, v23, v172
	v_max3_f32 v169, v24, v25, v169
	v_max3_f32 v172, v26, v27, v172
	v_max3_f32 v169, v28, v29, v169
	v_max3_f32 v172, v30, v31, v172
	v_max3_f32 v169, v32, v33, v169
	v_max3_f32 v172, v34, v35, v172
	v_max3_f32 v169, v36, v37, v169
	v_max3_f32 v172, v38, v39, v172
	v_max3_f32 v169, v40, v41, v169
	v_max3_f32 v172, v42, v43, v172
	v_max3_f32 v169, v44, v45, v169
	v_max3_f32 v172, v46, v47, v172
	v_max3_f32 v169, v48, v49, v169
	v_max3_f32 v172, v50, v51, v172
	v_max3_f32 v169, v52, v53, v169
	v_max3_f32 v172, v54, v55, v172
	v_max3_f32 v169, v56, v57, v169
	v_max3_f32 v172, v58, v59, v172
	v_max3_f32 v169, v60, v61, v169
	v_max3_f32 v172, v62, v63, v172
	v_max3_f32 v169, v64, v65, v169
	v_max3_f32 v172, v66, v67, v172
	v_max3_f32 v169, v68, v69, v169
	v_max_f32_e32 v169, v169, v172
	v_mul_f32_e32 v169, 0x3e000000, v169
	v_max_f32_e32 v169, v169, v146
	ds_bpermute_b32 v172, v1, v169
	s_waitcnt lgkmcnt(0)
	v_max_f32_e32 v169, v169, v172
	ds_bpermute_b32 v172, v114, v169
	s_waitcnt lgkmcnt(0)
	v_max_f32_e32 v169, v169, v172
	v_mul_f32_e32 v175, 0xbfb8aa3b, v169
	v_mov_b32_e32 v170, 0
	v_mov_b32_e32 v171, 0
	v_fma_f32 v2, v2, s46, v175
	v_fma_f32 v3, v3, s46, v175
	v_fma_f32 v4, v4, s46, v175
	v_fma_f32 v5, v5, s46, v175
	v_exp_f32_e32 v2, v2
	v_exp_f32_e32 v3, v3
	v_exp_f32_e32 v4, v4
	v_exp_f32_e32 v5, v5
	v_fma_f32 v6, v6, s46, v175
	v_fma_f32 v7, v7, s46, v175
	v_fma_f32 v8, v8, s46, v175
	v_fma_f32 v9, v9, s46, v175
	v_exp_f32_e32 v6, v6
	v_exp_f32_e32 v7, v7
	v_exp_f32_e32 v8, v8
	v_exp_f32_e32 v9, v9
	v_add_f32_e32 v171, v171, v2
	v_add_f32_e32 v170, v170, v3
	v_add_f32_e32 v171, v171, v4
	v_add_f32_e32 v170, v170, v5
	v_fma_f32 v10, v10, s46, v175
	v_fma_f32 v11, v11, s46, v175
	v_fma_f32 v12, v12, s46, v175
	v_fma_f32 v13, v13, s46, v175
	v_exp_f32_e32 v10, v10
	v_exp_f32_e32 v11, v11
	v_exp_f32_e32 v12, v12
	v_exp_f32_e32 v13, v13
	v_add_f32_e32 v171, v171, v6
	v_add_f32_e32 v170, v170, v7
	v_add_f32_e32 v171, v171, v8
	v_add_f32_e32 v170, v170, v9
	v_fma_f32 v14, v14, s46, v175
	v_fma_f32 v15, v15, s46, v175
	v_fma_f32 v16, v16, s46, v175
	v_fma_f32 v17, v17, s46, v175
	v_exp_f32_e32 v14, v14
	v_exp_f32_e32 v15, v15
	v_exp_f32_e32 v16, v16
	v_exp_f32_e32 v17, v17
	v_add_f32_e32 v171, v171, v10
	v_add_f32_e32 v170, v170, v11
	v_add_f32_e32 v171, v171, v12
	v_add_f32_e32 v170, v170, v13
	v_fma_f32 v18, v18, s46, v175
	v_fma_f32 v19, v19, s46, v175
	v_fma_f32 v20, v20, s46, v175
	v_fma_f32 v21, v21, s46, v175
	v_exp_f32_e32 v18, v18
	v_exp_f32_e32 v19, v19
	v_exp_f32_e32 v20, v20
	v_exp_f32_e32 v21, v21
	v_add_f32_e32 v171, v171, v14
	v_add_f32_e32 v170, v170, v15
	v_add_f32_e32 v171, v171, v16
	v_add_f32_e32 v170, v170, v17
	v_fma_f32 v22, v22, s46, v175
	v_fma_f32 v23, v23, s46, v175
	v_fma_f32 v24, v24, s46, v175
	v_fma_f32 v25, v25, s46, v175
	v_exp_f32_e32 v22, v22
	v_exp_f32_e32 v23, v23
	v_exp_f32_e32 v24, v24
	v_exp_f32_e32 v25, v25
	v_add_f32_e32 v171, v171, v18
	v_add_f32_e32 v170, v170, v19
	v_add_f32_e32 v171, v171, v20
	v_add_f32_e32 v170, v170, v21
; __device__ __forceinline__ unsigned cvt_pk_bf16_asm(float lo, float hi) { unsigned r; asm volatile("v_cvt_pk_bf16_f32 %0, %1, %2" : "=v"(r) : "v"(lo), "v"(hi)); return r; }
; __device__ void att_phase(int wv, const Params& p, unsigned char* lds) {
;     ...
;             for (int cb = 0; cb < 24; ++cb)
; #pragma unroll
;                 for (int j = 0; j < 4; ++j) { const float e = __expf(sc[cb][j] - mx); sc[cb][j] = e; sum += e; }
;             sum += __shfl_xor(sum, 16); sum += __shfl_xor(sum, 32);
;             sum += __expf(sink - mx);
;             const float inv = 1.0f / sum;
;             f32x4 oa[4];
; #pragma unroll
;             for (int db = 0; db < 4; ++db) oa[db] = (f32x4){0, 0, 0, 0};
; #pragma unroll
;             for (int ks = 0; ks < 12; ++ks) {
;                 union { bf16x8 v; unsigned u[4]; } pf;
;                 pf.u[0] = cvt_pk_bf16_asm(sc[2 * ks][0], sc[2 * ks][1]); pf.u[1] = cvt_pk_bf16_asm(sc[2 * ks][2], sc[2 * ks][3]);
;                 pf.u[2] = cvt_pk_bf16_asm(sc[2 * ks + 1][0], sc[2 * ks + 1][1]); pf.u[3] = cvt_pk_bf16_asm(sc[2 * ks + 1][2], sc[2 * ks + 1][3]);
	v_fma_f32 v26, v26, s46, v175
	v_fma_f32 v27, v27, s46, v175
	v_fma_f32 v28, v28, s46, v175
	v_fma_f32 v29, v29, s46, v175
	v_exp_f32_e32 v26, v26
	v_exp_f32_e32 v27, v27
	v_exp_f32_e32 v28, v28
	v_exp_f32_e32 v29, v29
	v_add_f32_e32 v171, v171, v22
	v_add_f32_e32 v170, v170, v23
	v_add_f32_e32 v171, v171, v24
	v_add_f32_e32 v170, v170, v25
	v_fma_f32 v30, v30, s46, v175
	v_fma_f32 v31, v31, s46, v175
	v_fma_f32 v32, v32, s46, v175
	v_fma_f32 v33, v33, s46, v175
	v_exp_f32_e32 v30, v30
	v_exp_f32_e32 v31, v31
	v_exp_f32_e32 v32, v32
	v_exp_f32_e32 v33, v33
	v_add_f32_e32 v171, v171, v26
	v_add_f32_e32 v170, v170, v27
	v_add_f32_e32 v171, v171, v28
	v_add_f32_e32 v170, v170, v29
	v_fma_f32 v34, v34, s46, v175
	v_fma_f32 v35, v35, s46, v175
	v_fma_f32 v36, v36, s46, v175
	v_fma_f32 v37, v37, s46, v175
	v_exp_f32_e32 v34, v34
	v_exp_f32_e32 v35, v35
	v_exp_f32_e32 v36, v36
	v_exp_f32_e32 v37, v37
	v_add_f32_e32 v171, v171, v30
	v_add_f32_e32 v170, v170, v31
	v_add_f32_e32 v171, v171, v32
	v_add_f32_e32 v170, v170, v33
	v_fma_f32 v38, v38, s46, v175
	v_fma_f32 v39, v39, s46, v175
	v_fma_f32 v40, v40, s46, v175
	v_fma_f32 v41, v41, s46, v175
	v_exp_f32_e32 v38, v38
	v_exp_f32_e32 v39, v39
	v_exp_f32_e32 v40, v40
	v_exp_f32_e32 v41, v41
	v_add_f32_e32 v171, v171, v34
	v_add_f32_e32 v170, v170, v35
	v_add_f32_e32 v171, v171, v36
	v_add_f32_e32 v170, v170, v37
	v_fma_f32 v42, v42, s46, v175
	v_fma_f32 v43, v43, s46, v175
	v_fma_f32 v44, v44, s46, v175
	v_fma_f32 v45, v45, s46, v175
	v_exp_f32_e32 v42, v42
	v_exp_f32_e32 v43, v43
	v_exp_f32_e32 v44, v44
	v_exp_f32_e32 v45, v45
	v_add_f32_e32 v171, v171, v38
	v_add_f32_e32 v170, v170, v39
	v_add_f32_e32 v171, v171, v40
	v_add_f32_e32 v170, v170, v41
	v_fma_f32 v46, v46, s46, v175
	v_fma_f32 v47, v47, s46, v175
	v_fma_f32 v48, v48, s46, v175
	v_fma_f32 v49, v49, s46, v175
	v_exp_f32_e32 v46, v46
	v_exp_f32_e32 v47, v47
	v_exp_f32_e32 v48, v48
	v_exp_f32_e32 v49, v49
	v_add_f32_e32 v171, v171, v42
	v_add_f32_e32 v170, v170, v43
	v_add_f32_e32 v171, v171, v44
	v_add_f32_e32 v170, v170, v45
	v_fma_f32 v50, v50, s46, v175
	v_fma_f32 v51, v51, s46, v175
	v_fma_f32 v52, v52, s46, v175
	v_fma_f32 v53, v53, s46, v175
	v_exp_f32_e32 v50, v50
	v_exp_f32_e32 v51, v51
	v_exp_f32_e32 v52, v52
	v_exp_f32_e32 v53, v53
	v_add_f32_e32 v171, v171, v46
	v_add_f32_e32 v170, v170, v47
	v_add_f32_e32 v171, v171, v48
	v_add_f32_e32 v170, v170, v49
	v_fma_f32 v54, v54, s46, v175
	v_fma_f32 v55, v55, s46, v175
	v_fma_f32 v56, v56, s46, v175
	v_fma_f32 v57, v57, s46, v175
	v_exp_f32_e32 v54, v54
	v_exp_f32_e32 v55, v55
	v_exp_f32_e32 v56, v56
	v_exp_f32_e32 v57, v57
	v_add_f32_e32 v171, v171, v50
	v_add_f32_e32 v170, v170, v51
	v_add_f32_e32 v171, v171, v52
	v_add_f32_e32 v170, v170, v53
	v_fma_f32 v58, v58, s46, v175
	v_fma_f32 v59, v59, s46, v175
	v_fma_f32 v60, v60, s46, v175
	v_fma_f32 v61, v61, s46, v175
	v_exp_f32_e32 v58, v58
	v_exp_f32_e32 v59, v59
	v_exp_f32_e32 v60, v60
	v_exp_f32_e32 v61, v61
	v_add_f32_e32 v171, v171, v54
	v_add_f32_e32 v170, v170, v55
	v_add_f32_e32 v171, v171, v56
	v_add_f32_e32 v170, v170, v57
	v_fma_f32 v62, v62, s46, v175
	v_fma_f32 v63, v63, s46, v175
	v_fma_f32 v64, v64, s46, v175
	v_fma_f32 v65, v65, s46, v175
	v_exp_f32_e32 v62, v62
	v_exp_f32_e32 v63, v63
	v_exp_f32_e32 v64, v64
	v_exp_f32_e32 v65, v65
	v_add_f32_e32 v171, v171, v58
	v_add_f32_e32 v170, v170, v59
	v_add_f32_e32 v171, v171, v60
	v_add_f32_e32 v170, v170, v61
	v_fma_f32 v66, v66, s46, v175
	v_fma_f32 v67, v67, s46, v175
	v_fma_f32 v68, v68, s46, v175
	v_fma_f32 v69, v69, s46, v175
	v_exp_f32_e32 v66, v66
	v_exp_f32_e32 v67, v67
	v_exp_f32_e32 v68, v68
	v_exp_f32_e32 v69, v69
	v_add_f32_e32 v171, v171, v62
	v_add_f32_e32 v170, v170, v63
	v_add_f32_e32 v171, v171, v64
	v_add_f32_e32 v170, v170, v65
	v_add_f32_e32 v171, v171, v66
	v_add_f32_e32 v170, v170, v67
	v_add_f32_e32 v171, v171, v68
	v_add_f32_e32 v170, v170, v69
	v_add_f32_e32 v170, v170, v171
	v_cvt_pk_bf16_f32 v2, v2, v3
	v_cvt_pk_bf16_f32 v3, v4, v5
	v_cvt_pk_bf16_f32 v4, v6, v7
	v_cvt_pk_bf16_f32 v5, v8, v9
	v_cvt_pk_bf16_f32 v10, v10, v11
	v_cvt_pk_bf16_f32 v11, v12, v13
	v_cvt_pk_bf16_f32 v12, v14, v15
	v_cvt_pk_bf16_f32 v13, v16, v17
	v_cvt_pk_bf16_f32 v18, v18, v19
	v_cvt_pk_bf16_f32 v19, v20, v21
	v_cvt_pk_bf16_f32 v20, v22, v23
	v_cvt_pk_bf16_f32 v21, v24, v25
	v_cvt_pk_bf16_f32 v26, v26, v27
	v_cvt_pk_bf16_f32 v27, v28, v29
	v_cvt_pk_bf16_f32 v28, v30, v31
	v_cvt_pk_bf16_f32 v29, v32, v33
	v_cvt_pk_bf16_f32 v34, v34, v35
	v_cvt_pk_bf16_f32 v35, v36, v37
	v_cvt_pk_bf16_f32 v36, v38, v39
	v_cvt_pk_bf16_f32 v37, v40, v41
	v_cvt_pk_bf16_f32 v42, v42, v43
	v_cvt_pk_bf16_f32 v43, v44, v45
	v_cvt_pk_bf16_f32 v44, v46, v47
	v_cvt_pk_bf16_f32 v45, v48, v49
	v_cvt_pk_bf16_f32 v50, v50, v51
	v_cvt_pk_bf16_f32 v51, v52, v53
	v_cvt_pk_bf16_f32 v52, v54, v55
	v_cvt_pk_bf16_f32 v53, v56, v57
	v_cvt_pk_bf16_f32 v58, v58, v59
	v_cvt_pk_bf16_f32 v59, v60, v61
	v_cvt_pk_bf16_f32 v60, v62, v63
	v_cvt_pk_bf16_f32 v61, v64, v65
	v_cvt_pk_bf16_f32 v66, v66, v67
	v_cvt_pk_bf16_f32 v67, v68, v69
	v_mov_b32_e32 v68, 0
	v_mov_b32_e32 v69, 0
	ds_bpermute_b32 v172, v1, v170
	v_sub_f32_e32 v173, v146, v169
	v_mul_f32_e32 v173, 0x3fb8aa3b, v173
	v_exp_f32_e32 v173, v173
	s_waitcnt lgkmcnt(0)
	v_add_f32_e32 v170, v170, v172
	ds_bpermute_b32 v172, v114, v170
	ds_read2_b64 v[232:235], v165 offset0:8 offset1:12
	ds_read2_b64 v[236:239], v166 offset0:8 offset1:12
	ds_read2_b64 v[240:243], v167 offset0:8 offset1:12
	ds_read2_b64 v[244:247], v168 offset0:8 offset1:12
	s_waitcnt lgkmcnt(4)
; __device__ __forceinline__ unsigned cvt_pk_bf16_asm(float lo, float hi) { unsigned r; asm volatile("v_cvt_pk_bf16_f32 %0, %1, %2" : "=v"(r) : "v"(lo), "v"(hi)); return r; }
; __device__ void att_phase(int wv, const Params& p, unsigned char* lds) {
;     ...
;             f32x4 sc[24];
; #pragma unroll
;             for (int cb = 0; cb < 24; ++cb) { f32x4 a = {0, 0, 0, 0};
; #pragma unroll
;                 for (int kk = 0; kk < 2; ++kk) { const bf16x8 kf = *(const bf16x8*)(KL + (16 * cb + lr) * KP + 32 * kk + 8 * lq); a = mfma16(kf, qf[kk], a); }
;                 sc[cb] = a; }
;             float mx = sink;
; #pragma unroll
;             for (int cb = 0; cb < 24; ++cb) { const int kb = B - 1 + (cb >> 3); const bool bval = (kb >= sb && kb < se);
; #pragma unroll
;                 for (int j = 0; j < 4; ++j) { const int krel = 16 * cb + 4 * lq + j - 128;
;                     int dist = qrow - krel; dist = dist < 0 ? -dist : dist;
;                     const float v = (bval && dist <= 128) ? sc[cb][j] * 0.125f - slope * (float)dist : -1e30f;
;                     sc[cb][j] = v; mx = fmaxf(mx, v); } }
;     ...
;             sum += __expf(sink - mx);
;             const float inv = 1.0f / sum;
;             f32x4 oa[4];
; #pragma unroll
;             for (int db = 0; db < 4; ++db) oa[db] = (f32x4){0, 0, 0, 0};
; #pragma unroll
;             for (int ks = 0; ks < 12; ++ks) {
;                 union { bf16x8 v; unsigned u[4]; } pf;
;                 pf.u[0] = cvt_pk_bf16_asm(sc[2 * ks][0], sc[2 * ks][1]); pf.u[1] = cvt_pk_bf16_asm(sc[2 * ks][2], sc[2 * ks][3]);
;                 pf.u[2] = cvt_pk_bf16_asm(sc[2 * ks + 1][0], sc[2 * ks + 1][1]); pf.u[3] = cvt_pk_bf16_asm(sc[2 * ks + 1][2], sc[2 * ks + 1][3]);
; #pragma unroll
;                 for (int db = 0; db < 4; ++db) {
;                     union { bf16x8 v; u32x2 h2[2]; } vf;
;                     const bf16_t* vp = VTL + (16 * db + lr) * VP + 32 * ks + 4 * lq;
;                     vf.h2[0] = *(const u32x2*)vp; vf.h2[1] = *(const u32x2*)(vp + 16);
;                     oa[db] = mfma16(vf.v, pf.v, oa[db]); } }
; #pragma unroll
;             for (int db = 0; db < 4; ++db) { const f32x4 o = oa[db] * inv; u32x2 wv; wv.x = cvt_pk_bf16_asm(o[0], o[1]); wv.y = cvt_pk_bf16_asm(o[2], o[3]);
;                 *(u32x2*)(qkv + tokq * 1536 + 64 * h + 16 * db + 4 * lq) = wv; }
	v_mfma_f32_16x16x32_bf16 v[70:73], v[216:219], v[2:5], 0
	v_mfma_f32_16x16x32_bf16 v[74:77], v[220:223], v[2:5], 0
	v_mfma_f32_16x16x32_bf16 v[78:81], v[224:227], v[2:5], 0
	v_mfma_f32_16x16x32_bf16 v[82:85], v[228:231], v[2:5], 0
	v_add_f32_e32 v170, v170, v172
	v_add_f32_e32 v170, v170, v173
	v_rcp_f32_e32 v147, v170
	s_nop 0
	v_fma_f32 v179, -v170, v147, 1.0
	v_fmac_f32_e32 v147, v179, v147
	ds_read2_b64 v[216:219], v165 offset0:16 offset1:20
	ds_read2_b64 v[220:223], v166 offset0:16 offset1:20
	ds_read2_b64 v[224:227], v167 offset0:16 offset1:20
	ds_read2_b64 v[228:231], v168 offset0:16 offset1:20
	s_waitcnt lgkmcnt(4)
	v_mfma_f32_16x16x32_bf16 v[70:73], v[232:235], v[10:13], v[70:73]
	v_mfma_f32_16x16x32_bf16 v[74:77], v[236:239], v[10:13], v[74:77]
	v_mfma_f32_16x16x32_bf16 v[78:81], v[240:243], v[10:13], v[78:81]
	v_mfma_f32_16x16x32_bf16 v[82:85], v[244:247], v[10:13], v[82:85]
	ds_read2_b64 v[232:235], v165 offset0:24 offset1:28
	ds_read2_b64 v[236:239], v166 offset0:24 offset1:28
	ds_read2_b64 v[240:243], v167 offset0:24 offset1:28
	ds_read2_b64 v[244:247], v168 offset0:24 offset1:28
	s_waitcnt lgkmcnt(4)
	v_mfma_f32_16x16x32_bf16 v[70:73], v[216:219], v[18:21], v[70:73]
	v_mfma_f32_16x16x32_bf16 v[74:77], v[220:223], v[18:21], v[74:77]
	v_mfma_f32_16x16x32_bf16 v[78:81], v[224:227], v[18:21], v[78:81]
	v_mfma_f32_16x16x32_bf16 v[82:85], v[228:231], v[18:21], v[82:85]
	ds_read2_b64 v[216:219], v165 offset0:32 offset1:36
	ds_read2_b64 v[220:223], v166 offset0:32 offset1:36
	ds_read2_b64 v[224:227], v167 offset0:32 offset1:36
	ds_read2_b64 v[228:231], v168 offset0:32 offset1:36
	s_waitcnt lgkmcnt(4)
	v_mfma_f32_16x16x32_bf16 v[70:73], v[232:235], v[26:29], v[70:73]
	v_mfma_f32_16x16x32_bf16 v[74:77], v[236:239], v[26:29], v[74:77]
	v_mfma_f32_16x16x32_bf16 v[78:81], v[240:243], v[26:29], v[78:81]
	v_mfma_f32_16x16x32_bf16 v[82:85], v[244:247], v[26:29], v[82:85]
	ds_read2_b64 v[232:235], v165 offset0:40 offset1:44
	ds_read2_b64 v[236:239], v166 offset0:40 offset1:44
	ds_read2_b64 v[240:243], v167 offset0:40 offset1:44
	ds_read2_b64 v[244:247], v168 offset0:40 offset1:44
	s_waitcnt lgkmcnt(4)
	v_mfma_f32_16x16x32_bf16 v[70:73], v[216:219], v[34:37], v[70:73]
	v_mfma_f32_16x16x32_bf16 v[74:77], v[220:223], v[34:37], v[74:77]
	v_mfma_f32_16x16x32_bf16 v[78:81], v[224:227], v[34:37], v[78:81]
	v_mfma_f32_16x16x32_bf16 v[82:85], v[228:231], v[34:37], v[82:85]
	ds_read2_b64 v[216:219], v165 offset0:48 offset1:52
	ds_read2_b64 v[220:223], v166 offset0:48 offset1:52
	ds_read2_b64 v[224:227], v167 offset0:48 offset1:52
	ds_read2_b64 v[228:231], v168 offset0:48 offset1:52
	s_waitcnt lgkmcnt(4)
	v_mfma_f32_16x16x32_bf16 v[70:73], v[232:235], v[42:45], v[70:73]
	v_mfma_f32_16x16x32_bf16 v[74:77], v[236:239], v[42:45], v[74:77]
	v_mfma_f32_16x16x32_bf16 v[78:81], v[240:243], v[42:45], v[78:81]
	v_mfma_f32_16x16x32_bf16 v[82:85], v[244:247], v[42:45], v[82:85]
	ds_read2_b64 v[232:235], v165 offset0:56 offset1:60
	ds_read2_b64 v[236:239], v166 offset0:56 offset1:60
	ds_read2_b64 v[240:243], v167 offset0:56 offset1:60
	ds_read2_b64 v[244:247], v168 offset0:56 offset1:60
	s_waitcnt lgkmcnt(4)
	v_mfma_f32_16x16x32_bf16 v[70:73], v[216:219], v[50:53], v[70:73]
	v_mfma_f32_16x16x32_bf16 v[74:77], v[220:223], v[50:53], v[74:77]
	v_mfma_f32_16x16x32_bf16 v[78:81], v[224:227], v[50:53], v[78:81]
	v_mfma_f32_16x16x32_bf16 v[82:85], v[228:231], v[50:53], v[82:85]
	ds_read2_b64 v[216:219], v165 offset0:64 offset1:64
	ds_read2_b64 v[220:223], v166 offset0:64 offset1:64
	ds_read2_b64 v[224:227], v167 offset0:64 offset1:64
	ds_read2_b64 v[228:231], v168 offset0:64 offset1:64
	s_waitcnt lgkmcnt(4)
	v_mfma_f32_16x16x32_bf16 v[70:73], v[232:235], v[58:61], v[70:73]
	v_mfma_f32_16x16x32_bf16 v[74:77], v[236:239], v[58:61], v[74:77]
	v_mfma_f32_16x16x32_bf16 v[78:81], v[240:243], v[58:61], v[78:81]
	v_mfma_f32_16x16x32_bf16 v[82:85], v[244:247], v[58:61], v[82:85]
	s_waitcnt lgkmcnt(0)
	v_mfma_f32_16x16x32_bf16 v[70:73], v[216:219], v[66:69], v[70:73]
	v_mfma_f32_16x16x32_bf16 v[74:77], v[220:223], v[66:69], v[74:77]
	v_mfma_f32_16x16x32_bf16 v[78:81], v[224:227], v[66:69], v[78:81]
	v_mfma_f32_16x16x32_bf16 v[82:85], v[228:231], v[66:69], v[82:85]
	s_nop 7
	s_nop 1
	v_mul_f32_e32 v70, v70, v147
	v_mul_f32_e32 v71, v71, v147
	v_mul_f32_e32 v72, v72, v147
	v_mul_f32_e32 v73, v73, v147
	v_mul_f32_e32 v74, v74, v147
	v_mul_f32_e32 v75, v75, v147
	v_mul_f32_e32 v76, v76, v147
	v_mul_f32_e32 v77, v77, v147
	v_mul_f32_e32 v78, v78, v147
	v_mul_f32_e32 v79, v79, v147
	v_mul_f32_e32 v80, v80, v147
	v_mul_f32_e32 v81, v81, v147
	v_mul_f32_e32 v82, v82, v147
	v_mul_f32_e32 v83, v83, v147
	v_mul_f32_e32 v84, v84, v147
	v_mul_f32_e32 v85, v85, v147
	v_cvt_pk_bf16_f32 v70, v70, v71
	v_cvt_pk_bf16_f32 v71, v72, v73
	v_cvt_pk_bf16_f32 v74, v74, v75
	v_cvt_pk_bf16_f32 v75, v76, v77
	v_cvt_pk_bf16_f32 v78, v78, v79
	v_cvt_pk_bf16_f32 v79, v80, v81
	v_cvt_pk_bf16_f32 v82, v82, v83
	v_cvt_pk_bf16_f32 v83, v84, v85
	global_store_dwordx2 v[248:249], v[70:71], off offset:-64
	global_store_dwordx2 v[248:249], v[74:75], off offset:-32
	global_store_dwordx2 v[248:249], v[78:79], off
	global_store_dwordx2 v[248:249], v[82:83], off offset:32
	v_lshl_add_u64 v[248:249], v[248:249], 0, s[48:49]
	v_sub_f32_e32 v86, v94, v176
	v_sub_f32_e32 v87, v95, v176
	v_sub_f32_e32 v88, v96, v176
	v_sub_f32_e32 v89, v97, v176
	v_cmp_ge_i32_e32 vcc, 0, v108
	s_nop 1
	v_cndmask_b32_e32 v212, v252, v86, vcc
	v_cmp_ge_i32_e32 vcc, 0, v110
	s_nop 1
	v_cndmask_b32_e32 v213, v252, v87, vcc
	v_cmp_ge_i32_e32 vcc, 0, v111
	s_nop 1
	v_cndmask_b32_e32 v214, v252, v88, vcc
	v_cmp_ge_i32_e32 vcc, 0, v177
	s_nop 1
	v_cndmask_b32_e32 v215, v252, v89, vcc
	ds_read_b128 v[148:151], v164 offset:2304
	ds_read_b128 v[152:155], v164 offset:2368
	ds_read_b128 v[156:159], v164 offset:4608
	ds_read_b128 v[160:163], v164 offset:4672
	v_add_f32_e32 v90, v86, v174
	v_add_f32_e32 v91, v87, v174
	v_add_f32_e32 v92, v88, v174
	v_add_f32_e32 v93, v89, v174
	s_waitcnt lgkmcnt(2)
; __device__ __forceinline__ f32x4 mfma16(bf16x8 a, bf16x8 b, f32x4 c) { return __builtin_amdgcn_mfma_f32_16x16x32_bf16(a, b, c, 0, 0, 0); }
; __device__ void att_phase(int wv, const Params& p, unsigned char* lds) {
;     ...
;             f32x4 sc[24];
; #pragma unroll
;             for (int cb = 0; cb < 24; ++cb) { f32x4 a = {0, 0, 0, 0};
; #pragma unroll
;                 for (int kk = 0; kk < 2; ++kk) { const bf16x8 kf = *(const bf16x8*)(KL + (16 * cb + lr) * KP + 32 * kk + 8 * lq); a = mfma16(kf, qf[kk], a); }
;                 sc[cb] = a; }
;             float mx = sink;
; #pragma unroll
;             for (int cb = 0; cb < 24; ++cb) { const int kb = B - 1 + (cb >> 3); const bool bval = (kb >= sb && kb < se);
; #pragma unroll
;                 for (int j = 0; j < 4; ++j) { const int krel = 16 * cb + 4 * lq + j - 128;
;                     int dist = qrow - krel; dist = dist < 0 ? -dist : dist;
;                     const float v = (bval && dist <= 128) ? sc[cb][j] * 0.125f - slope * (float)dist : -1e30f;
;                     sc[cb][j] = v; mx = fmaxf(mx, v); } }
	v_mfma_f32_16x16x32_bf16 v[2:5], v[148:151], v[188:191], v[212:215]
	v_mfma_f32_16x16x32_bf16 v[2:5], v[152:155], v[192:195], v[2:5]
	ds_read_b128 v[148:151], v164 offset:6912
	ds_read_b128 v[152:155], v164 offset:6976
	v_add_f32_e32 v86, v90, v174
	v_add_f32_e32 v87, v91, v174
	v_add_f32_e32 v88, v92, v174
	v_add_f32_e32 v89, v93, v174
	s_waitcnt lgkmcnt(2)
	v_mfma_f32_16x16x32_bf16 v[6:9], v[156:159], v[188:191], v[90:93]
	v_mfma_f32_16x16x32_bf16 v[6:9], v[160:163], v[192:195], v[6:9]
	ds_read_b128 v[156:159], v164 offset:9216
	ds_read_b128 v[160:163], v164 offset:9280
	v_add_f32_e32 v90, v86, v174
	v_add_f32_e32 v91, v87, v174
	v_add_f32_e32 v92, v88, v174
	v_add_f32_e32 v93, v89, v174
	s_waitcnt lgkmcnt(2)
	v_mfma_f32_16x16x32_bf16 v[10:13], v[148:151], v[188:191], v[86:89]
	v_mfma_f32_16x16x32_bf16 v[10:13], v[152:155], v[192:195], v[10:13]
	ds_read_b128 v[148:151], v164 offset:11520
	ds_read_b128 v[152:155], v164 offset:11584
	v_add_f32_e32 v86, v90, v174
	v_add_f32_e32 v87, v91, v174
	v_add_f32_e32 v88, v92, v174
	v_add_f32_e32 v89, v93, v174
	s_waitcnt lgkmcnt(2)
	v_mfma_f32_16x16x32_bf16 v[14:17], v[156:159], v[188:191], v[90:93]
	v_mfma_f32_16x16x32_bf16 v[14:17], v[160:163], v[192:195], v[14:17]
	ds_read_b128 v[156:159], v164 offset:13824
	ds_read_b128 v[160:163], v164 offset:13888
	v_add_f32_e32 v90, v86, v174
	v_add_f32_e32 v91, v87, v174
	v_add_f32_e32 v92, v88, v174
	v_add_f32_e32 v93, v89, v174
	s_waitcnt lgkmcnt(2)
	v_mfma_f32_16x16x32_bf16 v[18:21], v[148:151], v[188:191], v[86:89]
	v_mfma_f32_16x16x32_bf16 v[18:21], v[152:155], v[192:195], v[18:21]
	ds_read_b128 v[148:151], v164 offset:16128
	ds_read_b128 v[152:155], v164 offset:16192
	v_add_f32_e32 v86, v90, v174
	v_add_f32_e32 v87, v91, v174
	v_add_f32_e32 v88, v92, v174
	v_add_f32_e32 v89, v93, v174
	s_waitcnt lgkmcnt(2)
	v_mfma_f32_16x16x32_bf16 v[22:25], v[156:159], v[188:191], v[90:93]
	v_mfma_f32_16x16x32_bf16 v[22:25], v[160:163], v[192:195], v[22:25]
	ds_read_b128 v[156:159], v164 offset:18432
	ds_read_b128 v[160:163], v164 offset:18496
	v_add_f32_e32 v90, v86, v174
	v_add_f32_e32 v91, v87, v174
	v_add_f32_e32 v92, v88, v174
	v_add_f32_e32 v93, v89, v174
	s_waitcnt lgkmcnt(2)
	v_mfma_f32_16x16x32_bf16 v[26:29], v[148:151], v[188:191], v[86:89]
	v_mfma_f32_16x16x32_bf16 v[26:29], v[152:155], v[192:195], v[26:29]
	ds_read_b128 v[148:151], v164 offset:20736
	ds_read_b128 v[152:155], v164 offset:20800
	s_waitcnt lgkmcnt(2)
	v_mfma_f32_16x16x32_bf16 v[30:33], v[156:159], v[188:191], v[90:93]
	v_mfma_f32_16x16x32_bf16 v[30:33], v[160:163], v[192:195], v[30:33]
	ds_read_b128 v[156:159], v164 offset:23040
	ds_read_b128 v[160:163], v164 offset:23104
	v_sub_f32_e64 v86, -v94, v174
	v_sub_f32_e64 v87, -v95, v174
	v_sub_f32_e64 v88, -v96, v174
	v_sub_f32_e64 v89, -v97, v174
	s_waitcnt lgkmcnt(2)
	v_mfma_f32_16x16x32_bf16 v[34:37], v[148:151], v[188:191], v[98:101]
	v_mfma_f32_16x16x32_bf16 v[34:37], v[152:155], v[192:195], v[34:37]
	ds_read_b128 v[148:151], v164 offset:25344
	ds_read_b128 v[152:155], v164 offset:25408
	v_sub_f32_e32 v90, v86, v174
	v_sub_f32_e32 v91, v87, v174
	v_sub_f32_e32 v92, v88, v174
	v_sub_f32_e32 v93, v89, v174
	s_waitcnt lgkmcnt(2)
	v_mfma_f32_16x16x32_bf16 v[38:41], v[156:159], v[188:191], v[86:89]
	v_mfma_f32_16x16x32_bf16 v[38:41], v[160:163], v[192:195], v[38:41]
	ds_read_b128 v[156:159], v164 offset:27648
	ds_read_b128 v[160:163], v164 offset:27712
	v_sub_f32_e32 v86, v90, v174
	v_sub_f32_e32 v87, v91, v174
	v_sub_f32_e32 v88, v92, v174
	v_sub_f32_e32 v89, v93, v174
	s_waitcnt lgkmcnt(2)
	v_mfma_f32_16x16x32_bf16 v[42:45], v[148:151], v[188:191], v[90:93]
	v_mfma_f32_16x16x32_bf16 v[42:45], v[152:155], v[192:195], v[42:45]
	ds_read_b128 v[148:151], v164 offset:29952
	ds_read_b128 v[152:155], v164 offset:30016
	v_sub_f32_e32 v90, v86, v174
	v_sub_f32_e32 v91, v87, v174
	v_sub_f32_e32 v92, v88, v174
	v_sub_f32_e32 v93, v89, v174
	s_waitcnt lgkmcnt(2)
	v_mfma_f32_16x16x32_bf16 v[46:49], v[156:159], v[188:191], v[86:89]
	v_mfma_f32_16x16x32_bf16 v[46:49], v[160:163], v[192:195], v[46:49]
	ds_read_b128 v[156:159], v164 offset:32256
	ds_read_b128 v[160:163], v164 offset:32320
	v_sub_f32_e32 v86, v90, v174
	v_sub_f32_e32 v87, v91, v174
	v_sub_f32_e32 v88, v92, v174
	v_sub_f32_e32 v89, v93, v174
	s_waitcnt lgkmcnt(2)
	v_mfma_f32_16x16x32_bf16 v[50:53], v[148:151], v[188:191], v[90:93]
	v_mfma_f32_16x16x32_bf16 v[50:53], v[152:155], v[192:195], v[50:53]
	ds_read_b128 v[148:151], v164 offset:34560
	ds_read_b128 v[152:155], v164 offset:34624
	v_sub_f32_e32 v90, v86, v174
	v_sub_f32_e32 v91, v87, v174
	v_sub_f32_e32 v92, v88, v174
	v_sub_f32_e32 v93, v89, v174
	s_waitcnt lgkmcnt(2)
	v_mfma_f32_16x16x32_bf16 v[54:57], v[156:159], v[188:191], v[86:89]
	v_mfma_f32_16x16x32_bf16 v[54:57], v[160:163], v[192:195], v[54:57]
	ds_read_b128 v[156:159], v164 offset:36864
	ds_read_b128 v[160:163], v164 offset:36928
	v_sub_f32_e32 v86, v90, v174
	v_sub_f32_e32 v87, v91, v174
	v_sub_f32_e32 v88, v92, v174
	v_sub_f32_e32 v89, v93, v174
	s_waitcnt lgkmcnt(2)
	v_mfma_f32_16x16x32_bf16 v[58:61], v[148:151], v[188:191], v[90:93]
	v_mfma_f32_16x16x32_bf16 v[58:61], v[152:155], v[192:195], v[58:61]
	ds_read_b128 v[148:151], v164 offset:39168
	ds_read_b128 v[152:155], v164 offset:39232
	v_sub_f32_e32 v90, v86, v174
	v_sub_f32_e32 v91, v87, v174
	v_sub_f32_e32 v92, v88, v174
	v_sub_f32_e32 v93, v89, v174
	v_cmp_le_i32_e32 vcc, 0, v108
	s_nop 1
	v_cndmask_b32_e32 v212, v252, v90, vcc
	v_cmp_le_i32_e32 vcc, 0, v110
	s_nop 1
	v_cndmask_b32_e32 v213, v252, v91, vcc
	v_cmp_le_i32_e32 vcc, 0, v111
	s_nop 1
	v_cndmask_b32_e32 v214, v252, v92, vcc
	v_cmp_le_i32_e32 vcc, 0, v177
	s_nop 1
	v_cndmask_b32_e32 v215, v252, v93, vcc
	s_waitcnt lgkmcnt(2)
; __device__ __forceinline__ f32x4 mfma16(bf16x8 a, bf16x8 b, f32x4 c) { return __builtin_amdgcn_mfma_f32_16x16x32_bf16(a, b, c, 0, 0, 0); }
; __device__ void att_phase(int wv, const Params& p, unsigned char* lds) {
;     ...
;             for (int cb = 0; cb < 24; ++cb) { f32x4 a = {0, 0, 0, 0};
; #pragma unroll
;                 for (int kk = 0; kk < 2; ++kk) { const bf16x8 kf = *(const bf16x8*)(KL + (16 * cb + lr) * KP + 32 * kk + 8 * lq); a = mfma16(kf, qf[kk], a); }
;                 sc[cb] = a; }
;             float mx = sink;
; #pragma unroll
;             for (int cb = 0; cb < 24; ++cb) { const int kb = B - 1 + (cb >> 3); const bool bval = (kb >= sb && kb < se);
; #pragma unroll
;                 for (int j = 0; j < 4; ++j) { const int krel = 16 * cb + 4 * lq + j - 128;
;                     int dist = qrow - krel; dist = dist < 0 ? -dist : dist;
;                     const float v = (bval && dist <= 128) ? sc[cb][j] * 0.125f - slope * (float)dist : -1e30f;
;                     sc[cb][j] = v; mx = fmaxf(mx, v); } }
;             mx = fmaxf(mx, __shfl_xor(mx, 16)); mx = fmaxf(mx, __shfl_xor(mx, 32));
;             float sum = 0.f;
; #pragma unroll
;             for (int cb = 0; cb < 24; ++cb)
; #pragma unroll
;                 for (int j = 0; j < 4; ++j) { const float e = __expf(sc[cb][j] - mx); sc[cb][j] = e; sum += e; }
	v_mfma_f32_16x16x32_bf16 v[62:65], v[156:159], v[188:191], v[86:89]
	v_mfma_f32_16x16x32_bf16 v[62:65], v[160:163], v[192:195], v[62:65]
	s_waitcnt lgkmcnt(0)
	v_mfma_f32_16x16x32_bf16 v[66:69], v[148:151], v[188:191], v[212:215]
	v_mfma_f32_16x16x32_bf16 v[66:69], v[152:155], v[192:195], v[66:69]
	ds_read2_b64 v[216:219], v165 offset0:4 offset1:8
	ds_read2_b64 v[220:223], v166 offset0:4 offset1:8
	ds_read2_b64 v[224:227], v167 offset0:4 offset1:8
	ds_read2_b64 v[228:231], v168 offset0:4 offset1:8
	v_max3_f32 v169, v2, v3, v4
	v_max3_f32 v172, v5, v6, v7
	v_max3_f32 v169, v8, v9, v169
	v_max3_f32 v172, v10, v11, v172
	v_max3_f32 v169, v12, v13, v169
	v_max3_f32 v172, v14, v15, v172
	v_max3_f32 v169, v16, v17, v169
	v_max3_f32 v172, v18, v19, v172
	v_max3_f32 v169, v20, v21, v169
	v_max3_f32 v172, v22, v23, v172
	v_max3_f32 v169, v24, v25, v169
	v_max3_f32 v172, v26, v27, v172
	v_max3_f32 v169, v28, v29, v169
	v_max3_f32 v172, v30, v31, v172
	v_max3_f32 v169, v32, v33, v169
	v_max3_f32 v172, v34, v35, v172
	v_max3_f32 v169, v36, v37, v169
	v_max3_f32 v172, v38, v39, v172
	v_max3_f32 v169, v40, v41, v169
	v_max3_f32 v172, v42, v43, v172
	v_max3_f32 v169, v44, v45, v169
	v_max3_f32 v172, v46, v47, v172
	v_max3_f32 v169, v48, v49, v169
	v_max3_f32 v172, v50, v51, v172
	v_max3_f32 v169, v52, v53, v169
	v_max3_f32 v172, v54, v55, v172
	v_max3_f32 v169, v56, v57, v169
	v_max3_f32 v172, v58, v59, v172
	v_max3_f32 v169, v60, v61, v169
	v_max3_f32 v172, v62, v63, v172
	v_max3_f32 v169, v64, v65, v169
	v_max3_f32 v172, v66, v67, v172
	v_max3_f32 v169, v68, v69, v169
	v_max_f32_e32 v169, v169, v172
	v_mul_f32_e32 v169, 0x3e000000, v169
	v_max_f32_e32 v169, v169, v146
	ds_bpermute_b32 v172, v1, v169
	s_waitcnt lgkmcnt(0)
	v_max_f32_e32 v169, v169, v172
	ds_bpermute_b32 v172, v114, v169
	s_waitcnt lgkmcnt(0)
	v_max_f32_e32 v169, v169, v172
	v_mul_f32_e32 v175, 0xbfb8aa3b, v169
	v_mov_b32_e32 v170, 0
	v_mov_b32_e32 v171, 0
	v_fma_f32 v2, v2, s46, v175
	v_fma_f32 v3, v3, s46, v175
	v_fma_f32 v4, v4, s46, v175
	v_fma_f32 v5, v5, s46, v175
	v_exp_f32_e32 v2, v2
	v_exp_f32_e32 v3, v3
	v_exp_f32_e32 v4, v4
	v_exp_f32_e32 v5, v5
	v_fma_f32 v6, v6, s46, v175
	v_fma_f32 v7, v7, s46, v175
	v_fma_f32 v8, v8, s46, v175
	v_fma_f32 v9, v9, s46, v175
	v_exp_f32_e32 v6, v6
	v_exp_f32_e32 v7, v7
	v_exp_f32_e32 v8, v8
	v_exp_f32_e32 v9, v9
	v_add_f32_e32 v171, v171, v2
	v_add_f32_e32 v170, v170, v3
	v_add_f32_e32 v171, v171, v4
	v_add_f32_e32 v170, v170, v5
	v_fma_f32 v10, v10, s46, v175
	v_fma_f32 v11, v11, s46, v175
	v_fma_f32 v12, v12, s46, v175
	v_fma_f32 v13, v13, s46, v175
	v_exp_f32_e32 v10, v10
	v_exp_f32_e32 v11, v11
	v_exp_f32_e32 v12, v12
	v_exp_f32_e32 v13, v13
	v_add_f32_e32 v171, v171, v6
	v_add_f32_e32 v170, v170, v7
	v_add_f32_e32 v171, v171, v8
	v_add_f32_e32 v170, v170, v9
	v_fma_f32 v14, v14, s46, v175
	v_fma_f32 v15, v15, s46, v175
	v_fma_f32 v16, v16, s46, v175
	v_fma_f32 v17, v17, s46, v175
	v_exp_f32_e32 v14, v14
	v_exp_f32_e32 v15, v15
	v_exp_f32_e32 v16, v16
	v_exp_f32_e32 v17, v17
	v_add_f32_e32 v171, v171, v10
	v_add_f32_e32 v170, v170, v11
	v_add_f32_e32 v171, v171, v12
	v_add_f32_e32 v170, v170, v13
	v_fma_f32 v18, v18, s46, v175
	v_fma_f32 v19, v19, s46, v175
	v_fma_f32 v20, v20, s46, v175
	v_fma_f32 v21, v21, s46, v175
	v_exp_f32_e32 v18, v18
	v_exp_f32_e32 v19, v19
	v_exp_f32_e32 v20, v20
	v_exp_f32_e32 v21, v21
	v_add_f32_e32 v171, v171, v14
	v_add_f32_e32 v170, v170, v15
	v_add_f32_e32 v171, v171, v16
	v_add_f32_e32 v170, v170, v17
	v_fma_f32 v22, v22, s46, v175
	v_fma_f32 v23, v23, s46, v175
	v_fma_f32 v24, v24, s46, v175
	v_fma_f32 v25, v25, s46, v175
	v_exp_f32_e32 v22, v22
	v_exp_f32_e32 v23, v23
	v_exp_f32_e32 v24, v24
	v_exp_f32_e32 v25, v25
	v_add_f32_e32 v171, v171, v18
	v_add_f32_e32 v170, v170, v19
	v_add_f32_e32 v171, v171, v20
	v_add_f32_e32 v170, v170, v21
	v_fma_f32 v26, v26, s46, v175
	v_fma_f32 v27, v27, s46, v175
	v_fma_f32 v28, v28, s46, v175
	v_fma_f32 v29, v29, s46, v175
	v_exp_f32_e32 v26, v26
	v_exp_f32_e32 v27, v27
	v_exp_f32_e32 v28, v28
	v_exp_f32_e32 v29, v29
	v_add_f32_e32 v171, v171, v22
	v_add_f32_e32 v170, v170, v23
	v_add_f32_e32 v171, v171, v24
	v_add_f32_e32 v170, v170, v25
	v_fma_f32 v30, v30, s46, v175
	v_fma_f32 v31, v31, s46, v175
	v_fma_f32 v32, v32, s46, v175
	v_fma_f32 v33, v33, s46, v175
	v_exp_f32_e32 v30, v30
	v_exp_f32_e32 v31, v31
	v_exp_f32_e32 v32, v32
	v_exp_f32_e32 v33, v33
	v_add_f32_e32 v171, v171, v26
	v_add_f32_e32 v170, v170, v27
	v_add_f32_e32 v171, v171, v28
	v_add_f32_e32 v170, v170, v29
	v_fma_f32 v34, v34, s46, v175
	v_fma_f32 v35, v35, s46, v175
	v_fma_f32 v36, v36, s46, v175
	v_fma_f32 v37, v37, s46, v175
	v_exp_f32_e32 v34, v34
	v_exp_f32_e32 v35, v35
	v_exp_f32_e32 v36, v36
	v_exp_f32_e32 v37, v37
	v_add_f32_e32 v171, v171, v30
	v_add_f32_e32 v170, v170, v31
	v_add_f32_e32 v171, v171, v32
	v_add_f32_e32 v170, v170, v33
	v_fma_f32 v38, v38, s46, v175
	v_fma_f32 v39, v39, s46, v175
	v_fma_f32 v40, v40, s46, v175
	v_fma_f32 v41, v41, s46, v175
	v_exp_f32_e32 v38, v38
	v_exp_f32_e32 v39, v39
	v_exp_f32_e32 v40, v40
	v_exp_f32_e32 v41, v41
	v_add_f32_e32 v171, v171, v34
	v_add_f32_e32 v170, v170, v35
	v_add_f32_e32 v171, v171, v36
	v_add_f32_e32 v170, v170, v37
	v_fma_f32 v42, v42, s46, v175
	v_fma_f32 v43, v43, s46, v175
	v_fma_f32 v44, v44, s46, v175
	v_fma_f32 v45, v45, s46, v175
	v_exp_f32_e32 v42, v42
	v_exp_f32_e32 v43, v43
	v_exp_f32_e32 v44, v44
	v_exp_f32_e32 v45, v45
	v_add_f32_e32 v171, v171, v38
	v_add_f32_e32 v170, v170, v39
	v_add_f32_e32 v171, v171, v40
	v_add_f32_e32 v170, v170, v41
	v_fma_f32 v46, v46, s46, v175
	v_fma_f32 v47, v47, s46, v175
; __device__ __forceinline__ unsigned cvt_pk_bf16_asm(float lo, float hi) { unsigned r; asm volatile("v_cvt_pk_bf16_f32 %0, %1, %2" : "=v"(r) : "v"(lo), "v"(hi)); return r; }
; __device__ __forceinline__ f32x4 mfma16(bf16x8 a, bf16x8 b, f32x4 c) { return __builtin_amdgcn_mfma_f32_16x16x32_bf16(a, b, c, 0, 0, 0); }
; __device__ void att_phase(int wv, const Params& p, unsigned char* lds) {
;     ...
;             for (int cb = 0; cb < 24; ++cb)
; #pragma unroll
;                 for (int j = 0; j < 4; ++j) { const float e = __expf(sc[cb][j] - mx); sc[cb][j] = e; sum += e; }
;             sum += __shfl_xor(sum, 16); sum += __shfl_xor(sum, 32);
;             sum += __expf(sink - mx);
;             const float inv = 1.0f / sum;
;             f32x4 oa[4];
; #pragma unroll
;             for (int db = 0; db < 4; ++db) oa[db] = (f32x4){0, 0, 0, 0};
; #pragma unroll
;             for (int ks = 0; ks < 12; ++ks) {
;                 union { bf16x8 v; unsigned u[4]; } pf;
;                 pf.u[0] = cvt_pk_bf16_asm(sc[2 * ks][0], sc[2 * ks][1]); pf.u[1] = cvt_pk_bf16_asm(sc[2 * ks][2], sc[2 * ks][3]);
;                 pf.u[2] = cvt_pk_bf16_asm(sc[2 * ks + 1][0], sc[2 * ks + 1][1]); pf.u[3] = cvt_pk_bf16_asm(sc[2 * ks + 1][2], sc[2 * ks + 1][3]);
; #pragma unroll
;                 for (int db = 0; db < 4; ++db) {
;                     union { bf16x8 v; u32x2 h2[2]; } vf;
;                     const bf16_t* vp = VTL + (16 * db + lr) * VP + 32 * ks + 4 * lq;
;                     vf.h2[0] = *(const u32x2*)vp; vf.h2[1] = *(const u32x2*)(vp + 16);
;                     oa[db] = mfma16(vf.v, pf.v, oa[db]); } }
	v_fma_f32 v48, v48, s46, v175
	v_fma_f32 v49, v49, s46, v175
	v_exp_f32_e32 v46, v46
	v_exp_f32_e32 v47, v47
	v_exp_f32_e32 v48, v48
	v_exp_f32_e32 v49, v49
	v_add_f32_e32 v171, v171, v42
	v_add_f32_e32 v170, v170, v43
	v_add_f32_e32 v171, v171, v44
	v_add_f32_e32 v170, v170, v45
	v_fma_f32 v50, v50, s46, v175
	v_fma_f32 v51, v51, s46, v175
	v_fma_f32 v52, v52, s46, v175
	v_fma_f32 v53, v53, s46, v175
	v_exp_f32_e32 v50, v50
	v_exp_f32_e32 v51, v51
	v_exp_f32_e32 v52, v52
	v_exp_f32_e32 v53, v53
	v_add_f32_e32 v171, v171, v46
	v_add_f32_e32 v170, v170, v47
	v_add_f32_e32 v171, v171, v48
	v_add_f32_e32 v170, v170, v49
	v_fma_f32 v54, v54, s46, v175
	v_fma_f32 v55, v55, s46, v175
	v_fma_f32 v56, v56, s46, v175
	v_fma_f32 v57, v57, s46, v175
	v_exp_f32_e32 v54, v54
	v_exp_f32_e32 v55, v55
	v_exp_f32_e32 v56, v56
	v_exp_f32_e32 v57, v57
	v_add_f32_e32 v171, v171, v50
	v_add_f32_e32 v170, v170, v51
	v_add_f32_e32 v171, v171, v52
	v_add_f32_e32 v170, v170, v53
	v_fma_f32 v58, v58, s46, v175
	v_fma_f32 v59, v59, s46, v175
	v_fma_f32 v60, v60, s46, v175
	v_fma_f32 v61, v61, s46, v175
	v_exp_f32_e32 v58, v58
	v_exp_f32_e32 v59, v59
	v_exp_f32_e32 v60, v60
	v_exp_f32_e32 v61, v61
	v_add_f32_e32 v171, v171, v54
	v_add_f32_e32 v170, v170, v55
	v_add_f32_e32 v171, v171, v56
	v_add_f32_e32 v170, v170, v57
	v_fma_f32 v62, v62, s46, v175
	v_fma_f32 v63, v63, s46, v175
	v_fma_f32 v64, v64, s46, v175
	v_fma_f32 v65, v65, s46, v175
	v_exp_f32_e32 v62, v62
	v_exp_f32_e32 v63, v63
	v_exp_f32_e32 v64, v64
	v_exp_f32_e32 v65, v65
	v_add_f32_e32 v171, v171, v58
	v_add_f32_e32 v170, v170, v59
	v_add_f32_e32 v171, v171, v60
	v_add_f32_e32 v170, v170, v61
	v_fma_f32 v66, v66, s46, v175
	v_fma_f32 v67, v67, s46, v175
	v_fma_f32 v68, v68, s46, v175
	v_fma_f32 v69, v69, s46, v175
	v_exp_f32_e32 v66, v66
	v_exp_f32_e32 v67, v67
	v_exp_f32_e32 v68, v68
	v_exp_f32_e32 v69, v69
	v_add_f32_e32 v171, v171, v62
	v_add_f32_e32 v170, v170, v63
	v_add_f32_e32 v171, v171, v64
	v_add_f32_e32 v170, v170, v65
	v_add_f32_e32 v171, v171, v66
	v_add_f32_e32 v170, v170, v67
	v_add_f32_e32 v171, v171, v68
	v_add_f32_e32 v170, v170, v69
	v_add_f32_e32 v170, v170, v171
	v_cvt_pk_bf16_f32 v2, v2, v3
	v_cvt_pk_bf16_f32 v3, v4, v5
	v_cvt_pk_bf16_f32 v4, v6, v7
	v_cvt_pk_bf16_f32 v5, v8, v9
	v_cvt_pk_bf16_f32 v10, v10, v11
	v_cvt_pk_bf16_f32 v11, v12, v13
	v_cvt_pk_bf16_f32 v12, v14, v15
	v_cvt_pk_bf16_f32 v13, v16, v17
	v_cvt_pk_bf16_f32 v18, v18, v19
	v_cvt_pk_bf16_f32 v19, v20, v21
	v_cvt_pk_bf16_f32 v20, v22, v23
	v_cvt_pk_bf16_f32 v21, v24, v25
	v_cvt_pk_bf16_f32 v26, v26, v27
	v_cvt_pk_bf16_f32 v27, v28, v29
	v_cvt_pk_bf16_f32 v28, v30, v31
	v_cvt_pk_bf16_f32 v29, v32, v33
	v_cvt_pk_bf16_f32 v34, v34, v35
	v_cvt_pk_bf16_f32 v35, v36, v37
	v_cvt_pk_bf16_f32 v36, v38, v39
	v_cvt_pk_bf16_f32 v37, v40, v41
	v_cvt_pk_bf16_f32 v42, v42, v43
	v_cvt_pk_bf16_f32 v43, v44, v45
	v_cvt_pk_bf16_f32 v44, v46, v47
	v_cvt_pk_bf16_f32 v45, v48, v49
	v_cvt_pk_bf16_f32 v50, v50, v51
	v_cvt_pk_bf16_f32 v51, v52, v53
	v_cvt_pk_bf16_f32 v52, v54, v55
	v_cvt_pk_bf16_f32 v53, v56, v57
	v_cvt_pk_bf16_f32 v58, v58, v59
	v_cvt_pk_bf16_f32 v59, v60, v61
	v_cvt_pk_bf16_f32 v60, v62, v63
	v_cvt_pk_bf16_f32 v61, v64, v65
	v_cvt_pk_bf16_f32 v66, v66, v67
	v_cvt_pk_bf16_f32 v67, v68, v69
	v_mov_b32_e32 v68, 0
	v_mov_b32_e32 v69, 0
	ds_bpermute_b32 v172, v1, v170
	v_sub_f32_e32 v173, v146, v169
	v_mul_f32_e32 v173, 0x3fb8aa3b, v173
	v_exp_f32_e32 v173, v173
	s_waitcnt lgkmcnt(0)
	v_add_f32_e32 v170, v170, v172
	ds_bpermute_b32 v172, v114, v170
	ds_read2_b64 v[232:235], v165 offset0:12 offset1:16
	ds_read2_b64 v[236:239], v166 offset0:12 offset1:16
	ds_read2_b64 v[240:243], v167 offset0:12 offset1:16
	ds_read2_b64 v[244:247], v168 offset0:12 offset1:16
	s_waitcnt lgkmcnt(4)
	v_mfma_f32_16x16x32_bf16 v[70:73], v[216:219], v[2:5], 0
	v_mfma_f32_16x16x32_bf16 v[74:77], v[220:223], v[2:5], 0
	v_mfma_f32_16x16x32_bf16 v[78:81], v[224:227], v[2:5], 0
	v_mfma_f32_16x16x32_bf16 v[82:85], v[228:231], v[2:5], 0
	v_add_f32_e32 v170, v170, v172
	v_add_f32_e32 v170, v170, v173
	v_rcp_f32_e32 v147, v170
	s_nop 0
	v_fma_f32 v179, -v170, v147, 1.0
	v_fmac_f32_e32 v147, v179, v147
	ds_read2_b64 v[216:219], v165 offset0:20 offset1:24
	ds_read2_b64 v[220:223], v166 offset0:20 offset1:24
	ds_read2_b64 v[224:227], v167 offset0:20 offset1:24
	ds_read2_b64 v[228:231], v168 offset0:20 offset1:24
	s_waitcnt lgkmcnt(4)
	v_mfma_f32_16x16x32_bf16 v[70:73], v[232:235], v[10:13], v[70:73]
	v_mfma_f32_16x16x32_bf16 v[74:77], v[236:239], v[10:13], v[74:77]
	v_mfma_f32_16x16x32_bf16 v[78:81], v[240:243], v[10:13], v[78:81]
	v_mfma_f32_16x16x32_bf16 v[82:85], v[244:247], v[10:13], v[82:85]
	ds_read2_b64 v[232:235], v165 offset0:28 offset1:32
	ds_read2_b64 v[236:239], v166 offset0:28 offset1:32
	ds_read2_b64 v[240:243], v167 offset0:28 offset1:32
	ds_read2_b64 v[244:247], v168 offset0:28 offset1:32
	s_waitcnt lgkmcnt(4)
	v_mfma_f32_16x16x32_bf16 v[70:73], v[216:219], v[18:21], v[70:73]
	v_mfma_f32_16x16x32_bf16 v[74:77], v[220:223], v[18:21], v[74:77]
	v_mfma_f32_16x16x32_bf16 v[78:81], v[224:227], v[18:21], v[78:81]
	v_mfma_f32_16x16x32_bf16 v[82:85], v[228:231], v[18:21], v[82:85]
	ds_read2_b64 v[216:219], v165 offset0:36 offset1:40
	ds_read2_b64 v[220:223], v166 offset0:36 offset1:40
	ds_read2_b64 v[224:227], v167 offset0:36 offset1:40
	ds_read2_b64 v[228:231], v168 offset0:36 offset1:40
	s_waitcnt lgkmcnt(4)
; __device__ __forceinline__ unsigned cvt_pk_bf16_asm(float lo, float hi) { unsigned r; asm volatile("v_cvt_pk_bf16_f32 %0, %1, %2" : "=v"(r) : "v"(lo), "v"(hi)); return r; }
; __device__ __forceinline__ f32x4 mfma16(bf16x8 a, bf16x8 b, f32x4 c) { return __builtin_amdgcn_mfma_f32_16x16x32_bf16(a, b, c, 0, 0, 0); }
; __device__ void att_phase(int wv, const Params& p, unsigned char* lds) {
;     ...
;             f32x4 sc[24];
; #pragma unroll
;             for (int cb = 0; cb < 24; ++cb) { f32x4 a = {0, 0, 0, 0};
; #pragma unroll
;                 for (int kk = 0; kk < 2; ++kk) { const bf16x8 kf = *(const bf16x8*)(KL + (16 * cb + lr) * KP + 32 * kk + 8 * lq); a = mfma16(kf, qf[kk], a); }
;                 sc[cb] = a; }
;             float mx = sink;
; #pragma unroll
;             for (int cb = 0; cb < 24; ++cb) { const int kb = B - 1 + (cb >> 3); const bool bval = (kb >= sb && kb < se);
; #pragma unroll
;                 for (int j = 0; j < 4; ++j) { const int krel = 16 * cb + 4 * lq + j - 128;
;                     int dist = qrow - krel; dist = dist < 0 ? -dist : dist;
;                     const float v = (bval && dist <= 128) ? sc[cb][j] * 0.125f - slope * (float)dist : -1e30f;
;                     sc[cb][j] = v; mx = fmaxf(mx, v); } }
;     ...
;             for (int ks = 0; ks < 12; ++ks) {
;                 union { bf16x8 v; unsigned u[4]; } pf;
;                 pf.u[0] = cvt_pk_bf16_asm(sc[2 * ks][0], sc[2 * ks][1]); pf.u[1] = cvt_pk_bf16_asm(sc[2 * ks][2], sc[2 * ks][3]);
;                 pf.u[2] = cvt_pk_bf16_asm(sc[2 * ks + 1][0], sc[2 * ks + 1][1]); pf.u[3] = cvt_pk_bf16_asm(sc[2 * ks + 1][2], sc[2 * ks + 1][3]);
; #pragma unroll
;                 for (int db = 0; db < 4; ++db) {
;                     union { bf16x8 v; u32x2 h2[2]; } vf;
;                     const bf16_t* vp = VTL + (16 * db + lr) * VP + 32 * ks + 4 * lq;
;                     vf.h2[0] = *(const u32x2*)vp; vf.h2[1] = *(const u32x2*)(vp + 16);
;                     oa[db] = mfma16(vf.v, pf.v, oa[db]); } }
; #pragma unroll
;             for (int db = 0; db < 4; ++db) { const f32x4 o = oa[db] * inv; u32x2 wv; wv.x = cvt_pk_bf16_asm(o[0], o[1]); wv.y = cvt_pk_bf16_asm(o[2], o[3]);
;                 *(u32x2*)(qkv + tokq * 1536 + 64 * h + 16 * db + 4 * lq) = wv; }
	v_mfma_f32_16x16x32_bf16 v[70:73], v[232:235], v[26:29], v[70:73]
	v_mfma_f32_16x16x32_bf16 v[74:77], v[236:239], v[26:29], v[74:77]
	v_mfma_f32_16x16x32_bf16 v[78:81], v[240:243], v[26:29], v[78:81]
	v_mfma_f32_16x16x32_bf16 v[82:85], v[244:247], v[26:29], v[82:85]
	ds_read2_b64 v[232:235], v165 offset0:44 offset1:48
	ds_read2_b64 v[236:239], v166 offset0:44 offset1:48
	ds_read2_b64 v[240:243], v167 offset0:44 offset1:48
	ds_read2_b64 v[244:247], v168 offset0:44 offset1:48
	s_waitcnt lgkmcnt(4)
	v_mfma_f32_16x16x32_bf16 v[70:73], v[216:219], v[34:37], v[70:73]
	v_mfma_f32_16x16x32_bf16 v[74:77], v[220:223], v[34:37], v[74:77]
	v_mfma_f32_16x16x32_bf16 v[78:81], v[224:227], v[34:37], v[78:81]
	v_mfma_f32_16x16x32_bf16 v[82:85], v[228:231], v[34:37], v[82:85]
	ds_read2_b64 v[216:219], v165 offset0:52 offset1:56
	ds_read2_b64 v[220:223], v166 offset0:52 offset1:56
	ds_read2_b64 v[224:227], v167 offset0:52 offset1:56
	ds_read2_b64 v[228:231], v168 offset0:52 offset1:56
	s_waitcnt lgkmcnt(4)
	v_mfma_f32_16x16x32_bf16 v[70:73], v[232:235], v[42:45], v[70:73]
	v_mfma_f32_16x16x32_bf16 v[74:77], v[236:239], v[42:45], v[74:77]
	v_mfma_f32_16x16x32_bf16 v[78:81], v[240:243], v[42:45], v[78:81]
	v_mfma_f32_16x16x32_bf16 v[82:85], v[244:247], v[42:45], v[82:85]
	ds_read2_b64 v[232:235], v165 offset0:60 offset1:64
	ds_read2_b64 v[236:239], v166 offset0:60 offset1:64
	ds_read2_b64 v[240:243], v167 offset0:60 offset1:64
	ds_read2_b64 v[244:247], v168 offset0:60 offset1:64
	s_waitcnt lgkmcnt(4)
	v_mfma_f32_16x16x32_bf16 v[70:73], v[216:219], v[50:53], v[70:73]
	v_mfma_f32_16x16x32_bf16 v[74:77], v[220:223], v[50:53], v[74:77]
	v_mfma_f32_16x16x32_bf16 v[78:81], v[224:227], v[50:53], v[78:81]
	v_mfma_f32_16x16x32_bf16 v[82:85], v[228:231], v[50:53], v[82:85]
	ds_read2_b64 v[216:219], v165 offset0:68 offset1:68
	ds_read2_b64 v[220:223], v166 offset0:68 offset1:68
	ds_read2_b64 v[224:227], v167 offset0:68 offset1:68
	ds_read2_b64 v[228:231], v168 offset0:68 offset1:68
	s_waitcnt lgkmcnt(4)
	v_mfma_f32_16x16x32_bf16 v[70:73], v[232:235], v[58:61], v[70:73]
	v_mfma_f32_16x16x32_bf16 v[74:77], v[236:239], v[58:61], v[74:77]
	v_mfma_f32_16x16x32_bf16 v[78:81], v[240:243], v[58:61], v[78:81]
	v_mfma_f32_16x16x32_bf16 v[82:85], v[244:247], v[58:61], v[82:85]
	s_waitcnt lgkmcnt(0)
	v_mfma_f32_16x16x32_bf16 v[70:73], v[216:219], v[66:69], v[70:73]
	v_mfma_f32_16x16x32_bf16 v[74:77], v[220:223], v[66:69], v[74:77]
	v_mfma_f32_16x16x32_bf16 v[78:81], v[224:227], v[66:69], v[78:81]
	v_mfma_f32_16x16x32_bf16 v[82:85], v[228:231], v[66:69], v[82:85]
	s_nop 7
	s_nop 1
	v_mul_f32_e32 v70, v70, v147
	v_mul_f32_e32 v71, v71, v147
	v_mul_f32_e32 v72, v72, v147
	v_mul_f32_e32 v73, v73, v147
	v_mul_f32_e32 v74, v74, v147
	v_mul_f32_e32 v75, v75, v147
	v_mul_f32_e32 v76, v76, v147
	v_mul_f32_e32 v77, v77, v147
	v_mul_f32_e32 v78, v78, v147
	v_mul_f32_e32 v79, v79, v147
	v_mul_f32_e32 v80, v80, v147
	v_mul_f32_e32 v81, v81, v147
	v_mul_f32_e32 v82, v82, v147
	v_mul_f32_e32 v83, v83, v147
	v_mul_f32_e32 v84, v84, v147
	v_mul_f32_e32 v85, v85, v147
	v_cvt_pk_bf16_f32 v70, v70, v71
	v_cvt_pk_bf16_f32 v71, v72, v73
	v_cvt_pk_bf16_f32 v74, v74, v75
	v_cvt_pk_bf16_f32 v75, v76, v77
	v_cvt_pk_bf16_f32 v78, v78, v79
	v_cvt_pk_bf16_f32 v79, v80, v81
	v_cvt_pk_bf16_f32 v82, v82, v83
	v_cvt_pk_bf16_f32 v83, v84, v85
	global_store_dwordx2 v[248:249], v[70:71], off offset:-64
	global_store_dwordx2 v[248:249], v[74:75], off offset:-32
	global_store_dwordx2 v[248:249], v[78:79], off
	global_store_dwordx2 v[248:249], v[82:83], off offset:32
	v_lshl_add_u64 v[248:249], v[248:249], 0, s[48:49]
	v_sub_f32_e32 v86, v94, v176
	v_sub_f32_e32 v87, v95, v176
	v_sub_f32_e32 v88, v96, v176
	v_sub_f32_e32 v89, v97, v176
	v_cmp_ge_i32_e32 vcc, 0, v108
	s_nop 1
	v_cndmask_b32_e32 v212, v252, v86, vcc
	v_cmp_ge_i32_e32 vcc, 0, v110
	s_nop 1
	v_cndmask_b32_e32 v213, v252, v87, vcc
	v_cmp_ge_i32_e32 vcc, 0, v111
	s_nop 1
	v_cndmask_b32_e32 v214, v252, v88, vcc
	v_cmp_ge_i32_e32 vcc, 0, v177
	s_nop 1
	v_cndmask_b32_e32 v215, v252, v89, vcc
	ds_read_b128 v[148:151], v164 offset:4608
	ds_read_b128 v[152:155], v164 offset:4672
	ds_read_b128 v[156:159], v164 offset:6912
	ds_read_b128 v[160:163], v164 offset:6976
	v_add_f32_e32 v90, v86, v174
	v_add_f32_e32 v91, v87, v174
	v_add_f32_e32 v92, v88, v174
	v_add_f32_e32 v93, v89, v174
	s_waitcnt lgkmcnt(2)
	v_mfma_f32_16x16x32_bf16 v[2:5], v[148:151], v[196:199], v[212:215]
	v_mfma_f32_16x16x32_bf16 v[2:5], v[152:155], v[200:203], v[2:5]
	ds_read_b128 v[148:151], v164 offset:9216
	ds_read_b128 v[152:155], v164 offset:9280
	v_add_f32_e32 v86, v90, v174
	v_add_f32_e32 v87, v91, v174
	v_add_f32_e32 v88, v92, v174
	v_add_f32_e32 v89, v93, v174
	s_waitcnt lgkmcnt(2)
	v_mfma_f32_16x16x32_bf16 v[6:9], v[156:159], v[196:199], v[90:93]
	v_mfma_f32_16x16x32_bf16 v[6:9], v[160:163], v[200:203], v[6:9]
	ds_read_b128 v[156:159], v164 offset:11520
	ds_read_b128 v[160:163], v164 offset:11584
	v_add_f32_e32 v90, v86, v174
	v_add_f32_e32 v91, v87, v174
	v_add_f32_e32 v92, v88, v174
	v_add_f32_e32 v93, v89, v174
	s_waitcnt lgkmcnt(2)
	v_mfma_f32_16x16x32_bf16 v[10:13], v[148:151], v[196:199], v[86:89]
	v_mfma_f32_16x16x32_bf16 v[10:13], v[152:155], v[200:203], v[10:13]
	ds_read_b128 v[148:151], v164 offset:13824
	ds_read_b128 v[152:155], v164 offset:13888
	v_add_f32_e32 v86, v90, v174
	v_add_f32_e32 v87, v91, v174
	v_add_f32_e32 v88, v92, v174
	v_add_f32_e32 v89, v93, v174
	s_waitcnt lgkmcnt(2)
	v_mfma_f32_16x16x32_bf16 v[14:17], v[156:159], v[196:199], v[90:93]
	v_mfma_f32_16x16x32_bf16 v[14:17], v[160:163], v[200:203], v[14:17]
	ds_read_b128 v[156:159], v164 offset:16128
	ds_read_b128 v[160:163], v164 offset:16192
	v_add_f32_e32 v90, v86, v174
	v_add_f32_e32 v91, v87, v174
	v_add_f32_e32 v92, v88, v174
	v_add_f32_e32 v93, v89, v174
	s_waitcnt lgkmcnt(2)
; __device__ __forceinline__ f32x4 mfma16(bf16x8 a, bf16x8 b, f32x4 c) { return __builtin_amdgcn_mfma_f32_16x16x32_bf16(a, b, c, 0, 0, 0); }
; __device__ void att_phase(int wv, const Params& p, unsigned char* lds) {
;     ...
;             f32x4 sc[24];
; #pragma unroll
;             for (int cb = 0; cb < 24; ++cb) { f32x4 a = {0, 0, 0, 0};
; #pragma unroll
;                 for (int kk = 0; kk < 2; ++kk) { const bf16x8 kf = *(const bf16x8*)(KL + (16 * cb + lr) * KP + 32 * kk + 8 * lq); a = mfma16(kf, qf[kk], a); }
;                 sc[cb] = a; }
;             float mx = sink;
; #pragma unroll
;             for (int cb = 0; cb < 24; ++cb) { const int kb = B - 1 + (cb >> 3); const bool bval = (kb >= sb && kb < se);
; #pragma unroll
;                 for (int j = 0; j < 4; ++j) { const int krel = 16 * cb + 4 * lq + j - 128;
;                     int dist = qrow - krel; dist = dist < 0 ? -dist : dist;
;                     const float v = (bval && dist <= 128) ? sc[cb][j] * 0.125f - slope * (float)dist : -1e30f;
;                     sc[cb][j] = v; mx = fmaxf(mx, v); } }
;             mx = fmaxf(mx, __shfl_xor(mx, 16)); mx = fmaxf(mx, __shfl_xor(mx, 32));
;             float sum = 0.f;
; #pragma unroll
;             for (int cb = 0; cb < 24; ++cb)
; #pragma unroll
;                 for (int j = 0; j < 4; ++j) { const float e = __expf(sc[cb][j] - mx); sc[cb][j] = e; sum += e; }
	v_mfma_f32_16x16x32_bf16 v[18:21], v[148:151], v[196:199], v[86:89]
	v_mfma_f32_16x16x32_bf16 v[18:21], v[152:155], v[200:203], v[18:21]
	ds_read_b128 v[148:151], v164 offset:18432
	ds_read_b128 v[152:155], v164 offset:18496
	v_add_f32_e32 v86, v90, v174
	v_add_f32_e32 v87, v91, v174
	v_add_f32_e32 v88, v92, v174
	v_add_f32_e32 v89, v93, v174
	s_waitcnt lgkmcnt(2)
	v_mfma_f32_16x16x32_bf16 v[22:25], v[156:159], v[196:199], v[90:93]
	v_mfma_f32_16x16x32_bf16 v[22:25], v[160:163], v[200:203], v[22:25]
	ds_read_b128 v[156:159], v164 offset:20736
	ds_read_b128 v[160:163], v164 offset:20800
	v_add_f32_e32 v90, v86, v174
	v_add_f32_e32 v91, v87, v174
	v_add_f32_e32 v92, v88, v174
	v_add_f32_e32 v93, v89, v174
	s_waitcnt lgkmcnt(2)
	v_mfma_f32_16x16x32_bf16 v[26:29], v[148:151], v[196:199], v[86:89]
	v_mfma_f32_16x16x32_bf16 v[26:29], v[152:155], v[200:203], v[26:29]
	ds_read_b128 v[148:151], v164 offset:23040
	ds_read_b128 v[152:155], v164 offset:23104
	s_waitcnt lgkmcnt(2)
	v_mfma_f32_16x16x32_bf16 v[30:33], v[156:159], v[196:199], v[90:93]
	v_mfma_f32_16x16x32_bf16 v[30:33], v[160:163], v[200:203], v[30:33]
	ds_read_b128 v[156:159], v164 offset:25344
	ds_read_b128 v[160:163], v164 offset:25408
	v_sub_f32_e64 v86, -v94, v174
	v_sub_f32_e64 v87, -v95, v174
	v_sub_f32_e64 v88, -v96, v174
	v_sub_f32_e64 v89, -v97, v174
	s_waitcnt lgkmcnt(2)
	v_mfma_f32_16x16x32_bf16 v[34:37], v[148:151], v[196:199], v[98:101]
	v_mfma_f32_16x16x32_bf16 v[34:37], v[152:155], v[200:203], v[34:37]
	ds_read_b128 v[148:151], v164 offset:27648
	ds_read_b128 v[152:155], v164 offset:27712
	v_sub_f32_e32 v90, v86, v174
	v_sub_f32_e32 v91, v87, v174
	v_sub_f32_e32 v92, v88, v174
	v_sub_f32_e32 v93, v89, v174
	s_waitcnt lgkmcnt(2)
	v_mfma_f32_16x16x32_bf16 v[38:41], v[156:159], v[196:199], v[86:89]
	v_mfma_f32_16x16x32_bf16 v[38:41], v[160:163], v[200:203], v[38:41]
	ds_read_b128 v[156:159], v164 offset:29952
	ds_read_b128 v[160:163], v164 offset:30016
	v_sub_f32_e32 v86, v90, v174
	v_sub_f32_e32 v87, v91, v174
	v_sub_f32_e32 v88, v92, v174
	v_sub_f32_e32 v89, v93, v174
	s_waitcnt lgkmcnt(2)
	v_mfma_f32_16x16x32_bf16 v[42:45], v[148:151], v[196:199], v[90:93]
	v_mfma_f32_16x16x32_bf16 v[42:45], v[152:155], v[200:203], v[42:45]
	ds_read_b128 v[148:151], v164 offset:32256
	ds_read_b128 v[152:155], v164 offset:32320
	v_sub_f32_e32 v90, v86, v174
	v_sub_f32_e32 v91, v87, v174
	v_sub_f32_e32 v92, v88, v174
	v_sub_f32_e32 v93, v89, v174
	s_waitcnt lgkmcnt(2)
	v_mfma_f32_16x16x32_bf16 v[46:49], v[156:159], v[196:199], v[86:89]
	v_mfma_f32_16x16x32_bf16 v[46:49], v[160:163], v[200:203], v[46:49]
	ds_read_b128 v[156:159], v164 offset:34560
	ds_read_b128 v[160:163], v164 offset:34624
	v_sub_f32_e32 v86, v90, v174
	v_sub_f32_e32 v87, v91, v174
	v_sub_f32_e32 v88, v92, v174
	v_sub_f32_e32 v89, v93, v174
	s_waitcnt lgkmcnt(2)
	v_mfma_f32_16x16x32_bf16 v[50:53], v[148:151], v[196:199], v[90:93]
	v_mfma_f32_16x16x32_bf16 v[50:53], v[152:155], v[200:203], v[50:53]
	ds_read_b128 v[148:151], v164 offset:36864
	ds_read_b128 v[152:155], v164 offset:36928
	v_sub_f32_e32 v90, v86, v174
	v_sub_f32_e32 v91, v87, v174
	v_sub_f32_e32 v92, v88, v174
	v_sub_f32_e32 v93, v89, v174
	s_waitcnt lgkmcnt(2)
	v_mfma_f32_16x16x32_bf16 v[54:57], v[156:159], v[196:199], v[86:89]
	v_mfma_f32_16x16x32_bf16 v[54:57], v[160:163], v[200:203], v[54:57]
	ds_read_b128 v[156:159], v164 offset:39168
	ds_read_b128 v[160:163], v164 offset:39232
	v_sub_f32_e32 v86, v90, v174
	v_sub_f32_e32 v87, v91, v174
	v_sub_f32_e32 v88, v92, v174
	v_sub_f32_e32 v89, v93, v174
	s_waitcnt lgkmcnt(2)
	v_mfma_f32_16x16x32_bf16 v[58:61], v[148:151], v[196:199], v[90:93]
	v_mfma_f32_16x16x32_bf16 v[58:61], v[152:155], v[200:203], v[58:61]
	ds_read_b128 v[148:151], v164 offset:41472
	ds_read_b128 v[152:155], v164 offset:41536
	v_sub_f32_e32 v90, v86, v174
	v_sub_f32_e32 v91, v87, v174
	v_sub_f32_e32 v92, v88, v174
	v_sub_f32_e32 v93, v89, v174
	v_cmp_le_i32_e32 vcc, 0, v108
	s_nop 1
	v_cndmask_b32_e32 v212, v252, v90, vcc
	v_cmp_le_i32_e32 vcc, 0, v110
	s_nop 1
	v_cndmask_b32_e32 v213, v252, v91, vcc
	v_cmp_le_i32_e32 vcc, 0, v111
	s_nop 1
	v_cndmask_b32_e32 v214, v252, v92, vcc
	v_cmp_le_i32_e32 vcc, 0, v177
	s_nop 1
	v_cndmask_b32_e32 v215, v252, v93, vcc
	s_waitcnt lgkmcnt(2)
	v_mfma_f32_16x16x32_bf16 v[62:65], v[156:159], v[196:199], v[86:89]
	v_mfma_f32_16x16x32_bf16 v[62:65], v[160:163], v[200:203], v[62:65]
	s_waitcnt lgkmcnt(0)
	v_mfma_f32_16x16x32_bf16 v[66:69], v[148:151], v[196:199], v[212:215]
	v_mfma_f32_16x16x32_bf16 v[66:69], v[152:155], v[200:203], v[66:69]
	ds_read2_b64 v[216:219], v165 offset0:8 offset1:12
	ds_read2_b64 v[220:223], v166 offset0:8 offset1:12
	ds_read2_b64 v[224:227], v167 offset0:8 offset1:12
	ds_read2_b64 v[228:231], v168 offset0:8 offset1:12
	v_max3_f32 v169, v2, v3, v4
	v_max3_f32 v172, v5, v6, v7
	v_max3_f32 v169, v8, v9, v169
	v_max3_f32 v172, v10, v11, v172
	v_max3_f32 v169, v12, v13, v169
	v_max3_f32 v172, v14, v15, v172
	v_max3_f32 v169, v16, v17, v169
	v_max3_f32 v172, v18, v19, v172
	v_max3_f32 v169, v20, v21, v169
	v_max3_f32 v172, v22, v23, v172
	v_max3_f32 v169, v24, v25, v169
	v_max3_f32 v172, v26, v27, v172
	v_max3_f32 v169, v28, v29, v169
	v_max3_f32 v172, v30, v31, v172
	v_max3_f32 v169, v32, v33, v169
	v_max3_f32 v172, v34, v35, v172
	v_max3_f32 v169, v36, v37, v169
	v_max3_f32 v172, v38, v39, v172
	v_max3_f32 v169, v40, v41, v169
	v_max3_f32 v172, v42, v43, v172
	v_max3_f32 v169, v44, v45, v169
	v_max3_f32 v172, v46, v47, v172
	v_max3_f32 v169, v48, v49, v169
	v_max3_f32 v172, v50, v51, v172
	v_max3_f32 v169, v52, v53, v169
	v_max3_f32 v172, v54, v55, v172
	v_max3_f32 v169, v56, v57, v169
	v_max3_f32 v172, v58, v59, v172
	v_max3_f32 v169, v60, v61, v169
	v_max3_f32 v172, v62, v63, v172
	v_max3_f32 v169, v64, v65, v169
	v_max3_f32 v172, v66, v67, v172
	v_max3_f32 v169, v68, v69, v169
	v_max_f32_e32 v169, v169, v172
	v_mul_f32_e32 v169, 0x3e000000, v169
	v_max_f32_e32 v169, v169, v146
	ds_bpermute_b32 v172, v1, v169
	s_waitcnt lgkmcnt(0)
; __device__ void att_phase(int wv, const Params& p, unsigned char* lds) {
;     ...
;             float sum = 0.f;
; #pragma unroll
;             for (int cb = 0; cb < 24; ++cb)
; #pragma unroll
;                 for (int j = 0; j < 4; ++j) { const float e = __expf(sc[cb][j] - mx); sc[cb][j] = e; sum += e; }
	v_max_f32_e32 v169, v169, v172
	ds_bpermute_b32 v172, v114, v169
	s_waitcnt lgkmcnt(0)
	v_max_f32_e32 v169, v169, v172
	v_mul_f32_e32 v175, 0xbfb8aa3b, v169
	v_mov_b32_e32 v170, 0
	v_mov_b32_e32 v171, 0
	v_fma_f32 v2, v2, s46, v175
	v_fma_f32 v3, v3, s46, v175
	v_fma_f32 v4, v4, s46, v175
	v_fma_f32 v5, v5, s46, v175
	v_exp_f32_e32 v2, v2
	v_exp_f32_e32 v3, v3
	v_exp_f32_e32 v4, v4
	v_exp_f32_e32 v5, v5
	v_fma_f32 v6, v6, s46, v175
	v_fma_f32 v7, v7, s46, v175
	v_fma_f32 v8, v8, s46, v175
	v_fma_f32 v9, v9, s46, v175
	v_exp_f32_e32 v6, v6
	v_exp_f32_e32 v7, v7
	v_exp_f32_e32 v8, v8
	v_exp_f32_e32 v9, v9
	v_add_f32_e32 v171, v171, v2
	v_add_f32_e32 v170, v170, v3
	v_add_f32_e32 v171, v171, v4
	v_add_f32_e32 v170, v170, v5
	v_fma_f32 v10, v10, s46, v175
	v_fma_f32 v11, v11, s46, v175
	v_fma_f32 v12, v12, s46, v175
	v_fma_f32 v13, v13, s46, v175
	v_exp_f32_e32 v10, v10
	v_exp_f32_e32 v11, v11
	v_exp_f32_e32 v12, v12
	v_exp_f32_e32 v13, v13
	v_add_f32_e32 v171, v171, v6
	v_add_f32_e32 v170, v170, v7
	v_add_f32_e32 v171, v171, v8
	v_add_f32_e32 v170, v170, v9
	v_fma_f32 v14, v14, s46, v175
	v_fma_f32 v15, v15, s46, v175
	v_fma_f32 v16, v16, s46, v175
	v_fma_f32 v17, v17, s46, v175
	v_exp_f32_e32 v14, v14
	v_exp_f32_e32 v15, v15
	v_exp_f32_e32 v16, v16
	v_exp_f32_e32 v17, v17
	v_add_f32_e32 v171, v171, v10
	v_add_f32_e32 v170, v170, v11
	v_add_f32_e32 v171, v171, v12
	v_add_f32_e32 v170, v170, v13
	v_fma_f32 v18, v18, s46, v175
	v_fma_f32 v19, v19, s46, v175
	v_fma_f32 v20, v20, s46, v175
	v_fma_f32 v21, v21, s46, v175
	v_exp_f32_e32 v18, v18
	v_exp_f32_e32 v19, v19
	v_exp_f32_e32 v20, v20
	v_exp_f32_e32 v21, v21
	v_add_f32_e32 v171, v171, v14
	v_add_f32_e32 v170, v170, v15
	v_add_f32_e32 v171, v171, v16
	v_add_f32_e32 v170, v170, v17
	v_fma_f32 v22, v22, s46, v175
	v_fma_f32 v23, v23, s46, v175
	v_fma_f32 v24, v24, s46, v175
	v_fma_f32 v25, v25, s46, v175
	v_exp_f32_e32 v22, v22
	v_exp_f32_e32 v23, v23
	v_exp_f32_e32 v24, v24
	v_exp_f32_e32 v25, v25
	v_add_f32_e32 v171, v171, v18
	v_add_f32_e32 v170, v170, v19
	v_add_f32_e32 v171, v171, v20
	v_add_f32_e32 v170, v170, v21
	v_fma_f32 v26, v26, s46, v175
	v_fma_f32 v27, v27, s46, v175
	v_fma_f32 v28, v28, s46, v175
	v_fma_f32 v29, v29, s46, v175
	v_exp_f32_e32 v26, v26
	v_exp_f32_e32 v27, v27
	v_exp_f32_e32 v28, v28
	v_exp_f32_e32 v29, v29
	v_add_f32_e32 v171, v171, v22
	v_add_f32_e32 v170, v170, v23
	v_add_f32_e32 v171, v171, v24
	v_add_f32_e32 v170, v170, v25
	v_fma_f32 v30, v30, s46, v175
	v_fma_f32 v31, v31, s46, v175
	v_fma_f32 v32, v32, s46, v175
	v_fma_f32 v33, v33, s46, v175
	v_exp_f32_e32 v30, v30
	v_exp_f32_e32 v31, v31
	v_exp_f32_e32 v32, v32
	v_exp_f32_e32 v33, v33
	v_add_f32_e32 v171, v171, v26
	v_add_f32_e32 v170, v170, v27
	v_add_f32_e32 v171, v171, v28
	v_add_f32_e32 v170, v170, v29
	v_fma_f32 v34, v34, s46, v175
	v_fma_f32 v35, v35, s46, v175
	v_fma_f32 v36, v36, s46, v175
	v_fma_f32 v37, v37, s46, v175
	v_exp_f32_e32 v34, v34
	v_exp_f32_e32 v35, v35
	v_exp_f32_e32 v36, v36
	v_exp_f32_e32 v37, v37
	v_add_f32_e32 v171, v171, v30
	v_add_f32_e32 v170, v170, v31
	v_add_f32_e32 v171, v171, v32
	v_add_f32_e32 v170, v170, v33
	v_fma_f32 v38, v38, s46, v175
	v_fma_f32 v39, v39, s46, v175
	v_fma_f32 v40, v40, s46, v175
	v_fma_f32 v41, v41, s46, v175
	v_exp_f32_e32 v38, v38
	v_exp_f32_e32 v39, v39
	v_exp_f32_e32 v40, v40
	v_exp_f32_e32 v41, v41
	v_add_f32_e32 v171, v171, v34
	v_add_f32_e32 v170, v170, v35
	v_add_f32_e32 v171, v171, v36
	v_add_f32_e32 v170, v170, v37
	v_fma_f32 v42, v42, s46, v175
	v_fma_f32 v43, v43, s46, v175
	v_fma_f32 v44, v44, s46, v175
	v_fma_f32 v45, v45, s46, v175
	v_exp_f32_e32 v42, v42
	v_exp_f32_e32 v43, v43
	v_exp_f32_e32 v44, v44
	v_exp_f32_e32 v45, v45
	v_add_f32_e32 v171, v171, v38
	v_add_f32_e32 v170, v170, v39
	v_add_f32_e32 v171, v171, v40
	v_add_f32_e32 v170, v170, v41
	v_fma_f32 v46, v46, s46, v175
	v_fma_f32 v47, v47, s46, v175
	v_fma_f32 v48, v48, s46, v175
	v_fma_f32 v49, v49, s46, v175
	v_exp_f32_e32 v46, v46
	v_exp_f32_e32 v47, v47
	v_exp_f32_e32 v48, v48
	v_exp_f32_e32 v49, v49
	v_add_f32_e32 v171, v171, v42
	v_add_f32_e32 v170, v170, v43
	v_add_f32_e32 v171, v171, v44
	v_add_f32_e32 v170, v170, v45
	v_fma_f32 v50, v50, s46, v175
	v_fma_f32 v51, v51, s46, v175
	v_fma_f32 v52, v52, s46, v175
	v_fma_f32 v53, v53, s46, v175
	v_exp_f32_e32 v50, v50
	v_exp_f32_e32 v51, v51
	v_exp_f32_e32 v52, v52
	v_exp_f32_e32 v53, v53
	v_add_f32_e32 v171, v171, v46
	v_add_f32_e32 v170, v170, v47
	v_add_f32_e32 v171, v171, v48
	v_add_f32_e32 v170, v170, v49
	v_fma_f32 v54, v54, s46, v175
	v_fma_f32 v55, v55, s46, v175
	v_fma_f32 v56, v56, s46, v175
	v_fma_f32 v57, v57, s46, v175
	v_exp_f32_e32 v54, v54
	v_exp_f32_e32 v55, v55
	v_exp_f32_e32 v56, v56
	v_exp_f32_e32 v57, v57
	v_add_f32_e32 v171, v171, v50
	v_add_f32_e32 v170, v170, v51
	v_add_f32_e32 v171, v171, v52
	v_add_f32_e32 v170, v170, v53
	v_fma_f32 v58, v58, s46, v175
	v_fma_f32 v59, v59, s46, v175
	v_fma_f32 v60, v60, s46, v175
	v_fma_f32 v61, v61, s46, v175
	v_exp_f32_e32 v58, v58
	v_exp_f32_e32 v59, v59
	v_exp_f32_e32 v60, v60
	v_exp_f32_e32 v61, v61
	v_add_f32_e32 v171, v171, v54
	v_add_f32_e32 v170, v170, v55
	v_add_f32_e32 v171, v171, v56
	v_add_f32_e32 v170, v170, v57
	v_fma_f32 v62, v62, s46, v175
	v_fma_f32 v63, v63, s46, v175
	v_fma_f32 v64, v64, s46, v175
	v_fma_f32 v65, v65, s46, v175
	v_exp_f32_e32 v62, v62
	v_exp_f32_e32 v63, v63
	v_exp_f32_e32 v64, v64
	v_exp_f32_e32 v65, v65
	v_add_f32_e32 v171, v171, v58
	v_add_f32_e32 v170, v170, v59
	v_add_f32_e32 v171, v171, v60
	v_add_f32_e32 v170, v170, v61
	v_fma_f32 v66, v66, s46, v175
	v_fma_f32 v67, v67, s46, v175
	v_fma_f32 v68, v68, s46, v175
; __device__ __forceinline__ unsigned cvt_pk_bf16_asm(float lo, float hi) { unsigned r; asm volatile("v_cvt_pk_bf16_f32 %0, %1, %2" : "=v"(r) : "v"(lo), "v"(hi)); return r; }
; __device__ __forceinline__ f32x4 mfma16(bf16x8 a, bf16x8 b, f32x4 c) { return __builtin_amdgcn_mfma_f32_16x16x32_bf16(a, b, c, 0, 0, 0); }
; __device__ void att_phase(int wv, const Params& p, unsigned char* lds) {
;     ...
;             for (int cb = 0; cb < 24; ++cb)
; #pragma unroll
;                 for (int j = 0; j < 4; ++j) { const float e = __expf(sc[cb][j] - mx); sc[cb][j] = e; sum += e; }
;             sum += __shfl_xor(sum, 16); sum += __shfl_xor(sum, 32);
;             sum += __expf(sink - mx);
;             const float inv = 1.0f / sum;
;             f32x4 oa[4];
; #pragma unroll
;             for (int db = 0; db < 4; ++db) oa[db] = (f32x4){0, 0, 0, 0};
; #pragma unroll
;             for (int ks = 0; ks < 12; ++ks) {
;                 union { bf16x8 v; unsigned u[4]; } pf;
;                 pf.u[0] = cvt_pk_bf16_asm(sc[2 * ks][0], sc[2 * ks][1]); pf.u[1] = cvt_pk_bf16_asm(sc[2 * ks][2], sc[2 * ks][3]);
;                 pf.u[2] = cvt_pk_bf16_asm(sc[2 * ks + 1][0], sc[2 * ks + 1][1]); pf.u[3] = cvt_pk_bf16_asm(sc[2 * ks + 1][2], sc[2 * ks + 1][3]);
; #pragma unroll
;                 for (int db = 0; db < 4; ++db) {
;                     union { bf16x8 v; u32x2 h2[2]; } vf;
;                     const bf16_t* vp = VTL + (16 * db + lr) * VP + 32 * ks + 4 * lq;
;                     vf.h2[0] = *(const u32x2*)vp; vf.h2[1] = *(const u32x2*)(vp + 16);
;                     oa[db] = mfma16(vf.v, pf.v, oa[db]); } }
	v_fma_f32 v69, v69, s46, v175
	v_exp_f32_e32 v66, v66
	v_exp_f32_e32 v67, v67
	v_exp_f32_e32 v68, v68
	v_exp_f32_e32 v69, v69
	v_add_f32_e32 v171, v171, v62
	v_add_f32_e32 v170, v170, v63
	v_add_f32_e32 v171, v171, v64
	v_add_f32_e32 v170, v170, v65
	v_add_f32_e32 v171, v171, v66
	v_add_f32_e32 v170, v170, v67
	v_add_f32_e32 v171, v171, v68
	v_add_f32_e32 v170, v170, v69
	v_add_f32_e32 v170, v170, v171
	v_cvt_pk_bf16_f32 v2, v2, v3
	v_cvt_pk_bf16_f32 v3, v4, v5
	v_cvt_pk_bf16_f32 v4, v6, v7
	v_cvt_pk_bf16_f32 v5, v8, v9
	v_cvt_pk_bf16_f32 v10, v10, v11
	v_cvt_pk_bf16_f32 v11, v12, v13
	v_cvt_pk_bf16_f32 v12, v14, v15
	v_cvt_pk_bf16_f32 v13, v16, v17
	v_cvt_pk_bf16_f32 v18, v18, v19
	v_cvt_pk_bf16_f32 v19, v20, v21
	v_cvt_pk_bf16_f32 v20, v22, v23
	v_cvt_pk_bf16_f32 v21, v24, v25
	v_cvt_pk_bf16_f32 v26, v26, v27
	v_cvt_pk_bf16_f32 v27, v28, v29
	v_cvt_pk_bf16_f32 v28, v30, v31
	v_cvt_pk_bf16_f32 v29, v32, v33
	v_cvt_pk_bf16_f32 v34, v34, v35
	v_cvt_pk_bf16_f32 v35, v36, v37
	v_cvt_pk_bf16_f32 v36, v38, v39
	v_cvt_pk_bf16_f32 v37, v40, v41
	v_cvt_pk_bf16_f32 v42, v42, v43
	v_cvt_pk_bf16_f32 v43, v44, v45
	v_cvt_pk_bf16_f32 v44, v46, v47
	v_cvt_pk_bf16_f32 v45, v48, v49
	v_cvt_pk_bf16_f32 v50, v50, v51
	v_cvt_pk_bf16_f32 v51, v52, v53
	v_cvt_pk_bf16_f32 v52, v54, v55
	v_cvt_pk_bf16_f32 v53, v56, v57
	v_cvt_pk_bf16_f32 v58, v58, v59
	v_cvt_pk_bf16_f32 v59, v60, v61
	v_cvt_pk_bf16_f32 v60, v62, v63
	v_cvt_pk_bf16_f32 v61, v64, v65
	v_cvt_pk_bf16_f32 v66, v66, v67
	v_cvt_pk_bf16_f32 v67, v68, v69
	v_mov_b32_e32 v68, 0
	v_mov_b32_e32 v69, 0
	ds_bpermute_b32 v172, v1, v170
	v_sub_f32_e32 v173, v146, v169
	v_mul_f32_e32 v173, 0x3fb8aa3b, v173
	v_exp_f32_e32 v173, v173
	s_waitcnt lgkmcnt(0)
	v_add_f32_e32 v170, v170, v172
	ds_bpermute_b32 v172, v114, v170
	ds_read2_b64 v[232:235], v165 offset0:16 offset1:20
	ds_read2_b64 v[236:239], v166 offset0:16 offset1:20
	ds_read2_b64 v[240:243], v167 offset0:16 offset1:20
	ds_read2_b64 v[244:247], v168 offset0:16 offset1:20
	s_waitcnt lgkmcnt(4)
	v_mfma_f32_16x16x32_bf16 v[70:73], v[216:219], v[2:5], 0
	v_mfma_f32_16x16x32_bf16 v[74:77], v[220:223], v[2:5], 0
	v_mfma_f32_16x16x32_bf16 v[78:81], v[224:227], v[2:5], 0
	v_mfma_f32_16x16x32_bf16 v[82:85], v[228:231], v[2:5], 0
	v_add_f32_e32 v170, v170, v172
	v_add_f32_e32 v170, v170, v173
	v_rcp_f32_e32 v147, v170
	s_nop 0
	v_fma_f32 v179, -v170, v147, 1.0
	v_fmac_f32_e32 v147, v179, v147
	ds_read2_b64 v[216:219], v165 offset0:24 offset1:28
	ds_read2_b64 v[220:223], v166 offset0:24 offset1:28
	ds_read2_b64 v[224:227], v167 offset0:24 offset1:28
	ds_read2_b64 v[228:231], v168 offset0:24 offset1:28
	s_waitcnt lgkmcnt(4)
	v_mfma_f32_16x16x32_bf16 v[70:73], v[232:235], v[10:13], v[70:73]
	v_mfma_f32_16x16x32_bf16 v[74:77], v[236:239], v[10:13], v[74:77]
	v_mfma_f32_16x16x32_bf16 v[78:81], v[240:243], v[10:13], v[78:81]
	v_mfma_f32_16x16x32_bf16 v[82:85], v[244:247], v[10:13], v[82:85]
	ds_read2_b64 v[232:235], v165 offset0:32 offset1:36
	ds_read2_b64 v[236:239], v166 offset0:32 offset1:36
	ds_read2_b64 v[240:243], v167 offset0:32 offset1:36
	ds_read2_b64 v[244:247], v168 offset0:32 offset1:36
	s_waitcnt lgkmcnt(4)
	v_mfma_f32_16x16x32_bf16 v[70:73], v[216:219], v[18:21], v[70:73]
	v_mfma_f32_16x16x32_bf16 v[74:77], v[220:223], v[18:21], v[74:77]
	v_mfma_f32_16x16x32_bf16 v[78:81], v[224:227], v[18:21], v[78:81]
	v_mfma_f32_16x16x32_bf16 v[82:85], v[228:231], v[18:21], v[82:85]
	ds_read2_b64 v[216:219], v165 offset0:40 offset1:44
	ds_read2_b64 v[220:223], v166 offset0:40 offset1:44
	ds_read2_b64 v[224:227], v167 offset0:40 offset1:44
	ds_read2_b64 v[228:231], v168 offset0:40 offset1:44
	s_waitcnt lgkmcnt(4)
	v_mfma_f32_16x16x32_bf16 v[70:73], v[232:235], v[26:29], v[70:73]
	v_mfma_f32_16x16x32_bf16 v[74:77], v[236:239], v[26:29], v[74:77]
	v_mfma_f32_16x16x32_bf16 v[78:81], v[240:243], v[26:29], v[78:81]
	v_mfma_f32_16x16x32_bf16 v[82:85], v[244:247], v[26:29], v[82:85]
	ds_read2_b64 v[232:235], v165 offset0:48 offset1:52
	ds_read2_b64 v[236:239], v166 offset0:48 offset1:52
	ds_read2_b64 v[240:243], v167 offset0:48 offset1:52
	ds_read2_b64 v[244:247], v168 offset0:48 offset1:52
	s_waitcnt lgkmcnt(4)
	v_mfma_f32_16x16x32_bf16 v[70:73], v[216:219], v[34:37], v[70:73]
	v_mfma_f32_16x16x32_bf16 v[74:77], v[220:223], v[34:37], v[74:77]
	v_mfma_f32_16x16x32_bf16 v[78:81], v[224:227], v[34:37], v[78:81]
	v_mfma_f32_16x16x32_bf16 v[82:85], v[228:231], v[34:37], v[82:85]
	ds_read2_b64 v[216:219], v165 offset0:56 offset1:60
	ds_read2_b64 v[220:223], v166 offset0:56 offset1:60
	ds_read2_b64 v[224:227], v167 offset0:56 offset1:60
	ds_read2_b64 v[228:231], v168 offset0:56 offset1:60
	s_waitcnt lgkmcnt(4)
	v_mfma_f32_16x16x32_bf16 v[70:73], v[232:235], v[42:45], v[70:73]
	v_mfma_f32_16x16x32_bf16 v[74:77], v[236:239], v[42:45], v[74:77]
	v_mfma_f32_16x16x32_bf16 v[78:81], v[240:243], v[42:45], v[78:81]
	v_mfma_f32_16x16x32_bf16 v[82:85], v[244:247], v[42:45], v[82:85]
	ds_read2_b64 v[232:235], v165 offset0:64 offset1:68
	ds_read2_b64 v[236:239], v166 offset0:64 offset1:68
	ds_read2_b64 v[240:243], v167 offset0:64 offset1:68
	ds_read2_b64 v[244:247], v168 offset0:64 offset1:68
	s_waitcnt lgkmcnt(4)
	v_mfma_f32_16x16x32_bf16 v[70:73], v[216:219], v[50:53], v[70:73]
	v_mfma_f32_16x16x32_bf16 v[74:77], v[220:223], v[50:53], v[74:77]
	v_mfma_f32_16x16x32_bf16 v[78:81], v[224:227], v[50:53], v[78:81]
	v_mfma_f32_16x16x32_bf16 v[82:85], v[228:231], v[50:53], v[82:85]
	ds_read2_b64 v[216:219], v165 offset0:72 offset1:72
	ds_read2_b64 v[220:223], v166 offset0:72 offset1:72
	ds_read2_b64 v[224:227], v167 offset0:72 offset1:72
	ds_read2_b64 v[228:231], v168 offset0:72 offset1:72
	s_waitcnt lgkmcnt(4)
; __device__ __forceinline__ unsigned cvt_pk_bf16_asm(float lo, float hi) { unsigned r; asm volatile("v_cvt_pk_bf16_f32 %0, %1, %2" : "=v"(r) : "v"(lo), "v"(hi)); return r; }
; __device__ __forceinline__ f32x4 mfma16(bf16x8 a, bf16x8 b, f32x4 c) { return __builtin_amdgcn_mfma_f32_16x16x32_bf16(a, b, c, 0, 0, 0); }
; __device__ void att_phase(int wv, const Params& p, unsigned char* lds) {
;     ...
;             f32x4 sc[24];
; #pragma unroll
;             for (int cb = 0; cb < 24; ++cb) { f32x4 a = {0, 0, 0, 0};
; #pragma unroll
;                 for (int kk = 0; kk < 2; ++kk) { const bf16x8 kf = *(const bf16x8*)(KL + (16 * cb + lr) * KP + 32 * kk + 8 * lq); a = mfma16(kf, qf[kk], a); }
;                 sc[cb] = a; }
;             float mx = sink;
; #pragma unroll
;             for (int cb = 0; cb < 24; ++cb) { const int kb = B - 1 + (cb >> 3); const bool bval = (kb >= sb && kb < se);
; #pragma unroll
;                 for (int j = 0; j < 4; ++j) { const int krel = 16 * cb + 4 * lq + j - 128;
;                     int dist = qrow - krel; dist = dist < 0 ? -dist : dist;
;                     const float v = (bval && dist <= 128) ? sc[cb][j] * 0.125f - slope * (float)dist : -1e30f;
;                     sc[cb][j] = v; mx = fmaxf(mx, v); } }
;     ...
;                     oa[db] = mfma16(vf.v, pf.v, oa[db]); } }
; #pragma unroll
;             for (int db = 0; db < 4; ++db) { const f32x4 o = oa[db] * inv; u32x2 wv; wv.x = cvt_pk_bf16_asm(o[0], o[1]); wv.y = cvt_pk_bf16_asm(o[2], o[3]);
;                 *(u32x2*)(qkv + tokq * 1536 + 64 * h + 16 * db + 4 * lq) = wv; }
	v_mfma_f32_16x16x32_bf16 v[70:73], v[232:235], v[58:61], v[70:73]
	v_mfma_f32_16x16x32_bf16 v[74:77], v[236:239], v[58:61], v[74:77]
	v_mfma_f32_16x16x32_bf16 v[78:81], v[240:243], v[58:61], v[78:81]
	v_mfma_f32_16x16x32_bf16 v[82:85], v[244:247], v[58:61], v[82:85]
	s_waitcnt lgkmcnt(0)
	v_mfma_f32_16x16x32_bf16 v[70:73], v[216:219], v[66:69], v[70:73]
	v_mfma_f32_16x16x32_bf16 v[74:77], v[220:223], v[66:69], v[74:77]
	v_mfma_f32_16x16x32_bf16 v[78:81], v[224:227], v[66:69], v[78:81]
	v_mfma_f32_16x16x32_bf16 v[82:85], v[228:231], v[66:69], v[82:85]
	s_nop 7
	s_nop 1
	v_mul_f32_e32 v70, v70, v147
	v_mul_f32_e32 v71, v71, v147
	v_mul_f32_e32 v72, v72, v147
	v_mul_f32_e32 v73, v73, v147
	v_mul_f32_e32 v74, v74, v147
	v_mul_f32_e32 v75, v75, v147
	v_mul_f32_e32 v76, v76, v147
	v_mul_f32_e32 v77, v77, v147
	v_mul_f32_e32 v78, v78, v147
	v_mul_f32_e32 v79, v79, v147
	v_mul_f32_e32 v80, v80, v147
	v_mul_f32_e32 v81, v81, v147
	v_mul_f32_e32 v82, v82, v147
	v_mul_f32_e32 v83, v83, v147
	v_mul_f32_e32 v84, v84, v147
	v_mul_f32_e32 v85, v85, v147
	v_cvt_pk_bf16_f32 v70, v70, v71
	v_cvt_pk_bf16_f32 v71, v72, v73
	v_cvt_pk_bf16_f32 v74, v74, v75
	v_cvt_pk_bf16_f32 v75, v76, v77
	v_cvt_pk_bf16_f32 v78, v78, v79
	v_cvt_pk_bf16_f32 v79, v80, v81
	v_cvt_pk_bf16_f32 v82, v82, v83
	v_cvt_pk_bf16_f32 v83, v84, v85
	global_store_dwordx2 v[248:249], v[70:71], off offset:-64
	global_store_dwordx2 v[248:249], v[74:75], off offset:-32
	global_store_dwordx2 v[248:249], v[78:79], off
	global_store_dwordx2 v[248:249], v[82:83], off offset:32
	v_lshl_add_u64 v[248:249], v[248:249], 0, s[48:49]
	v_sub_f32_e32 v86, v94, v176
	v_sub_f32_e32 v87, v95, v176
	v_sub_f32_e32 v88, v96, v176
	v_sub_f32_e32 v89, v97, v176
	v_cmp_ge_i32_e32 vcc, 0, v108
	s_nop 1
	v_cndmask_b32_e32 v212, v252, v86, vcc
	v_cmp_ge_i32_e32 vcc, 0, v110
	s_nop 1
	v_cndmask_b32_e32 v213, v252, v87, vcc
	v_cmp_ge_i32_e32 vcc, 0, v111
	s_nop 1
	v_cndmask_b32_e32 v214, v252, v88, vcc
	v_cmp_ge_i32_e32 vcc, 0, v177
	s_nop 1
	v_cndmask_b32_e32 v215, v252, v89, vcc
	ds_read_b128 v[148:151], v164 offset:6912
	ds_read_b128 v[152:155], v164 offset:6976
	ds_read_b128 v[156:159], v164 offset:9216
	ds_read_b128 v[160:163], v164 offset:9280
	v_add_f32_e32 v90, v86, v174
	v_add_f32_e32 v91, v87, v174
	v_add_f32_e32 v92, v88, v174
	v_add_f32_e32 v93, v89, v174
	s_waitcnt lgkmcnt(2)
	v_mfma_f32_16x16x32_bf16 v[2:5], v[148:151], v[204:207], v[212:215]
	v_mfma_f32_16x16x32_bf16 v[2:5], v[152:155], v[208:211], v[2:5]
	ds_read_b128 v[148:151], v164 offset:11520
	ds_read_b128 v[152:155], v164 offset:11584
	v_add_f32_e32 v86, v90, v174
	v_add_f32_e32 v87, v91, v174
	v_add_f32_e32 v88, v92, v174
	v_add_f32_e32 v89, v93, v174
	s_waitcnt lgkmcnt(2)
	v_mfma_f32_16x16x32_bf16 v[6:9], v[156:159], v[204:207], v[90:93]
	v_mfma_f32_16x16x32_bf16 v[6:9], v[160:163], v[208:211], v[6:9]
	ds_read_b128 v[156:159], v164 offset:13824
	ds_read_b128 v[160:163], v164 offset:13888
	v_add_f32_e32 v90, v86, v174
	v_add_f32_e32 v91, v87, v174
	v_add_f32_e32 v92, v88, v174
	v_add_f32_e32 v93, v89, v174
	s_waitcnt lgkmcnt(2)
	v_mfma_f32_16x16x32_bf16 v[10:13], v[148:151], v[204:207], v[86:89]
	v_mfma_f32_16x16x32_bf16 v[10:13], v[152:155], v[208:211], v[10:13]
	ds_read_b128 v[148:151], v164 offset:16128
	ds_read_b128 v[152:155], v164 offset:16192
	v_add_f32_e32 v86, v90, v174
	v_add_f32_e32 v87, v91, v174
	v_add_f32_e32 v88, v92, v174
	v_add_f32_e32 v89, v93, v174
	s_waitcnt lgkmcnt(2)
	v_mfma_f32_16x16x32_bf16 v[14:17], v[156:159], v[204:207], v[90:93]
	v_mfma_f32_16x16x32_bf16 v[14:17], v[160:163], v[208:211], v[14:17]
	ds_read_b128 v[156:159], v164 offset:18432
	ds_read_b128 v[160:163], v164 offset:18496
	v_add_f32_e32 v90, v86, v174
	v_add_f32_e32 v91, v87, v174
	v_add_f32_e32 v92, v88, v174
	v_add_f32_e32 v93, v89, v174
	s_waitcnt lgkmcnt(2)
	v_mfma_f32_16x16x32_bf16 v[18:21], v[148:151], v[204:207], v[86:89]
	v_mfma_f32_16x16x32_bf16 v[18:21], v[152:155], v[208:211], v[18:21]
	ds_read_b128 v[148:151], v164 offset:20736
	ds_read_b128 v[152:155], v164 offset:20800
	v_add_f32_e32 v86, v90, v174
	v_add_f32_e32 v87, v91, v174
	v_add_f32_e32 v88, v92, v174
	v_add_f32_e32 v89, v93, v174
	s_waitcnt lgkmcnt(2)
	v_mfma_f32_16x16x32_bf16 v[22:25], v[156:159], v[204:207], v[90:93]
	v_mfma_f32_16x16x32_bf16 v[22:25], v[160:163], v[208:211], v[22:25]
	ds_read_b128 v[156:159], v164 offset:23040
	ds_read_b128 v[160:163], v164 offset:23104
	v_add_f32_e32 v90, v86, v174
	v_add_f32_e32 v91, v87, v174
	v_add_f32_e32 v92, v88, v174
	v_add_f32_e32 v93, v89, v174
	s_waitcnt lgkmcnt(2)
	v_mfma_f32_16x16x32_bf16 v[26:29], v[148:151], v[204:207], v[86:89]
	v_mfma_f32_16x16x32_bf16 v[26:29], v[152:155], v[208:211], v[26:29]
	ds_read_b128 v[148:151], v164 offset:25344
	ds_read_b128 v[152:155], v164 offset:25408
	s_waitcnt lgkmcnt(2)
	v_mfma_f32_16x16x32_bf16 v[30:33], v[156:159], v[204:207], v[90:93]
	v_mfma_f32_16x16x32_bf16 v[30:33], v[160:163], v[208:211], v[30:33]
	ds_read_b128 v[156:159], v164 offset:27648
	ds_read_b128 v[160:163], v164 offset:27712
	v_sub_f32_e64 v86, -v94, v174
	v_sub_f32_e64 v87, -v95, v174
	v_sub_f32_e64 v88, -v96, v174
	v_sub_f32_e64 v89, -v97, v174
	s_waitcnt lgkmcnt(2)
	v_mfma_f32_16x16x32_bf16 v[34:37], v[148:151], v[204:207], v[98:101]
	v_mfma_f32_16x16x32_bf16 v[34:37], v[152:155], v[208:211], v[34:37]
	ds_read_b128 v[148:151], v164 offset:29952
	ds_read_b128 v[152:155], v164 offset:30016
	v_sub_f32_e32 v90, v86, v174
	v_sub_f32_e32 v91, v87, v174
	v_sub_f32_e32 v92, v88, v174
	v_sub_f32_e32 v93, v89, v174
	s_waitcnt lgkmcnt(2)
; __device__ __forceinline__ f32x4 mfma16(bf16x8 a, bf16x8 b, f32x4 c) { return __builtin_amdgcn_mfma_f32_16x16x32_bf16(a, b, c, 0, 0, 0); }
; __device__ void att_phase(int wv, const Params& p, unsigned char* lds) {
;     ...
;             for (int cb = 0; cb < 24; ++cb) { f32x4 a = {0, 0, 0, 0};
; #pragma unroll
;                 for (int kk = 0; kk < 2; ++kk) { const bf16x8 kf = *(const bf16x8*)(KL + (16 * cb + lr) * KP + 32 * kk + 8 * lq); a = mfma16(kf, qf[kk], a); }
;                 sc[cb] = a; }
;             float mx = sink;
; #pragma unroll
;             for (int cb = 0; cb < 24; ++cb) { const int kb = B - 1 + (cb >> 3); const bool bval = (kb >= sb && kb < se);
; #pragma unroll
;                 for (int j = 0; j < 4; ++j) { const int krel = 16 * cb + 4 * lq + j - 128;
;                     int dist = qrow - krel; dist = dist < 0 ? -dist : dist;
;                     const float v = (bval && dist <= 128) ? sc[cb][j] * 0.125f - slope * (float)dist : -1e30f;
;                     sc[cb][j] = v; mx = fmaxf(mx, v); } }
;             mx = fmaxf(mx, __shfl_xor(mx, 16)); mx = fmaxf(mx, __shfl_xor(mx, 32));
;             float sum = 0.f;
; #pragma unroll
;             for (int cb = 0; cb < 24; ++cb)
; #pragma unroll
;                 for (int j = 0; j < 4; ++j) { const float e = __expf(sc[cb][j] - mx); sc[cb][j] = e; sum += e; }
	v_mfma_f32_16x16x32_bf16 v[38:41], v[156:159], v[204:207], v[86:89]
	v_mfma_f32_16x16x32_bf16 v[38:41], v[160:163], v[208:211], v[38:41]
	ds_read_b128 v[156:159], v164 offset:32256
	ds_read_b128 v[160:163], v164 offset:32320
	v_sub_f32_e32 v86, v90, v174
	v_sub_f32_e32 v87, v91, v174
	v_sub_f32_e32 v88, v92, v174
	v_sub_f32_e32 v89, v93, v174
	s_waitcnt lgkmcnt(2)
	v_mfma_f32_16x16x32_bf16 v[42:45], v[148:151], v[204:207], v[90:93]
	v_mfma_f32_16x16x32_bf16 v[42:45], v[152:155], v[208:211], v[42:45]
	ds_read_b128 v[148:151], v164 offset:34560
	ds_read_b128 v[152:155], v164 offset:34624
	v_sub_f32_e32 v90, v86, v174
	v_sub_f32_e32 v91, v87, v174
	v_sub_f32_e32 v92, v88, v174
	v_sub_f32_e32 v93, v89, v174
	s_waitcnt lgkmcnt(2)
	v_mfma_f32_16x16x32_bf16 v[46:49], v[156:159], v[204:207], v[86:89]
	v_mfma_f32_16x16x32_bf16 v[46:49], v[160:163], v[208:211], v[46:49]
	ds_read_b128 v[156:159], v164 offset:36864
	ds_read_b128 v[160:163], v164 offset:36928
	v_sub_f32_e32 v86, v90, v174
	v_sub_f32_e32 v87, v91, v174
	v_sub_f32_e32 v88, v92, v174
	v_sub_f32_e32 v89, v93, v174
	s_waitcnt lgkmcnt(2)
	v_mfma_f32_16x16x32_bf16 v[50:53], v[148:151], v[204:207], v[90:93]
	v_mfma_f32_16x16x32_bf16 v[50:53], v[152:155], v[208:211], v[50:53]
	ds_read_b128 v[148:151], v164 offset:39168
	ds_read_b128 v[152:155], v164 offset:39232
	v_sub_f32_e32 v90, v86, v174
	v_sub_f32_e32 v91, v87, v174
	v_sub_f32_e32 v92, v88, v174
	v_sub_f32_e32 v93, v89, v174
	s_waitcnt lgkmcnt(2)
	v_mfma_f32_16x16x32_bf16 v[54:57], v[156:159], v[204:207], v[86:89]
	v_mfma_f32_16x16x32_bf16 v[54:57], v[160:163], v[208:211], v[54:57]
	ds_read_b128 v[156:159], v164 offset:41472
	ds_read_b128 v[160:163], v164 offset:41536
	v_sub_f32_e32 v86, v90, v174
	v_sub_f32_e32 v87, v91, v174
	v_sub_f32_e32 v88, v92, v174
	v_sub_f32_e32 v89, v93, v174
	s_waitcnt lgkmcnt(2)
	v_mfma_f32_16x16x32_bf16 v[58:61], v[148:151], v[204:207], v[90:93]
	v_mfma_f32_16x16x32_bf16 v[58:61], v[152:155], v[208:211], v[58:61]
	ds_read_b128 v[148:151], v164 offset:43776
	ds_read_b128 v[152:155], v164 offset:43840
	v_sub_f32_e32 v90, v86, v174
	v_sub_f32_e32 v91, v87, v174
	v_sub_f32_e32 v92, v88, v174
	v_sub_f32_e32 v93, v89, v174
	v_cmp_le_i32_e32 vcc, 0, v108
	s_nop 1
	v_cndmask_b32_e32 v212, v252, v90, vcc
	v_cmp_le_i32_e32 vcc, 0, v110
	s_nop 1
	v_cndmask_b32_e32 v213, v252, v91, vcc
	v_cmp_le_i32_e32 vcc, 0, v111
	s_nop 1
	v_cndmask_b32_e32 v214, v252, v92, vcc
	v_cmp_le_i32_e32 vcc, 0, v177
	s_nop 1
	v_cndmask_b32_e32 v215, v252, v93, vcc
	s_waitcnt lgkmcnt(2)
	v_mfma_f32_16x16x32_bf16 v[62:65], v[156:159], v[204:207], v[86:89]
	v_mfma_f32_16x16x32_bf16 v[62:65], v[160:163], v[208:211], v[62:65]
	s_waitcnt lgkmcnt(0)
	v_mfma_f32_16x16x32_bf16 v[66:69], v[148:151], v[204:207], v[212:215]
	v_mfma_f32_16x16x32_bf16 v[66:69], v[152:155], v[208:211], v[66:69]
	ds_read2_b64 v[216:219], v165 offset0:12 offset1:16
	ds_read2_b64 v[220:223], v166 offset0:12 offset1:16
	ds_read2_b64 v[224:227], v167 offset0:12 offset1:16
	ds_read2_b64 v[228:231], v168 offset0:12 offset1:16
	v_max3_f32 v169, v2, v3, v4
	v_max3_f32 v172, v5, v6, v7
	v_max3_f32 v169, v8, v9, v169
	v_max3_f32 v172, v10, v11, v172
	v_max3_f32 v169, v12, v13, v169
	v_max3_f32 v172, v14, v15, v172
	v_max3_f32 v169, v16, v17, v169
	v_max3_f32 v172, v18, v19, v172
	v_max3_f32 v169, v20, v21, v169
	v_max3_f32 v172, v22, v23, v172
	v_max3_f32 v169, v24, v25, v169
	v_max3_f32 v172, v26, v27, v172
	v_max3_f32 v169, v28, v29, v169
	v_max3_f32 v172, v30, v31, v172
	v_max3_f32 v169, v32, v33, v169
	v_max3_f32 v172, v34, v35, v172
	v_max3_f32 v169, v36, v37, v169
	v_max3_f32 v172, v38, v39, v172
	v_max3_f32 v169, v40, v41, v169
	v_max3_f32 v172, v42, v43, v172
	v_max3_f32 v169, v44, v45, v169
	v_max3_f32 v172, v46, v47, v172
	v_max3_f32 v169, v48, v49, v169
	v_max3_f32 v172, v50, v51, v172
	v_max3_f32 v169, v52, v53, v169
	v_max3_f32 v172, v54, v55, v172
	v_max3_f32 v169, v56, v57, v169
	v_max3_f32 v172, v58, v59, v172
	v_max3_f32 v169, v60, v61, v169
	v_max3_f32 v172, v62, v63, v172
	v_max3_f32 v169, v64, v65, v169
	v_max3_f32 v172, v66, v67, v172
	v_max3_f32 v169, v68, v69, v169
	v_max_f32_e32 v169, v169, v172
	v_mul_f32_e32 v169, 0x3e000000, v169
	v_max_f32_e32 v169, v169, v146
	ds_bpermute_b32 v172, v1, v169
	s_waitcnt lgkmcnt(0)
	v_max_f32_e32 v169, v169, v172
	ds_bpermute_b32 v172, v114, v169
	s_waitcnt lgkmcnt(0)
; __device__ void att_phase(int wv, const Params& p, unsigned char* lds) {
;     ...
;             float sum = 0.f;
; #pragma unroll
;             for (int cb = 0; cb < 24; ++cb)
; #pragma unroll
;                 for (int j = 0; j < 4; ++j) { const float e = __expf(sc[cb][j] - mx); sc[cb][j] = e; sum += e; }
	v_max_f32_e32 v169, v169, v172
	v_mul_f32_e32 v175, 0xbfb8aa3b, v169
	v_mov_b32_e32 v170, 0
	v_mov_b32_e32 v171, 0
	v_fma_f32 v2, v2, s46, v175
	v_fma_f32 v3, v3, s46, v175
	v_fma_f32 v4, v4, s46, v175
	v_fma_f32 v5, v5, s46, v175
	v_exp_f32_e32 v2, v2
	v_exp_f32_e32 v3, v3
	v_exp_f32_e32 v4, v4
	v_exp_f32_e32 v5, v5
	v_fma_f32 v6, v6, s46, v175
	v_fma_f32 v7, v7, s46, v175
	v_fma_f32 v8, v8, s46, v175
	v_fma_f32 v9, v9, s46, v175
	v_exp_f32_e32 v6, v6
	v_exp_f32_e32 v7, v7
	v_exp_f32_e32 v8, v8
	v_exp_f32_e32 v9, v9
	v_add_f32_e32 v171, v171, v2
	v_add_f32_e32 v170, v170, v3
	v_add_f32_e32 v171, v171, v4
	v_add_f32_e32 v170, v170, v5
	v_fma_f32 v10, v10, s46, v175
	v_fma_f32 v11, v11, s46, v175
	v_fma_f32 v12, v12, s46, v175
	v_fma_f32 v13, v13, s46, v175
	v_exp_f32_e32 v10, v10
	v_exp_f32_e32 v11, v11
	v_exp_f32_e32 v12, v12
	v_exp_f32_e32 v13, v13
	v_add_f32_e32 v171, v171, v6
	v_add_f32_e32 v170, v170, v7
	v_add_f32_e32 v171, v171, v8
	v_add_f32_e32 v170, v170, v9
	v_fma_f32 v14, v14, s46, v175
	v_fma_f32 v15, v15, s46, v175
	v_fma_f32 v16, v16, s46, v175
	v_fma_f32 v17, v17, s46, v175
	v_exp_f32_e32 v14, v14
	v_exp_f32_e32 v15, v15
	v_exp_f32_e32 v16, v16
	v_exp_f32_e32 v17, v17
	v_add_f32_e32 v171, v171, v10
	v_add_f32_e32 v170, v170, v11
	v_add_f32_e32 v171, v171, v12
	v_add_f32_e32 v170, v170, v13
	v_fma_f32 v18, v18, s46, v175
	v_fma_f32 v19, v19, s46, v175
	v_fma_f32 v20, v20, s46, v175
	v_fma_f32 v21, v21, s46, v175
	v_exp_f32_e32 v18, v18
	v_exp_f32_e32 v19, v19
	v_exp_f32_e32 v20, v20
	v_exp_f32_e32 v21, v21
	v_add_f32_e32 v171, v171, v14
	v_add_f32_e32 v170, v170, v15
	v_add_f32_e32 v171, v171, v16
	v_add_f32_e32 v170, v170, v17
	v_fma_f32 v22, v22, s46, v175
	v_fma_f32 v23, v23, s46, v175
	v_fma_f32 v24, v24, s46, v175
	v_fma_f32 v25, v25, s46, v175
	v_exp_f32_e32 v22, v22
	v_exp_f32_e32 v23, v23
	v_exp_f32_e32 v24, v24
	v_exp_f32_e32 v25, v25
	v_add_f32_e32 v171, v171, v18
	v_add_f32_e32 v170, v170, v19
	v_add_f32_e32 v171, v171, v20
	v_add_f32_e32 v170, v170, v21
	v_fma_f32 v26, v26, s46, v175
	v_fma_f32 v27, v27, s46, v175
	v_fma_f32 v28, v28, s46, v175
	v_fma_f32 v29, v29, s46, v175
	v_exp_f32_e32 v26, v26
	v_exp_f32_e32 v27, v27
	v_exp_f32_e32 v28, v28
	v_exp_f32_e32 v29, v29
	v_add_f32_e32 v171, v171, v22
	v_add_f32_e32 v170, v170, v23
	v_add_f32_e32 v171, v171, v24
	v_add_f32_e32 v170, v170, v25
	v_fma_f32 v30, v30, s46, v175
	v_fma_f32 v31, v31, s46, v175
	v_fma_f32 v32, v32, s46, v175
	v_fma_f32 v33, v33, s46, v175
	v_exp_f32_e32 v30, v30
	v_exp_f32_e32 v31, v31
	v_exp_f32_e32 v32, v32
	v_exp_f32_e32 v33, v33
	v_add_f32_e32 v171, v171, v26
	v_add_f32_e32 v170, v170, v27
	v_add_f32_e32 v171, v171, v28
	v_add_f32_e32 v170, v170, v29
	v_fma_f32 v34, v34, s46, v175
	v_fma_f32 v35, v35, s46, v175
	v_fma_f32 v36, v36, s46, v175
	v_fma_f32 v37, v37, s46, v175
	v_exp_f32_e32 v34, v34
	v_exp_f32_e32 v35, v35
	v_exp_f32_e32 v36, v36
	v_exp_f32_e32 v37, v37
	v_add_f32_e32 v171, v171, v30
	v_add_f32_e32 v170, v170, v31
	v_add_f32_e32 v171, v171, v32
	v_add_f32_e32 v170, v170, v33
	v_fma_f32 v38, v38, s46, v175
	v_fma_f32 v39, v39, s46, v175
	v_fma_f32 v40, v40, s46, v175
	v_fma_f32 v41, v41, s46, v175
	v_exp_f32_e32 v38, v38
	v_exp_f32_e32 v39, v39
	v_exp_f32_e32 v40, v40
	v_exp_f32_e32 v41, v41
	v_add_f32_e32 v171, v171, v34
	v_add_f32_e32 v170, v170, v35
	v_add_f32_e32 v171, v171, v36
	v_add_f32_e32 v170, v170, v37
	v_fma_f32 v42, v42, s46, v175
	v_fma_f32 v43, v43, s46, v175
	v_fma_f32 v44, v44, s46, v175
	v_fma_f32 v45, v45, s46, v175
	v_exp_f32_e32 v42, v42
	v_exp_f32_e32 v43, v43
	v_exp_f32_e32 v44, v44
	v_exp_f32_e32 v45, v45
	v_add_f32_e32 v171, v171, v38
	v_add_f32_e32 v170, v170, v39
	v_add_f32_e32 v171, v171, v40
	v_add_f32_e32 v170, v170, v41
	v_fma_f32 v46, v46, s46, v175
	v_fma_f32 v47, v47, s46, v175
	v_fma_f32 v48, v48, s46, v175
	v_fma_f32 v49, v49, s46, v175
	v_exp_f32_e32 v46, v46
	v_exp_f32_e32 v47, v47
	v_exp_f32_e32 v48, v48
	v_exp_f32_e32 v49, v49
	v_add_f32_e32 v171, v171, v42
	v_add_f32_e32 v170, v170, v43
	v_add_f32_e32 v171, v171, v44
	v_add_f32_e32 v170, v170, v45
	v_fma_f32 v50, v50, s46, v175
	v_fma_f32 v51, v51, s46, v175
	v_fma_f32 v52, v52, s46, v175
	v_fma_f32 v53, v53, s46, v175
	v_exp_f32_e32 v50, v50
	v_exp_f32_e32 v51, v51
	v_exp_f32_e32 v52, v52
	v_exp_f32_e32 v53, v53
	v_add_f32_e32 v171, v171, v46
	v_add_f32_e32 v170, v170, v47
	v_add_f32_e32 v171, v171, v48
	v_add_f32_e32 v170, v170, v49
	v_fma_f32 v54, v54, s46, v175
	v_fma_f32 v55, v55, s46, v175
	v_fma_f32 v56, v56, s46, v175
	v_fma_f32 v57, v57, s46, v175
	v_exp_f32_e32 v54, v54
	v_exp_f32_e32 v55, v55
	v_exp_f32_e32 v56, v56
	v_exp_f32_e32 v57, v57
	v_add_f32_e32 v171, v171, v50
	v_add_f32_e32 v170, v170, v51
	v_add_f32_e32 v171, v171, v52
	v_add_f32_e32 v170, v170, v53
	v_fma_f32 v58, v58, s46, v175
	v_fma_f32 v59, v59, s46, v175
	v_fma_f32 v60, v60, s46, v175
	v_fma_f32 v61, v61, s46, v175
	v_exp_f32_e32 v58, v58
	v_exp_f32_e32 v59, v59
	v_exp_f32_e32 v60, v60
	v_exp_f32_e32 v61, v61
	v_add_f32_e32 v171, v171, v54
	v_add_f32_e32 v170, v170, v55
	v_add_f32_e32 v171, v171, v56
	v_add_f32_e32 v170, v170, v57
	v_fma_f32 v62, v62, s46, v175
	v_fma_f32 v63, v63, s46, v175
	v_fma_f32 v64, v64, s46, v175
	v_fma_f32 v65, v65, s46, v175
	v_exp_f32_e32 v62, v62
	v_exp_f32_e32 v63, v63
	v_exp_f32_e32 v64, v64
	v_exp_f32_e32 v65, v65
	v_add_f32_e32 v171, v171, v58
	v_add_f32_e32 v170, v170, v59
	v_add_f32_e32 v171, v171, v60
	v_add_f32_e32 v170, v170, v61
	v_fma_f32 v66, v66, s46, v175
	v_fma_f32 v67, v67, s46, v175
	v_fma_f32 v68, v68, s46, v175
	v_fma_f32 v69, v69, s46, v175
	v_exp_f32_e32 v66, v66
	v_exp_f32_e32 v67, v67
; __device__ __forceinline__ unsigned cvt_pk_bf16_asm(float lo, float hi) { unsigned r; asm volatile("v_cvt_pk_bf16_f32 %0, %1, %2" : "=v"(r) : "v"(lo), "v"(hi)); return r; }
; __device__ __forceinline__ f32x4 mfma16(bf16x8 a, bf16x8 b, f32x4 c) { return __builtin_amdgcn_mfma_f32_16x16x32_bf16(a, b, c, 0, 0, 0); }
; __device__ void att_phase(int wv, const Params& p, unsigned char* lds) {
;     ...
;             float sum = 0.f;
; #pragma unroll
;             for (int cb = 0; cb < 24; ++cb)
; #pragma unroll
;                 for (int j = 0; j < 4; ++j) { const float e = __expf(sc[cb][j] - mx); sc[cb][j] = e; sum += e; }
;             sum += __shfl_xor(sum, 16); sum += __shfl_xor(sum, 32);
;             sum += __expf(sink - mx);
;             const float inv = 1.0f / sum;
;             f32x4 oa[4];
; #pragma unroll
;             for (int db = 0; db < 4; ++db) oa[db] = (f32x4){0, 0, 0, 0};
; #pragma unroll
;             for (int ks = 0; ks < 12; ++ks) {
;                 union { bf16x8 v; unsigned u[4]; } pf;
;                 pf.u[0] = cvt_pk_bf16_asm(sc[2 * ks][0], sc[2 * ks][1]); pf.u[1] = cvt_pk_bf16_asm(sc[2 * ks][2], sc[2 * ks][3]);
;                 pf.u[2] = cvt_pk_bf16_asm(sc[2 * ks + 1][0], sc[2 * ks + 1][1]); pf.u[3] = cvt_pk_bf16_asm(sc[2 * ks + 1][2], sc[2 * ks + 1][3]);
; #pragma unroll
;                 for (int db = 0; db < 4; ++db) {
;                     union { bf16x8 v; u32x2 h2[2]; } vf;
;                     const bf16_t* vp = VTL + (16 * db + lr) * VP + 32 * ks + 4 * lq;
;                     vf.h2[0] = *(const u32x2*)vp; vf.h2[1] = *(const u32x2*)(vp + 16);
;                     oa[db] = mfma16(vf.v, pf.v, oa[db]); } }
	v_exp_f32_e32 v68, v68
	v_exp_f32_e32 v69, v69
	v_add_f32_e32 v171, v171, v62
	v_add_f32_e32 v170, v170, v63
	v_add_f32_e32 v171, v171, v64
	v_add_f32_e32 v170, v170, v65
	v_add_f32_e32 v171, v171, v66
	v_add_f32_e32 v170, v170, v67
	v_add_f32_e32 v171, v171, v68
	v_add_f32_e32 v170, v170, v69
	v_add_f32_e32 v170, v170, v171
	v_cvt_pk_bf16_f32 v2, v2, v3
	v_cvt_pk_bf16_f32 v3, v4, v5
	v_cvt_pk_bf16_f32 v4, v6, v7
	v_cvt_pk_bf16_f32 v5, v8, v9
	v_cvt_pk_bf16_f32 v10, v10, v11
	v_cvt_pk_bf16_f32 v11, v12, v13
	v_cvt_pk_bf16_f32 v12, v14, v15
	v_cvt_pk_bf16_f32 v13, v16, v17
	v_cvt_pk_bf16_f32 v18, v18, v19
	v_cvt_pk_bf16_f32 v19, v20, v21
	v_cvt_pk_bf16_f32 v20, v22, v23
	v_cvt_pk_bf16_f32 v21, v24, v25
	v_cvt_pk_bf16_f32 v26, v26, v27
	v_cvt_pk_bf16_f32 v27, v28, v29
	v_cvt_pk_bf16_f32 v28, v30, v31
	v_cvt_pk_bf16_f32 v29, v32, v33
	v_cvt_pk_bf16_f32 v34, v34, v35
	v_cvt_pk_bf16_f32 v35, v36, v37
	v_cvt_pk_bf16_f32 v36, v38, v39
	v_cvt_pk_bf16_f32 v37, v40, v41
	v_cvt_pk_bf16_f32 v42, v42, v43
	v_cvt_pk_bf16_f32 v43, v44, v45
	v_cvt_pk_bf16_f32 v44, v46, v47
	v_cvt_pk_bf16_f32 v45, v48, v49
	v_cvt_pk_bf16_f32 v50, v50, v51
	v_cvt_pk_bf16_f32 v51, v52, v53
	v_cvt_pk_bf16_f32 v52, v54, v55
	v_cvt_pk_bf16_f32 v53, v56, v57
	v_cvt_pk_bf16_f32 v58, v58, v59
	v_cvt_pk_bf16_f32 v59, v60, v61
	v_cvt_pk_bf16_f32 v60, v62, v63
	v_cvt_pk_bf16_f32 v61, v64, v65
	v_cvt_pk_bf16_f32 v66, v66, v67
	v_cvt_pk_bf16_f32 v67, v68, v69
	v_mov_b32_e32 v68, 0
	v_mov_b32_e32 v69, 0
	ds_bpermute_b32 v172, v1, v170
	v_sub_f32_e32 v173, v146, v169
	v_mul_f32_e32 v173, 0x3fb8aa3b, v173
	v_exp_f32_e32 v173, v173
	s_waitcnt lgkmcnt(0)
	v_add_f32_e32 v170, v170, v172
	ds_bpermute_b32 v172, v114, v170
	ds_read2_b64 v[232:235], v165 offset0:20 offset1:24
	ds_read2_b64 v[236:239], v166 offset0:20 offset1:24
	ds_read2_b64 v[240:243], v167 offset0:20 offset1:24
	ds_read2_b64 v[244:247], v168 offset0:20 offset1:24
	s_waitcnt lgkmcnt(4)
	v_mfma_f32_16x16x32_bf16 v[70:73], v[216:219], v[2:5], 0
	v_mfma_f32_16x16x32_bf16 v[74:77], v[220:223], v[2:5], 0
	v_mfma_f32_16x16x32_bf16 v[78:81], v[224:227], v[2:5], 0
	v_mfma_f32_16x16x32_bf16 v[82:85], v[228:231], v[2:5], 0
	v_add_f32_e32 v170, v170, v172
	v_add_f32_e32 v170, v170, v173
	v_rcp_f32_e32 v147, v170
	s_nop 0
	v_fma_f32 v179, -v170, v147, 1.0
	v_fmac_f32_e32 v147, v179, v147
	ds_read2_b64 v[216:219], v165 offset0:28 offset1:32
	ds_read2_b64 v[220:223], v166 offset0:28 offset1:32
	ds_read2_b64 v[224:227], v167 offset0:28 offset1:32
	ds_read2_b64 v[228:231], v168 offset0:28 offset1:32
	s_waitcnt lgkmcnt(4)
	v_mfma_f32_16x16x32_bf16 v[70:73], v[232:235], v[10:13], v[70:73]
	v_mfma_f32_16x16x32_bf16 v[74:77], v[236:239], v[10:13], v[74:77]
	v_mfma_f32_16x16x32_bf16 v[78:81], v[240:243], v[10:13], v[78:81]
	v_mfma_f32_16x16x32_bf16 v[82:85], v[244:247], v[10:13], v[82:85]
	ds_read2_b64 v[232:235], v165 offset0:36 offset1:40
	ds_read2_b64 v[236:239], v166 offset0:36 offset1:40
	ds_read2_b64 v[240:243], v167 offset0:36 offset1:40
	ds_read2_b64 v[244:247], v168 offset0:36 offset1:40
	s_waitcnt lgkmcnt(4)
	v_mfma_f32_16x16x32_bf16 v[70:73], v[216:219], v[18:21], v[70:73]
	v_mfma_f32_16x16x32_bf16 v[74:77], v[220:223], v[18:21], v[74:77]
	v_mfma_f32_16x16x32_bf16 v[78:81], v[224:227], v[18:21], v[78:81]
	v_mfma_f32_16x16x32_bf16 v[82:85], v[228:231], v[18:21], v[82:85]
	ds_read2_b64 v[216:219], v165 offset0:44 offset1:48
	ds_read2_b64 v[220:223], v166 offset0:44 offset1:48
	ds_read2_b64 v[224:227], v167 offset0:44 offset1:48
	ds_read2_b64 v[228:231], v168 offset0:44 offset1:48
	s_waitcnt lgkmcnt(4)
	v_mfma_f32_16x16x32_bf16 v[70:73], v[232:235], v[26:29], v[70:73]
	v_mfma_f32_16x16x32_bf16 v[74:77], v[236:239], v[26:29], v[74:77]
	v_mfma_f32_16x16x32_bf16 v[78:81], v[240:243], v[26:29], v[78:81]
	v_mfma_f32_16x16x32_bf16 v[82:85], v[244:247], v[26:29], v[82:85]
	ds_read2_b64 v[232:235], v165 offset0:52 offset1:56
	ds_read2_b64 v[236:239], v166 offset0:52 offset1:56
	ds_read2_b64 v[240:243], v167 offset0:52 offset1:56
	ds_read2_b64 v[244:247], v168 offset0:52 offset1:56
	s_waitcnt lgkmcnt(4)
	v_mfma_f32_16x16x32_bf16 v[70:73], v[216:219], v[34:37], v[70:73]
	v_mfma_f32_16x16x32_bf16 v[74:77], v[220:223], v[34:37], v[74:77]
	v_mfma_f32_16x16x32_bf16 v[78:81], v[224:227], v[34:37], v[78:81]
	v_mfma_f32_16x16x32_bf16 v[82:85], v[228:231], v[34:37], v[82:85]
	ds_read2_b64 v[216:219], v165 offset0:60 offset1:64
	ds_read2_b64 v[220:223], v166 offset0:60 offset1:64
	ds_read2_b64 v[224:227], v167 offset0:60 offset1:64
	ds_read2_b64 v[228:231], v168 offset0:60 offset1:64
	s_waitcnt lgkmcnt(4)
	v_mfma_f32_16x16x32_bf16 v[70:73], v[232:235], v[42:45], v[70:73]
	v_mfma_f32_16x16x32_bf16 v[74:77], v[236:239], v[42:45], v[74:77]
	v_mfma_f32_16x16x32_bf16 v[78:81], v[240:243], v[42:45], v[78:81]
	v_mfma_f32_16x16x32_bf16 v[82:85], v[244:247], v[42:45], v[82:85]
	ds_read2_b64 v[232:235], v165 offset0:68 offset1:72
	ds_read2_b64 v[236:239], v166 offset0:68 offset1:72
	ds_read2_b64 v[240:243], v167 offset0:68 offset1:72
	ds_read2_b64 v[244:247], v168 offset0:68 offset1:72
	s_waitcnt lgkmcnt(4)
	v_mfma_f32_16x16x32_bf16 v[70:73], v[216:219], v[50:53], v[70:73]
	v_mfma_f32_16x16x32_bf16 v[74:77], v[220:223], v[50:53], v[74:77]
	v_mfma_f32_16x16x32_bf16 v[78:81], v[224:227], v[50:53], v[78:81]
	v_mfma_f32_16x16x32_bf16 v[82:85], v[228:231], v[50:53], v[82:85]
	ds_read2_b64 v[216:219], v165 offset0:76 offset1:76
	ds_read2_b64 v[220:223], v166 offset0:76 offset1:76
	ds_read2_b64 v[224:227], v167 offset0:76 offset1:76
	ds_read2_b64 v[228:231], v168 offset0:76 offset1:76
	s_waitcnt lgkmcnt(4)
; __device__ __forceinline__ unsigned cvt_pk_bf16_asm(float lo, float hi) { unsigned r; asm volatile("v_cvt_pk_bf16_f32 %0, %1, %2" : "=v"(r) : "v"(lo), "v"(hi)); return r; }
; __device__ __forceinline__ f32x4 mfma16(bf16x8 a, bf16x8 b, f32x4 c) { return __builtin_amdgcn_mfma_f32_16x16x32_bf16(a, b, c, 0, 0, 0); }
; __device__ void att_phase(int wv, const Params& p, unsigned char* lds) {
;     ...
;         const int gq = w >> 1, h = 4 * kh + gq;
;         const float slope = exp2f(-0.5f * (float)(h + 1)), sink = p.b_sinks[h];
;         for (int rb = 0; rb < 4; ++rb) {
;             const int qrow = 64 * (w & 1) + 16 * rb + lr;
;             const size_t tokq = (size_t)B * 128 + qrow;
;             bf16x8 qf[2];
; #pragma unroll
;             for (int kk = 0; kk < 2; ++kk) qf[kk] = *(const bf16x8*)(qkv + tokq * 1536 + 64 * h + 32 * kk + 8 * lq);
;             f32x4 sc[24];
; #pragma unroll
;             for (int cb = 0; cb < 24; ++cb) { f32x4 a = {0, 0, 0, 0};
; #pragma unroll
;                 for (int kk = 0; kk < 2; ++kk) { const bf16x8 kf = *(const bf16x8*)(KL + (16 * cb + lr) * KP + 32 * kk + 8 * lq); a = mfma16(kf, qf[kk], a); }
;                 sc[cb] = a; }
;     ...
;             for (int db = 0; db < 4; ++db) { const f32x4 o = oa[db] * inv; u32x2 wv; wv.x = cvt_pk_bf16_asm(o[0], o[1]); wv.y = cvt_pk_bf16_asm(o[2], o[3]);
;                 *(u32x2*)(qkv + tokq * 1536 + 64 * h + 16 * db + 4 * lq) = wv; }
	v_mfma_f32_16x16x32_bf16 v[70:73], v[232:235], v[58:61], v[70:73]
	v_mfma_f32_16x16x32_bf16 v[74:77], v[236:239], v[58:61], v[74:77]
	v_mfma_f32_16x16x32_bf16 v[78:81], v[240:243], v[58:61], v[78:81]
	v_mfma_f32_16x16x32_bf16 v[82:85], v[244:247], v[58:61], v[82:85]
	s_waitcnt lgkmcnt(0)
	v_mfma_f32_16x16x32_bf16 v[70:73], v[216:219], v[66:69], v[70:73]
	v_mfma_f32_16x16x32_bf16 v[74:77], v[220:223], v[66:69], v[74:77]
	v_mfma_f32_16x16x32_bf16 v[78:81], v[224:227], v[66:69], v[78:81]
	v_mfma_f32_16x16x32_bf16 v[82:85], v[228:231], v[66:69], v[82:85]
	s_nop 7
	s_nop 1
	v_mul_f32_e32 v70, v70, v147
	v_mul_f32_e32 v71, v71, v147
	v_mul_f32_e32 v72, v72, v147
	v_mul_f32_e32 v73, v73, v147
	v_mul_f32_e32 v74, v74, v147
	v_mul_f32_e32 v75, v75, v147
	v_mul_f32_e32 v76, v76, v147
	v_mul_f32_e32 v77, v77, v147
	v_mul_f32_e32 v78, v78, v147
	v_mul_f32_e32 v79, v79, v147
	v_mul_f32_e32 v80, v80, v147
	v_mul_f32_e32 v81, v81, v147
	v_mul_f32_e32 v82, v82, v147
	v_mul_f32_e32 v83, v83, v147
	v_mul_f32_e32 v84, v84, v147
	v_mul_f32_e32 v85, v85, v147
	v_cvt_pk_bf16_f32 v70, v70, v71
	v_cvt_pk_bf16_f32 v71, v72, v73
	v_cvt_pk_bf16_f32 v74, v74, v75
	v_cvt_pk_bf16_f32 v75, v76, v77
	v_cvt_pk_bf16_f32 v78, v78, v79
	v_cvt_pk_bf16_f32 v79, v80, v81
	v_cvt_pk_bf16_f32 v82, v82, v83
	v_cvt_pk_bf16_f32 v83, v84, v85
	global_store_dwordx2 v[248:249], v[70:71], off offset:-64
	global_store_dwordx2 v[248:249], v[74:75], off offset:-32
	global_store_dwordx2 v[248:249], v[78:79], off
	global_store_dwordx2 v[248:249], v[82:83], off offset:32
	s_branch .Latt_done
.Latt_general:
	s_waitcnt vmcnt(0)
	s_mov_b32 s46, 0x3e38aa3b
	s_and_b32 s47, s33, 1
	s_mul_i32 s22, s47, 0x2400
	v_add_u32_e32 v164, s22, v141
	s_lshl_b32 s22, s47, 7
	s_add_i32 s22, s22, 0xd800
	v_add_u32_e32 v165, s22, v142
	v_add_u32_e32 v166, s22, v143
	v_add_u32_e32 v167, s22, v144
	v_add_u32_e32 v168, s22, v145
	s_lshl_b32 s47, s47, 2
	v_and_b32_e32 v172, 15, v250
	v_lshrrev_b32_e32 v173, 4, v250
	v_lshlrev_b32_e32 v173, 2, v173
	v_sub_u32_e32 v108, v172, v173
	v_subrev_u32_e32 v110, 1, v108
	v_subrev_u32_e32 v111, 2, v108
	v_subrev_u32_e32 v177, 3, v108
	v_mul_f32_e32 v147, 0xc1000000, v109
	v_mul_f32_e32 v174, 0x43000000, v109
	v_mul_f32_e32 v176, 0x44800000, v109
	v_cvt_f32_i32_e32 v179, v108
	v_mul_f32_e32 v94, v147, v179
	v_mul_f32_e64 v98, v147, |v179|
	v_cvt_f32_i32_e32 v179, v110
	v_mul_f32_e32 v95, v147, v179
	v_mul_f32_e64 v99, v147, |v179|
	v_cvt_f32_i32_e32 v179, v111
	v_mul_f32_e32 v96, v147, v179
	v_mul_f32_e64 v100, v147, |v179|
	v_cvt_f32_i32_e32 v179, v177
	v_mul_f32_e32 v97, v147, v179
	v_mul_f32_e64 v101, v147, |v179|
	v_lshl_add_u64 v[248:249], v[112:113], 0, s[0:1]
	v_sub_f32_e32 v86, v94, v176
	v_sub_f32_e32 v87, v95, v176
	v_sub_f32_e32 v88, v96, v176
	v_sub_f32_e32 v89, v97, v176
	v_cmp_ge_i32_e32 vcc, 0, v108
	s_nop 1
	v_cndmask_b32_e32 v212, v252, v86, vcc
	v_cmp_ge_i32_e32 vcc, 0, v110
	s_nop 1
	v_cndmask_b32_e32 v213, v252, v87, vcc
	v_cmp_ge_i32_e32 vcc, 0, v111
	s_nop 1
	v_cndmask_b32_e32 v214, v252, v88, vcc
	v_cmp_ge_i32_e32 vcc, 0, v177
	s_nop 1
	v_cndmask_b32_e32 v215, v252, v89, vcc
	ds_read_b128 v[148:151], v164 offset:0
	ds_read_b128 v[152:155], v164 offset:64
	ds_read_b128 v[156:159], v164 offset:2304
	ds_read_b128 v[160:163], v164 offset:2368
	v_add_f32_e32 v90, v86, v174
	v_add_f32_e32 v91, v87, v174
	v_add_f32_e32 v92, v88, v174
	v_add_f32_e32 v93, v89, v174
	s_cmp_lt_i32 s47, 16
	s_cselect_b64 vcc, -1, s[10:11]
	s_cmp_lt_i32 s47, 8
	s_cselect_b64 vcc, s[6:7], vcc
	v_cndmask_b32_e32 v232, v252, v212, vcc
	v_cndmask_b32_e32 v233, v252, v213, vcc
	v_cndmask_b32_e32 v234, v252, v214, vcc
	v_cndmask_b32_e32 v235, v252, v215, vcc
	s_waitcnt lgkmcnt(2)
	v_mfma_f32_16x16x32_bf16 v[2:5], v[148:151], v[180:183], v[232:235]
	v_mfma_f32_16x16x32_bf16 v[2:5], v[152:155], v[184:187], v[2:5]
	ds_read_b128 v[148:151], v164 offset:4608
	ds_read_b128 v[152:155], v164 offset:4672
	v_add_f32_e32 v86, v90, v174
	v_add_f32_e32 v87, v91, v174
	v_add_f32_e32 v88, v92, v174
	v_add_f32_e32 v89, v93, v174
	s_cmp_lt_i32 s47, 15
	s_cselect_b64 vcc, -1, s[10:11]
	s_cmp_lt_i32 s47, 7
	s_cselect_b64 vcc, s[6:7], vcc
	v_cndmask_b32_e32 v236, v252, v90, vcc
	v_cndmask_b32_e32 v237, v252, v91, vcc
	v_cndmask_b32_e32 v238, v252, v92, vcc
	v_cndmask_b32_e32 v239, v252, v93, vcc
	s_waitcnt lgkmcnt(2)
	v_mfma_f32_16x16x32_bf16 v[6:9], v[156:159], v[180:183], v[236:239]
	v_mfma_f32_16x16x32_bf16 v[6:9], v[160:163], v[184:187], v[6:9]
	ds_read_b128 v[156:159], v164 offset:6912
	ds_read_b128 v[160:163], v164 offset:6976
	v_add_f32_e32 v90, v86, v174
	v_add_f32_e32 v91, v87, v174
	v_add_f32_e32 v92, v88, v174
	v_add_f32_e32 v93, v89, v174
	s_cmp_lt_i32 s47, 14
	s_cselect_b64 vcc, -1, s[10:11]
	s_cmp_lt_i32 s47, 6
	s_cselect_b64 vcc, s[6:7], vcc
	v_cndmask_b32_e32 v232, v252, v86, vcc
	v_cndmask_b32_e32 v233, v252, v87, vcc
	v_cndmask_b32_e32 v234, v252, v88, vcc
	v_cndmask_b32_e32 v235, v252, v89, vcc
	s_waitcnt lgkmcnt(2)
	v_mfma_f32_16x16x32_bf16 v[10:13], v[148:151], v[180:183], v[232:235]
	v_mfma_f32_16x16x32_bf16 v[10:13], v[152:155], v[184:187], v[10:13]
	ds_read_b128 v[148:151], v164 offset:9216
	ds_read_b128 v[152:155], v164 offset:9280
	v_add_f32_e32 v86, v90, v174
	v_add_f32_e32 v87, v91, v174
	v_add_f32_e32 v88, v92, v174
	v_add_f32_e32 v89, v93, v174
	s_cmp_lt_i32 s47, 13
	s_cselect_b64 vcc, -1, s[10:11]
	s_cmp_lt_i32 s47, 5
	s_cselect_b64 vcc, s[6:7], vcc
	v_cndmask_b32_e32 v236, v252, v90, vcc
	v_cndmask_b32_e32 v237, v252, v91, vcc
	v_cndmask_b32_e32 v238, v252, v92, vcc
	v_cndmask_b32_e32 v239, v252, v93, vcc
	s_waitcnt lgkmcnt(2)
; __device__ __forceinline__ f32x4 mfma16(bf16x8 a, bf16x8 b, f32x4 c) { return __builtin_amdgcn_mfma_f32_16x16x32_bf16(a, b, c, 0, 0, 0); }
; __device__ void att_phase(int wv, const Params& p, unsigned char* lds) {
;     ...
;             f32x4 sc[24];
; #pragma unroll
;             for (int cb = 0; cb < 24; ++cb) { f32x4 a = {0, 0, 0, 0};
; #pragma unroll
;                 for (int kk = 0; kk < 2; ++kk) { const bf16x8 kf = *(const bf16x8*)(KL + (16 * cb + lr) * KP + 32 * kk + 8 * lq); a = mfma16(kf, qf[kk], a); }
;                 sc[cb] = a; }
;             float mx = sink;
; #pragma unroll
;             for (int cb = 0; cb < 24; ++cb) { const int kb = B - 1 + (cb >> 3); const bool bval = (kb >= sb && kb < se);
; #pragma unroll
;                 for (int j = 0; j < 4; ++j) { const int krel = 16 * cb + 4 * lq + j - 128;
;                     int dist = qrow - krel; dist = dist < 0 ? -dist : dist;
;                     const float v = (bval && dist <= 128) ? sc[cb][j] * 0.125f - slope * (float)dist : -1e30f;
;                     sc[cb][j] = v; mx = fmaxf(mx, v); } }
	v_mfma_f32_16x16x32_bf16 v[14:17], v[156:159], v[180:183], v[236:239]
	v_mfma_f32_16x16x32_bf16 v[14:17], v[160:163], v[184:187], v[14:17]
	ds_read_b128 v[156:159], v164 offset:11520
	ds_read_b128 v[160:163], v164 offset:11584
	v_add_f32_e32 v90, v86, v174
	v_add_f32_e32 v91, v87, v174
	v_add_f32_e32 v92, v88, v174
	v_add_f32_e32 v93, v89, v174
	s_cmp_lt_i32 s47, 12
	s_cselect_b64 vcc, -1, s[10:11]
	s_cmp_lt_i32 s47, 4
	s_cselect_b64 vcc, s[6:7], vcc
	v_cndmask_b32_e32 v232, v252, v86, vcc
	v_cndmask_b32_e32 v233, v252, v87, vcc
	v_cndmask_b32_e32 v234, v252, v88, vcc
	v_cndmask_b32_e32 v235, v252, v89, vcc
	s_waitcnt lgkmcnt(2)
	v_mfma_f32_16x16x32_bf16 v[18:21], v[148:151], v[180:183], v[232:235]
	v_mfma_f32_16x16x32_bf16 v[18:21], v[152:155], v[184:187], v[18:21]
	ds_read_b128 v[148:151], v164 offset:13824
	ds_read_b128 v[152:155], v164 offset:13888
	v_add_f32_e32 v86, v90, v174
	v_add_f32_e32 v87, v91, v174
	v_add_f32_e32 v88, v92, v174
	v_add_f32_e32 v89, v93, v174
	s_cmp_lt_i32 s47, 11
	s_cselect_b64 vcc, -1, s[10:11]
	s_cmp_lt_i32 s47, 3
	s_cselect_b64 vcc, s[6:7], vcc
	v_cndmask_b32_e32 v236, v252, v90, vcc
	v_cndmask_b32_e32 v237, v252, v91, vcc
	v_cndmask_b32_e32 v238, v252, v92, vcc
	v_cndmask_b32_e32 v239, v252, v93, vcc
	s_waitcnt lgkmcnt(2)
	v_mfma_f32_16x16x32_bf16 v[22:25], v[156:159], v[180:183], v[236:239]
	v_mfma_f32_16x16x32_bf16 v[22:25], v[160:163], v[184:187], v[22:25]
	ds_read_b128 v[156:159], v164 offset:16128
	ds_read_b128 v[160:163], v164 offset:16192
	v_add_f32_e32 v90, v86, v174
	v_add_f32_e32 v91, v87, v174
	v_add_f32_e32 v92, v88, v174
	v_add_f32_e32 v93, v89, v174
	s_cmp_lt_i32 s47, 10
	s_cselect_b64 vcc, -1, s[10:11]
	s_cmp_lt_i32 s47, 2
	s_cselect_b64 vcc, s[6:7], vcc
	v_cndmask_b32_e32 v232, v252, v86, vcc
	v_cndmask_b32_e32 v233, v252, v87, vcc
	v_cndmask_b32_e32 v234, v252, v88, vcc
	v_cndmask_b32_e32 v235, v252, v89, vcc
	s_waitcnt lgkmcnt(2)
	v_mfma_f32_16x16x32_bf16 v[26:29], v[148:151], v[180:183], v[232:235]
	v_mfma_f32_16x16x32_bf16 v[26:29], v[152:155], v[184:187], v[26:29]
	ds_read_b128 v[148:151], v164 offset:18432
	ds_read_b128 v[152:155], v164 offset:18496
	s_cmp_lt_i32 s47, 9
	s_cselect_b64 vcc, -1, s[10:11]
	s_cmp_lt_i32 s47, 1
	s_cselect_b64 vcc, s[6:7], vcc
	v_cndmask_b32_e32 v236, v252, v90, vcc
	v_cndmask_b32_e32 v237, v252, v91, vcc
	v_cndmask_b32_e32 v238, v252, v92, vcc
	v_cndmask_b32_e32 v239, v252, v93, vcc
	s_waitcnt lgkmcnt(2)
	v_mfma_f32_16x16x32_bf16 v[30:33], v[156:159], v[180:183], v[236:239]
	v_mfma_f32_16x16x32_bf16 v[30:33], v[160:163], v[184:187], v[30:33]
	ds_read_b128 v[156:159], v164 offset:20736
	ds_read_b128 v[160:163], v164 offset:20800
	v_sub_f32_e64 v86, -v94, v174
	v_sub_f32_e64 v87, -v95, v174
	v_sub_f32_e64 v88, -v96, v174
	v_sub_f32_e64 v89, -v97, v174
	s_waitcnt lgkmcnt(2)
	v_mfma_f32_16x16x32_bf16 v[34:37], v[148:151], v[180:183], v[98:101]
	v_mfma_f32_16x16x32_bf16 v[34:37], v[152:155], v[184:187], v[34:37]
	ds_read_b128 v[148:151], v164 offset:23040
	ds_read_b128 v[152:155], v164 offset:23104
	v_sub_f32_e32 v90, v86, v174
	v_sub_f32_e32 v91, v87, v174
	v_sub_f32_e32 v92, v88, v174
	v_sub_f32_e32 v93, v89, v174
	s_waitcnt lgkmcnt(2)
	v_mfma_f32_16x16x32_bf16 v[38:41], v[156:159], v[180:183], v[86:89]
	v_mfma_f32_16x16x32_bf16 v[38:41], v[160:163], v[184:187], v[38:41]
	ds_read_b128 v[156:159], v164 offset:25344
	ds_read_b128 v[160:163], v164 offset:25408
	v_sub_f32_e32 v86, v90, v174
	v_sub_f32_e32 v87, v91, v174
	v_sub_f32_e32 v88, v92, v174
	v_sub_f32_e32 v89, v93, v174
	s_waitcnt lgkmcnt(2)
	v_mfma_f32_16x16x32_bf16 v[42:45], v[148:151], v[180:183], v[90:93]
	v_mfma_f32_16x16x32_bf16 v[42:45], v[152:155], v[184:187], v[42:45]
	ds_read_b128 v[148:151], v164 offset:27648
	ds_read_b128 v[152:155], v164 offset:27712
	v_sub_f32_e32 v90, v86, v174
	v_sub_f32_e32 v91, v87, v174
	v_sub_f32_e32 v92, v88, v174
	v_sub_f32_e32 v93, v89, v174
	s_waitcnt lgkmcnt(2)
	v_mfma_f32_16x16x32_bf16 v[46:49], v[156:159], v[180:183], v[86:89]
	v_mfma_f32_16x16x32_bf16 v[46:49], v[160:163], v[184:187], v[46:49]
	ds_read_b128 v[156:159], v164 offset:29952
	ds_read_b128 v[160:163], v164 offset:30016
	v_sub_f32_e32 v86, v90, v174
	v_sub_f32_e32 v87, v91, v174
	v_sub_f32_e32 v88, v92, v174
	v_sub_f32_e32 v89, v93, v174
	s_cmp_lt_i32 s47, 4
	s_cselect_b64 vcc, -1, s[10:11]
	s_cmp_lt_i32 s47, -4
	s_cselect_b64 vcc, s[6:7], vcc
	v_cndmask_b32_e32 v232, v252, v90, vcc
	v_cndmask_b32_e32 v233, v252, v91, vcc
	v_cndmask_b32_e32 v234, v252, v92, vcc
	v_cndmask_b32_e32 v235, v252, v93, vcc
	s_waitcnt lgkmcnt(2)
	v_mfma_f32_16x16x32_bf16 v[50:53], v[148:151], v[180:183], v[232:235]
	v_mfma_f32_16x16x32_bf16 v[50:53], v[152:155], v[184:187], v[50:53]
	ds_read_b128 v[148:151], v164 offset:32256
	ds_read_b128 v[152:155], v164 offset:32320
	v_sub_f32_e32 v90, v86, v174
	v_sub_f32_e32 v91, v87, v174
	v_sub_f32_e32 v92, v88, v174
	v_sub_f32_e32 v93, v89, v174
	s_cmp_lt_i32 s47, 3
	s_cselect_b64 vcc, -1, s[10:11]
	s_cmp_lt_i32 s47, -5
	s_cselect_b64 vcc, s[6:7], vcc
	v_cndmask_b32_e32 v236, v252, v86, vcc
	v_cndmask_b32_e32 v237, v252, v87, vcc
	v_cndmask_b32_e32 v238, v252, v88, vcc
	v_cndmask_b32_e32 v239, v252, v89, vcc
	s_waitcnt lgkmcnt(2)
	v_mfma_f32_16x16x32_bf16 v[54:57], v[156:159], v[180:183], v[236:239]
	v_mfma_f32_16x16x32_bf16 v[54:57], v[160:163], v[184:187], v[54:57]
	ds_read_b128 v[156:159], v164 offset:34560
	ds_read_b128 v[160:163], v164 offset:34624
	v_sub_f32_e32 v86, v90, v174
	v_sub_f32_e32 v87, v91, v174
	v_sub_f32_e32 v88, v92, v174
	v_sub_f32_e32 v89, v93, v174
	s_cmp_lt_i32 s47, 2
	s_cselect_b64 vcc, -1, s[10:11]
	s_cmp_lt_i32 s47, -6
	s_cselect_b64 vcc, s[6:7], vcc
	v_cndmask_b32_e32 v232, v252, v90, vcc
	v_cndmask_b32_e32 v233, v252, v91, vcc
	v_cndmask_b32_e32 v234, v252, v92, vcc
	v_cndmask_b32_e32 v235, v252, v93, vcc
	s_waitcnt lgkmcnt(2)
; __device__ __forceinline__ f32x4 mfma16(bf16x8 a, bf16x8 b, f32x4 c) { return __builtin_amdgcn_mfma_f32_16x16x32_bf16(a, b, c, 0, 0, 0); }
; __device__ void att_phase(int wv, const Params& p, unsigned char* lds) {
;     ...
;             f32x4 sc[24];
; #pragma unroll
;             for (int cb = 0; cb < 24; ++cb) { f32x4 a = {0, 0, 0, 0};
; #pragma unroll
;                 for (int kk = 0; kk < 2; ++kk) { const bf16x8 kf = *(const bf16x8*)(KL + (16 * cb + lr) * KP + 32 * kk + 8 * lq); a = mfma16(kf, qf[kk], a); }
;                 sc[cb] = a; }
;             float mx = sink;
; #pragma unroll
;             for (int cb = 0; cb < 24; ++cb) { const int kb = B - 1 + (cb >> 3); const bool bval = (kb >= sb && kb < se);
; #pragma unroll
;                 for (int j = 0; j < 4; ++j) { const int krel = 16 * cb + 4 * lq + j - 128;
;                     int dist = qrow - krel; dist = dist < 0 ? -dist : dist;
;                     const float v = (bval && dist <= 128) ? sc[cb][j] * 0.125f - slope * (float)dist : -1e30f;
;                     sc[cb][j] = v; mx = fmaxf(mx, v); } }
;             mx = fmaxf(mx, __shfl_xor(mx, 16)); mx = fmaxf(mx, __shfl_xor(mx, 32));
	v_mfma_f32_16x16x32_bf16 v[58:61], v[148:151], v[180:183], v[232:235]
	v_mfma_f32_16x16x32_bf16 v[58:61], v[152:155], v[184:187], v[58:61]
	ds_read_b128 v[148:151], v164 offset:36864
	ds_read_b128 v[152:155], v164 offset:36928
	v_sub_f32_e32 v90, v86, v174
	v_sub_f32_e32 v91, v87, v174
	v_sub_f32_e32 v92, v88, v174
	v_sub_f32_e32 v93, v89, v174
	v_cmp_le_i32_e32 vcc, 0, v108
	s_nop 1
	v_cndmask_b32_e32 v212, v252, v90, vcc
	v_cmp_le_i32_e32 vcc, 0, v110
	s_nop 1
	v_cndmask_b32_e32 v213, v252, v91, vcc
	v_cmp_le_i32_e32 vcc, 0, v111
	s_nop 1
	v_cndmask_b32_e32 v214, v252, v92, vcc
	v_cmp_le_i32_e32 vcc, 0, v177
	s_nop 1
	v_cndmask_b32_e32 v215, v252, v93, vcc
	s_cmp_lt_i32 s47, 1
	s_cselect_b64 vcc, -1, s[10:11]
	s_cmp_lt_i32 s47, -7
	s_cselect_b64 vcc, s[6:7], vcc
	v_cndmask_b32_e32 v236, v252, v86, vcc
	v_cndmask_b32_e32 v237, v252, v87, vcc
	v_cndmask_b32_e32 v238, v252, v88, vcc
	v_cndmask_b32_e32 v239, v252, v89, vcc
	s_waitcnt lgkmcnt(2)
	v_mfma_f32_16x16x32_bf16 v[62:65], v[156:159], v[180:183], v[236:239]
	v_mfma_f32_16x16x32_bf16 v[62:65], v[160:163], v[184:187], v[62:65]
	s_cmp_lt_i32 s47, 0
	s_cselect_b64 vcc, -1, s[10:11]
	s_cmp_lt_i32 s47, -8
	s_cselect_b64 vcc, s[6:7], vcc
	v_cndmask_b32_e32 v232, v252, v212, vcc
	v_cndmask_b32_e32 v233, v252, v213, vcc
	v_cndmask_b32_e32 v234, v252, v214, vcc
	v_cndmask_b32_e32 v235, v252, v215, vcc
	s_waitcnt lgkmcnt(0)
	v_mfma_f32_16x16x32_bf16 v[66:69], v[148:151], v[180:183], v[232:235]
	v_mfma_f32_16x16x32_bf16 v[66:69], v[152:155], v[184:187], v[66:69]
	ds_read2_b64 v[216:219], v165 offset0:0 offset1:4
	ds_read2_b64 v[220:223], v166 offset0:0 offset1:4
	ds_read2_b64 v[224:227], v167 offset0:0 offset1:4
	ds_read2_b64 v[228:231], v168 offset0:0 offset1:4
	v_max3_f32 v169, v2, v3, v4
	v_max3_f32 v172, v5, v6, v7
	v_max3_f32 v169, v8, v9, v169
	v_max3_f32 v172, v10, v11, v172
	v_max3_f32 v169, v12, v13, v169
	v_max3_f32 v172, v14, v15, v172
	v_max3_f32 v169, v16, v17, v169
	v_max3_f32 v172, v18, v19, v172
	v_max3_f32 v169, v20, v21, v169
	v_max3_f32 v172, v22, v23, v172
	v_max3_f32 v169, v24, v25, v169
	v_max3_f32 v172, v26, v27, v172
	v_max3_f32 v169, v28, v29, v169
	v_max3_f32 v172, v30, v31, v172
	v_max3_f32 v169, v32, v33, v169
	v_max3_f32 v172, v34, v35, v172
	v_max3_f32 v169, v36, v37, v169
	v_max3_f32 v172, v38, v39, v172
	v_max3_f32 v169, v40, v41, v169
	v_max3_f32 v172, v42, v43, v172
	v_max3_f32 v169, v44, v45, v169
	v_max3_f32 v172, v46, v47, v172
	v_max3_f32 v169, v48, v49, v169
	v_max3_f32 v172, v50, v51, v172
	v_max3_f32 v169, v52, v53, v169
	v_max3_f32 v172, v54, v55, v172
	v_max3_f32 v169, v56, v57, v169
	v_max3_f32 v172, v58, v59, v172
	v_max3_f32 v169, v60, v61, v169
	v_max3_f32 v172, v62, v63, v172
	v_max3_f32 v169, v64, v65, v169
	v_max3_f32 v172, v66, v67, v172
	v_max3_f32 v169, v68, v69, v169
	v_max_f32_e32 v169, v169, v172
	v_mul_f32_e32 v169, 0x3e000000, v169
	v_max_f32_e32 v169, v169, v146
	ds_bpermute_b32 v172, v1, v169
	s_waitcnt lgkmcnt(0)
	v_max_f32_e32 v169, v169, v172
	ds_bpermute_b32 v172, v114, v169
	s_waitcnt lgkmcnt(0)
	v_max_f32_e32 v169, v169, v172
	v_mul_f32_e32 v175, 0xbfb8aa3b, v169
	v_mov_b32_e32 v170, 0
	v_mov_b32_e32 v171, 0
	v_fma_f32 v2, v2, s46, v175
	v_fma_f32 v3, v3, s46, v175
	v_fma_f32 v4, v4, s46, v175
	v_fma_f32 v5, v5, s46, v175
	v_exp_f32_e32 v2, v2
	v_exp_f32_e32 v3, v3
	v_exp_f32_e32 v4, v4
	v_exp_f32_e32 v5, v5
	v_fma_f32 v6, v6, s46, v175
	v_fma_f32 v7, v7, s46, v175
	v_fma_f32 v8, v8, s46, v175
	v_fma_f32 v9, v9, s46, v175
	v_exp_f32_e32 v6, v6
	v_exp_f32_e32 v7, v7
	v_exp_f32_e32 v8, v8
	v_exp_f32_e32 v9, v9
	v_add_f32_e32 v171, v171, v2
	v_add_f32_e32 v170, v170, v3
	v_add_f32_e32 v171, v171, v4
	v_add_f32_e32 v170, v170, v5
	v_fma_f32 v10, v10, s46, v175
	v_fma_f32 v11, v11, s46, v175
	v_fma_f32 v12, v12, s46, v175
	v_fma_f32 v13, v13, s46, v175
	v_exp_f32_e32 v10, v10
	v_exp_f32_e32 v11, v11
	v_exp_f32_e32 v12, v12
	v_exp_f32_e32 v13, v13
	v_add_f32_e32 v171, v171, v6
	v_add_f32_e32 v170, v170, v7
	v_add_f32_e32 v171, v171, v8
	v_add_f32_e32 v170, v170, v9
	v_fma_f32 v14, v14, s46, v175
	v_fma_f32 v15, v15, s46, v175
	v_fma_f32 v16, v16, s46, v175
	v_fma_f32 v17, v17, s46, v175
	v_exp_f32_e32 v14, v14
	v_exp_f32_e32 v15, v15
	v_exp_f32_e32 v16, v16
	v_exp_f32_e32 v17, v17
	v_add_f32_e32 v171, v171, v10
	v_add_f32_e32 v170, v170, v11
	v_add_f32_e32 v171, v171, v12
	v_add_f32_e32 v170, v170, v13
	v_fma_f32 v18, v18, s46, v175
	v_fma_f32 v19, v19, s46, v175
	v_fma_f32 v20, v20, s46, v175
	v_fma_f32 v21, v21, s46, v175
	v_exp_f32_e32 v18, v18
	v_exp_f32_e32 v19, v19
	v_exp_f32_e32 v20, v20
	v_exp_f32_e32 v21, v21
	v_add_f32_e32 v171, v171, v14
	v_add_f32_e32 v170, v170, v15
	v_add_f32_e32 v171, v171, v16
	v_add_f32_e32 v170, v170, v17
	v_fma_f32 v22, v22, s46, v175
	v_fma_f32 v23, v23, s46, v175
	v_fma_f32 v24, v24, s46, v175
	v_fma_f32 v25, v25, s46, v175
	v_exp_f32_e32 v22, v22
	v_exp_f32_e32 v23, v23
	v_exp_f32_e32 v24, v24
	v_exp_f32_e32 v25, v25
	v_add_f32_e32 v171, v171, v18
	v_add_f32_e32 v170, v170, v19
	v_add_f32_e32 v171, v171, v20
	v_add_f32_e32 v170, v170, v21
	v_fma_f32 v26, v26, s46, v175
	v_fma_f32 v27, v27, s46, v175
	v_fma_f32 v28, v28, s46, v175
	v_fma_f32 v29, v29, s46, v175
	v_exp_f32_e32 v26, v26
	v_exp_f32_e32 v27, v27
	v_exp_f32_e32 v28, v28
	v_exp_f32_e32 v29, v29
	v_add_f32_e32 v171, v171, v22
	v_add_f32_e32 v170, v170, v23
	v_add_f32_e32 v171, v171, v24
	v_add_f32_e32 v170, v170, v25
	v_fma_f32 v30, v30, s46, v175
	v_fma_f32 v31, v31, s46, v175
	v_fma_f32 v32, v32, s46, v175
	v_fma_f32 v33, v33, s46, v175
	v_exp_f32_e32 v30, v30
	v_exp_f32_e32 v31, v31
	v_exp_f32_e32 v32, v32
	v_exp_f32_e32 v33, v33
; __device__ __forceinline__ unsigned cvt_pk_bf16_asm(float lo, float hi) { unsigned r; asm volatile("v_cvt_pk_bf16_f32 %0, %1, %2" : "=v"(r) : "v"(lo), "v"(hi)); return r; }
; __device__ __forceinline__ f32x4 mfma16(bf16x8 a, bf16x8 b, f32x4 c) { return __builtin_amdgcn_mfma_f32_16x16x32_bf16(a, b, c, 0, 0, 0); }
; __device__ void att_phase(int wv, const Params& p, unsigned char* lds) {
;     ...
;             mx = fmaxf(mx, __shfl_xor(mx, 16)); mx = fmaxf(mx, __shfl_xor(mx, 32));
;             float sum = 0.f;
; #pragma unroll
;             for (int cb = 0; cb < 24; ++cb)
; #pragma unroll
;                 for (int j = 0; j < 4; ++j) { const float e = __expf(sc[cb][j] - mx); sc[cb][j] = e; sum += e; }
;             sum += __shfl_xor(sum, 16); sum += __shfl_xor(sum, 32);
;             sum += __expf(sink - mx);
;             const float inv = 1.0f / sum;
;             f32x4 oa[4];
; #pragma unroll
;             for (int db = 0; db < 4; ++db) oa[db] = (f32x4){0, 0, 0, 0};
; #pragma unroll
;             for (int ks = 0; ks < 12; ++ks) {
;                 union { bf16x8 v; unsigned u[4]; } pf;
;                 pf.u[0] = cvt_pk_bf16_asm(sc[2 * ks][0], sc[2 * ks][1]); pf.u[1] = cvt_pk_bf16_asm(sc[2 * ks][2], sc[2 * ks][3]);
;                 pf.u[2] = cvt_pk_bf16_asm(sc[2 * ks + 1][0], sc[2 * ks + 1][1]); pf.u[3] = cvt_pk_bf16_asm(sc[2 * ks + 1][2], sc[2 * ks + 1][3]);
; #pragma unroll
;                 for (int db = 0; db < 4; ++db) {
;                     union { bf16x8 v; u32x2 h2[2]; } vf;
;                     const bf16_t* vp = VTL + (16 * db + lr) * VP + 32 * ks + 4 * lq;
;                     vf.h2[0] = *(const u32x2*)vp; vf.h2[1] = *(const u32x2*)(vp + 16);
;                     oa[db] = mfma16(vf.v, pf.v, oa[db]); } }
	v_add_f32_e32 v171, v171, v26
	v_add_f32_e32 v170, v170, v27
	v_add_f32_e32 v171, v171, v28
	v_add_f32_e32 v170, v170, v29
	v_fma_f32 v34, v34, s46, v175
	v_fma_f32 v35, v35, s46, v175
	v_fma_f32 v36, v36, s46, v175
	v_fma_f32 v37, v37, s46, v175
	v_exp_f32_e32 v34, v34
	v_exp_f32_e32 v35, v35
	v_exp_f32_e32 v36, v36
	v_exp_f32_e32 v37, v37
	v_add_f32_e32 v171, v171, v30
	v_add_f32_e32 v170, v170, v31
	v_add_f32_e32 v171, v171, v32
	v_add_f32_e32 v170, v170, v33
	v_fma_f32 v38, v38, s46, v175
	v_fma_f32 v39, v39, s46, v175
	v_fma_f32 v40, v40, s46, v175
	v_fma_f32 v41, v41, s46, v175
	v_exp_f32_e32 v38, v38
	v_exp_f32_e32 v39, v39
	v_exp_f32_e32 v40, v40
	v_exp_f32_e32 v41, v41
	v_add_f32_e32 v171, v171, v34
	v_add_f32_e32 v170, v170, v35
	v_add_f32_e32 v171, v171, v36
	v_add_f32_e32 v170, v170, v37
	v_fma_f32 v42, v42, s46, v175
	v_fma_f32 v43, v43, s46, v175
	v_fma_f32 v44, v44, s46, v175
	v_fma_f32 v45, v45, s46, v175
	v_exp_f32_e32 v42, v42
	v_exp_f32_e32 v43, v43
	v_exp_f32_e32 v44, v44
	v_exp_f32_e32 v45, v45
	v_add_f32_e32 v171, v171, v38
	v_add_f32_e32 v170, v170, v39
	v_add_f32_e32 v171, v171, v40
	v_add_f32_e32 v170, v170, v41
	v_fma_f32 v46, v46, s46, v175
	v_fma_f32 v47, v47, s46, v175
	v_fma_f32 v48, v48, s46, v175
	v_fma_f32 v49, v49, s46, v175
	v_exp_f32_e32 v46, v46
	v_exp_f32_e32 v47, v47
	v_exp_f32_e32 v48, v48
	v_exp_f32_e32 v49, v49
	v_add_f32_e32 v171, v171, v42
	v_add_f32_e32 v170, v170, v43
	v_add_f32_e32 v171, v171, v44
	v_add_f32_e32 v170, v170, v45
	v_fma_f32 v50, v50, s46, v175
	v_fma_f32 v51, v51, s46, v175
	v_fma_f32 v52, v52, s46, v175
	v_fma_f32 v53, v53, s46, v175
	v_exp_f32_e32 v50, v50
	v_exp_f32_e32 v51, v51
	v_exp_f32_e32 v52, v52
	v_exp_f32_e32 v53, v53
	v_add_f32_e32 v171, v171, v46
	v_add_f32_e32 v170, v170, v47
	v_add_f32_e32 v171, v171, v48
	v_add_f32_e32 v170, v170, v49
	v_fma_f32 v54, v54, s46, v175
	v_fma_f32 v55, v55, s46, v175
	v_fma_f32 v56, v56, s46, v175
	v_fma_f32 v57, v57, s46, v175
	v_exp_f32_e32 v54, v54
	v_exp_f32_e32 v55, v55
	v_exp_f32_e32 v56, v56
	v_exp_f32_e32 v57, v57
	v_add_f32_e32 v171, v171, v50
	v_add_f32_e32 v170, v170, v51
	v_add_f32_e32 v171, v171, v52
	v_add_f32_e32 v170, v170, v53
	v_fma_f32 v58, v58, s46, v175
	v_fma_f32 v59, v59, s46, v175
	v_fma_f32 v60, v60, s46, v175
	v_fma_f32 v61, v61, s46, v175
	v_exp_f32_e32 v58, v58
	v_exp_f32_e32 v59, v59
	v_exp_f32_e32 v60, v60
	v_exp_f32_e32 v61, v61
	v_add_f32_e32 v171, v171, v54
	v_add_f32_e32 v170, v170, v55
	v_add_f32_e32 v171, v171, v56
	v_add_f32_e32 v170, v170, v57
	v_fma_f32 v62, v62, s46, v175
	v_fma_f32 v63, v63, s46, v175
	v_fma_f32 v64, v64, s46, v175
	v_fma_f32 v65, v65, s46, v175
	v_exp_f32_e32 v62, v62
	v_exp_f32_e32 v63, v63
	v_exp_f32_e32 v64, v64
	v_exp_f32_e32 v65, v65
	v_add_f32_e32 v171, v171, v58
	v_add_f32_e32 v170, v170, v59
	v_add_f32_e32 v171, v171, v60
	v_add_f32_e32 v170, v170, v61
	v_fma_f32 v66, v66, s46, v175
	v_fma_f32 v67, v67, s46, v175
	v_fma_f32 v68, v68, s46, v175
	v_fma_f32 v69, v69, s46, v175
	v_exp_f32_e32 v66, v66
	v_exp_f32_e32 v67, v67
	v_exp_f32_e32 v68, v68
	v_exp_f32_e32 v69, v69
	v_add_f32_e32 v171, v171, v62
	v_add_f32_e32 v170, v170, v63
	v_add_f32_e32 v171, v171, v64
	v_add_f32_e32 v170, v170, v65
	v_add_f32_e32 v171, v171, v66
	v_add_f32_e32 v170, v170, v67
	v_add_f32_e32 v171, v171, v68
	v_add_f32_e32 v170, v170, v69
	v_add_f32_e32 v170, v170, v171
	v_cvt_pk_bf16_f32 v2, v2, v3
	v_cvt_pk_bf16_f32 v3, v4, v5
	v_cvt_pk_bf16_f32 v4, v6, v7
	v_cvt_pk_bf16_f32 v5, v8, v9
	v_cvt_pk_bf16_f32 v10, v10, v11
	v_cvt_pk_bf16_f32 v11, v12, v13
	v_cvt_pk_bf16_f32 v12, v14, v15
	v_cvt_pk_bf16_f32 v13, v16, v17
	v_cvt_pk_bf16_f32 v18, v18, v19
	v_cvt_pk_bf16_f32 v19, v20, v21
	v_cvt_pk_bf16_f32 v20, v22, v23
	v_cvt_pk_bf16_f32 v21, v24, v25
	v_cvt_pk_bf16_f32 v26, v26, v27
	v_cvt_pk_bf16_f32 v27, v28, v29
	v_cvt_pk_bf16_f32 v28, v30, v31
	v_cvt_pk_bf16_f32 v29, v32, v33
	v_cvt_pk_bf16_f32 v34, v34, v35
	v_cvt_pk_bf16_f32 v35, v36, v37
	v_cvt_pk_bf16_f32 v36, v38, v39
	v_cvt_pk_bf16_f32 v37, v40, v41
	v_cvt_pk_bf16_f32 v42, v42, v43
	v_cvt_pk_bf16_f32 v43, v44, v45
	v_cvt_pk_bf16_f32 v44, v46, v47
	v_cvt_pk_bf16_f32 v45, v48, v49
	v_cvt_pk_bf16_f32 v50, v50, v51
	v_cvt_pk_bf16_f32 v51, v52, v53
	v_cvt_pk_bf16_f32 v52, v54, v55
	v_cvt_pk_bf16_f32 v53, v56, v57
	v_cvt_pk_bf16_f32 v58, v58, v59
	v_cvt_pk_bf16_f32 v59, v60, v61
	v_cvt_pk_bf16_f32 v60, v62, v63
	v_cvt_pk_bf16_f32 v61, v64, v65
	v_cvt_pk_bf16_f32 v66, v66, v67
	v_cvt_pk_bf16_f32 v67, v68, v69
	v_mov_b32_e32 v68, 0
	v_mov_b32_e32 v69, 0
	ds_bpermute_b32 v172, v1, v170
	v_sub_f32_e32 v173, v146, v169
	v_mul_f32_e32 v173, 0x3fb8aa3b, v173
	v_exp_f32_e32 v173, v173
	s_waitcnt lgkmcnt(0)
	v_add_f32_e32 v170, v170, v172
	ds_bpermute_b32 v172, v114, v170
	ds_read2_b64 v[232:235], v165 offset0:8 offset1:12
	ds_read2_b64 v[236:239], v166 offset0:8 offset1:12
	ds_read2_b64 v[240:243], v167 offset0:8 offset1:12
	ds_read2_b64 v[244:247], v168 offset0:8 offset1:12
	s_waitcnt lgkmcnt(4)
	v_mfma_f32_16x16x32_bf16 v[70:73], v[216:219], v[2:5], 0
	v_mfma_f32_16x16x32_bf16 v[74:77], v[220:223], v[2:5], 0
	v_mfma_f32_16x16x32_bf16 v[78:81], v[224:227], v[2:5], 0
	v_mfma_f32_16x16x32_bf16 v[82:85], v[228:231], v[2:5], 0
	v_add_f32_e32 v170, v170, v172
	v_add_f32_e32 v170, v170, v173
	v_rcp_f32_e32 v147, v170
	s_nop 0
	v_fma_f32 v179, -v170, v147, 1.0
	v_fmac_f32_e32 v147, v179, v147
	ds_read2_b64 v[216:219], v165 offset0:16 offset1:20
	ds_read2_b64 v[220:223], v166 offset0:16 offset1:20
	ds_read2_b64 v[224:227], v167 offset0:16 offset1:20
	ds_read2_b64 v[228:231], v168 offset0:16 offset1:20
	s_waitcnt lgkmcnt(4)
; __device__ __forceinline__ unsigned cvt_pk_bf16_asm(float lo, float hi) { unsigned r; asm volatile("v_cvt_pk_bf16_f32 %0, %1, %2" : "=v"(r) : "v"(lo), "v"(hi)); return r; }
; __device__ __forceinline__ f32x4 mfma16(bf16x8 a, bf16x8 b, f32x4 c) { return __builtin_amdgcn_mfma_f32_16x16x32_bf16(a, b, c, 0, 0, 0); }
; __device__ void att_phase(int wv, const Params& p, unsigned char* lds) {
;     ...
;             f32x4 sc[24];
; #pragma unroll
;             for (int cb = 0; cb < 24; ++cb) { f32x4 a = {0, 0, 0, 0};
; #pragma unroll
;                 for (int kk = 0; kk < 2; ++kk) { const bf16x8 kf = *(const bf16x8*)(KL + (16 * cb + lr) * KP + 32 * kk + 8 * lq); a = mfma16(kf, qf[kk], a); }
;                 sc[cb] = a; }
;     ...
;             for (int ks = 0; ks < 12; ++ks) {
;                 union { bf16x8 v; unsigned u[4]; } pf;
;                 pf.u[0] = cvt_pk_bf16_asm(sc[2 * ks][0], sc[2 * ks][1]); pf.u[1] = cvt_pk_bf16_asm(sc[2 * ks][2], sc[2 * ks][3]);
;                 pf.u[2] = cvt_pk_bf16_asm(sc[2 * ks + 1][0], sc[2 * ks + 1][1]); pf.u[3] = cvt_pk_bf16_asm(sc[2 * ks + 1][2], sc[2 * ks + 1][3]);
; #pragma unroll
;                 for (int db = 0; db < 4; ++db) {
;                     union { bf16x8 v; u32x2 h2[2]; } vf;
;                     const bf16_t* vp = VTL + (16 * db + lr) * VP + 32 * ks + 4 * lq;
;                     vf.h2[0] = *(const u32x2*)vp; vf.h2[1] = *(const u32x2*)(vp + 16);
;                     oa[db] = mfma16(vf.v, pf.v, oa[db]); } }
; #pragma unroll
;             for (int db = 0; db < 4; ++db) { const f32x4 o = oa[db] * inv; u32x2 wv; wv.x = cvt_pk_bf16_asm(o[0], o[1]); wv.y = cvt_pk_bf16_asm(o[2], o[3]);
;                 *(u32x2*)(qkv + tokq * 1536 + 64 * h + 16 * db + 4 * lq) = wv; }
	v_mfma_f32_16x16x32_bf16 v[70:73], v[232:235], v[10:13], v[70:73]
	v_mfma_f32_16x16x32_bf16 v[74:77], v[236:239], v[10:13], v[74:77]
	v_mfma_f32_16x16x32_bf16 v[78:81], v[240:243], v[10:13], v[78:81]
	v_mfma_f32_16x16x32_bf16 v[82:85], v[244:247], v[10:13], v[82:85]
	ds_read2_b64 v[232:235], v165 offset0:24 offset1:28
	ds_read2_b64 v[236:239], v166 offset0:24 offset1:28
	ds_read2_b64 v[240:243], v167 offset0:24 offset1:28
	ds_read2_b64 v[244:247], v168 offset0:24 offset1:28
	s_waitcnt lgkmcnt(4)
	v_mfma_f32_16x16x32_bf16 v[70:73], v[216:219], v[18:21], v[70:73]
	v_mfma_f32_16x16x32_bf16 v[74:77], v[220:223], v[18:21], v[74:77]
	v_mfma_f32_16x16x32_bf16 v[78:81], v[224:227], v[18:21], v[78:81]
	v_mfma_f32_16x16x32_bf16 v[82:85], v[228:231], v[18:21], v[82:85]
	ds_read2_b64 v[216:219], v165 offset0:32 offset1:36
	ds_read2_b64 v[220:223], v166 offset0:32 offset1:36
	ds_read2_b64 v[224:227], v167 offset0:32 offset1:36
	ds_read2_b64 v[228:231], v168 offset0:32 offset1:36
	s_waitcnt lgkmcnt(4)
	v_mfma_f32_16x16x32_bf16 v[70:73], v[232:235], v[26:29], v[70:73]
	v_mfma_f32_16x16x32_bf16 v[74:77], v[236:239], v[26:29], v[74:77]
	v_mfma_f32_16x16x32_bf16 v[78:81], v[240:243], v[26:29], v[78:81]
	v_mfma_f32_16x16x32_bf16 v[82:85], v[244:247], v[26:29], v[82:85]
	ds_read2_b64 v[232:235], v165 offset0:40 offset1:44
	ds_read2_b64 v[236:239], v166 offset0:40 offset1:44
	ds_read2_b64 v[240:243], v167 offset0:40 offset1:44
	ds_read2_b64 v[244:247], v168 offset0:40 offset1:44
	s_waitcnt lgkmcnt(4)
	v_mfma_f32_16x16x32_bf16 v[70:73], v[216:219], v[34:37], v[70:73]
	v_mfma_f32_16x16x32_bf16 v[74:77], v[220:223], v[34:37], v[74:77]
	v_mfma_f32_16x16x32_bf16 v[78:81], v[224:227], v[34:37], v[78:81]
	v_mfma_f32_16x16x32_bf16 v[82:85], v[228:231], v[34:37], v[82:85]
	ds_read2_b64 v[216:219], v165 offset0:48 offset1:52
	ds_read2_b64 v[220:223], v166 offset0:48 offset1:52
	ds_read2_b64 v[224:227], v167 offset0:48 offset1:52
	ds_read2_b64 v[228:231], v168 offset0:48 offset1:52
	s_waitcnt lgkmcnt(4)
	v_mfma_f32_16x16x32_bf16 v[70:73], v[232:235], v[42:45], v[70:73]
	v_mfma_f32_16x16x32_bf16 v[74:77], v[236:239], v[42:45], v[74:77]
	v_mfma_f32_16x16x32_bf16 v[78:81], v[240:243], v[42:45], v[78:81]
	v_mfma_f32_16x16x32_bf16 v[82:85], v[244:247], v[42:45], v[82:85]
	ds_read2_b64 v[232:235], v165 offset0:56 offset1:60
	ds_read2_b64 v[236:239], v166 offset0:56 offset1:60
	ds_read2_b64 v[240:243], v167 offset0:56 offset1:60
	ds_read2_b64 v[244:247], v168 offset0:56 offset1:60
	s_waitcnt lgkmcnt(4)
	v_mfma_f32_16x16x32_bf16 v[70:73], v[216:219], v[50:53], v[70:73]
	v_mfma_f32_16x16x32_bf16 v[74:77], v[220:223], v[50:53], v[74:77]
	v_mfma_f32_16x16x32_bf16 v[78:81], v[224:227], v[50:53], v[78:81]
	v_mfma_f32_16x16x32_bf16 v[82:85], v[228:231], v[50:53], v[82:85]
	ds_read2_b64 v[216:219], v165 offset0:64 offset1:64
	ds_read2_b64 v[220:223], v166 offset0:64 offset1:64
	ds_read2_b64 v[224:227], v167 offset0:64 offset1:64
	ds_read2_b64 v[228:231], v168 offset0:64 offset1:64
	s_waitcnt lgkmcnt(4)
	v_mfma_f32_16x16x32_bf16 v[70:73], v[232:235], v[58:61], v[70:73]
	v_mfma_f32_16x16x32_bf16 v[74:77], v[236:239], v[58:61], v[74:77]
	v_mfma_f32_16x16x32_bf16 v[78:81], v[240:243], v[58:61], v[78:81]
	v_mfma_f32_16x16x32_bf16 v[82:85], v[244:247], v[58:61], v[82:85]
	s_waitcnt lgkmcnt(0)
	v_mfma_f32_16x16x32_bf16 v[70:73], v[216:219], v[66:69], v[70:73]
	v_mfma_f32_16x16x32_bf16 v[74:77], v[220:223], v[66:69], v[74:77]
	v_mfma_f32_16x16x32_bf16 v[78:81], v[224:227], v[66:69], v[78:81]
	v_mfma_f32_16x16x32_bf16 v[82:85], v[228:231], v[66:69], v[82:85]
	s_nop 7
	s_nop 1
	v_mul_f32_e32 v70, v70, v147
	v_mul_f32_e32 v71, v71, v147
	v_mul_f32_e32 v72, v72, v147
	v_mul_f32_e32 v73, v73, v147
	v_mul_f32_e32 v74, v74, v147
	v_mul_f32_e32 v75, v75, v147
	v_mul_f32_e32 v76, v76, v147
	v_mul_f32_e32 v77, v77, v147
	v_mul_f32_e32 v78, v78, v147
	v_mul_f32_e32 v79, v79, v147
	v_mul_f32_e32 v80, v80, v147
	v_mul_f32_e32 v81, v81, v147
	v_mul_f32_e32 v82, v82, v147
	v_mul_f32_e32 v83, v83, v147
	v_mul_f32_e32 v84, v84, v147
	v_mul_f32_e32 v85, v85, v147
	v_cvt_pk_bf16_f32 v70, v70, v71
	v_cvt_pk_bf16_f32 v71, v72, v73
	v_cvt_pk_bf16_f32 v74, v74, v75
	v_cvt_pk_bf16_f32 v75, v76, v77
	v_cvt_pk_bf16_f32 v78, v78, v79
	v_cvt_pk_bf16_f32 v79, v80, v81
	v_cvt_pk_bf16_f32 v82, v82, v83
	v_cvt_pk_bf16_f32 v83, v84, v85
	global_store_dwordx2 v[248:249], v[70:71], off offset:-64
	global_store_dwordx2 v[248:249], v[74:75], off offset:-32
	global_store_dwordx2 v[248:249], v[78:79], off
	global_store_dwordx2 v[248:249], v[82:83], off offset:32
	v_lshl_add_u64 v[248:249], v[248:249], 0, s[48:49]
	v_sub_f32_e32 v86, v94, v176
	v_sub_f32_e32 v87, v95, v176
	v_sub_f32_e32 v88, v96, v176
	v_sub_f32_e32 v89, v97, v176
	v_cmp_ge_i32_e32 vcc, 0, v108
	s_nop 1
	v_cndmask_b32_e32 v212, v252, v86, vcc
	v_cmp_ge_i32_e32 vcc, 0, v110
	s_nop 1
	v_cndmask_b32_e32 v213, v252, v87, vcc
	v_cmp_ge_i32_e32 vcc, 0, v111
	s_nop 1
	v_cndmask_b32_e32 v214, v252, v88, vcc
	v_cmp_ge_i32_e32 vcc, 0, v177
	s_nop 1
	v_cndmask_b32_e32 v215, v252, v89, vcc
	ds_read_b128 v[148:151], v164 offset:2304
	ds_read_b128 v[152:155], v164 offset:2368
	ds_read_b128 v[156:159], v164 offset:4608
	ds_read_b128 v[160:163], v164 offset:4672
	v_add_f32_e32 v90, v86, v174
	v_add_f32_e32 v91, v87, v174
	v_add_f32_e32 v92, v88, v174
	v_add_f32_e32 v93, v89, v174
	s_cmp_lt_i32 s47, 15
	s_cselect_b64 vcc, -1, s[10:11]
	s_cmp_lt_i32 s47, 7
	s_cselect_b64 vcc, s[6:7], vcc
	v_cndmask_b32_e32 v232, v252, v212, vcc
	v_cndmask_b32_e32 v233, v252, v213, vcc
	v_cndmask_b32_e32 v234, v252, v214, vcc
	v_cndmask_b32_e32 v235, v252, v215, vcc
	s_waitcnt lgkmcnt(2)
; __device__ __forceinline__ f32x4 mfma16(bf16x8 a, bf16x8 b, f32x4 c) { return __builtin_amdgcn_mfma_f32_16x16x32_bf16(a, b, c, 0, 0, 0); }
; __device__ void att_phase(int wv, const Params& p, unsigned char* lds) {
;     ...
;             f32x4 sc[24];
; #pragma unroll
;             for (int cb = 0; cb < 24; ++cb) { f32x4 a = {0, 0, 0, 0};
; #pragma unroll
;                 for (int kk = 0; kk < 2; ++kk) { const bf16x8 kf = *(const bf16x8*)(KL + (16 * cb + lr) * KP + 32 * kk + 8 * lq); a = mfma16(kf, qf[kk], a); }
;                 sc[cb] = a; }
;             float mx = sink;
; #pragma unroll
;             for (int cb = 0; cb < 24; ++cb) { const int kb = B - 1 + (cb >> 3); const bool bval = (kb >= sb && kb < se);
; #pragma unroll
;                 for (int j = 0; j < 4; ++j) { const int krel = 16 * cb + 4 * lq + j - 128;
;                     int dist = qrow - krel; dist = dist < 0 ? -dist : dist;
;                     const float v = (bval && dist <= 128) ? sc[cb][j] * 0.125f - slope * (float)dist : -1e30f;
;                     sc[cb][j] = v; mx = fmaxf(mx, v); } }
	v_mfma_f32_16x16x32_bf16 v[2:5], v[148:151], v[188:191], v[232:235]
	v_mfma_f32_16x16x32_bf16 v[2:5], v[152:155], v[192:195], v[2:5]
	ds_read_b128 v[148:151], v164 offset:6912
	ds_read_b128 v[152:155], v164 offset:6976
	v_add_f32_e32 v86, v90, v174
	v_add_f32_e32 v87, v91, v174
	v_add_f32_e32 v88, v92, v174
	v_add_f32_e32 v89, v93, v174
	s_cmp_lt_i32 s47, 14
	s_cselect_b64 vcc, -1, s[10:11]
	s_cmp_lt_i32 s47, 6
	s_cselect_b64 vcc, s[6:7], vcc
	v_cndmask_b32_e32 v236, v252, v90, vcc
	v_cndmask_b32_e32 v237, v252, v91, vcc
	v_cndmask_b32_e32 v238, v252, v92, vcc
	v_cndmask_b32_e32 v239, v252, v93, vcc
	s_waitcnt lgkmcnt(2)
	v_mfma_f32_16x16x32_bf16 v[6:9], v[156:159], v[188:191], v[236:239]
	v_mfma_f32_16x16x32_bf16 v[6:9], v[160:163], v[192:195], v[6:9]
	ds_read_b128 v[156:159], v164 offset:9216
	ds_read_b128 v[160:163], v164 offset:9280
	v_add_f32_e32 v90, v86, v174
	v_add_f32_e32 v91, v87, v174
	v_add_f32_e32 v92, v88, v174
	v_add_f32_e32 v93, v89, v174
	s_cmp_lt_i32 s47, 13
	s_cselect_b64 vcc, -1, s[10:11]
	s_cmp_lt_i32 s47, 5
	s_cselect_b64 vcc, s[6:7], vcc
	v_cndmask_b32_e32 v232, v252, v86, vcc
	v_cndmask_b32_e32 v233, v252, v87, vcc
	v_cndmask_b32_e32 v234, v252, v88, vcc
	v_cndmask_b32_e32 v235, v252, v89, vcc
	s_waitcnt lgkmcnt(2)
	v_mfma_f32_16x16x32_bf16 v[10:13], v[148:151], v[188:191], v[232:235]
	v_mfma_f32_16x16x32_bf16 v[10:13], v[152:155], v[192:195], v[10:13]
	ds_read_b128 v[148:151], v164 offset:11520
	ds_read_b128 v[152:155], v164 offset:11584
	v_add_f32_e32 v86, v90, v174
	v_add_f32_e32 v87, v91, v174
	v_add_f32_e32 v88, v92, v174
	v_add_f32_e32 v89, v93, v174
	s_cmp_lt_i32 s47, 12
	s_cselect_b64 vcc, -1, s[10:11]
	s_cmp_lt_i32 s47, 4
	s_cselect_b64 vcc, s[6:7], vcc
	v_cndmask_b32_e32 v236, v252, v90, vcc
	v_cndmask_b32_e32 v237, v252, v91, vcc
	v_cndmask_b32_e32 v238, v252, v92, vcc
	v_cndmask_b32_e32 v239, v252, v93, vcc
	s_waitcnt lgkmcnt(2)
	v_mfma_f32_16x16x32_bf16 v[14:17], v[156:159], v[188:191], v[236:239]
	v_mfma_f32_16x16x32_bf16 v[14:17], v[160:163], v[192:195], v[14:17]
	ds_read_b128 v[156:159], v164 offset:13824
	ds_read_b128 v[160:163], v164 offset:13888
	v_add_f32_e32 v90, v86, v174
	v_add_f32_e32 v91, v87, v174
	v_add_f32_e32 v92, v88, v174
	v_add_f32_e32 v93, v89, v174
	s_cmp_lt_i32 s47, 11
	s_cselect_b64 vcc, -1, s[10:11]
	s_cmp_lt_i32 s47, 3
	s_cselect_b64 vcc, s[6:7], vcc
	v_cndmask_b32_e32 v232, v252, v86, vcc
	v_cndmask_b32_e32 v233, v252, v87, vcc
	v_cndmask_b32_e32 v234, v252, v88, vcc
	v_cndmask_b32_e32 v235, v252, v89, vcc
	s_waitcnt lgkmcnt(2)
	v_mfma_f32_16x16x32_bf16 v[18:21], v[148:151], v[188:191], v[232:235]
	v_mfma_f32_16x16x32_bf16 v[18:21], v[152:155], v[192:195], v[18:21]
	ds_read_b128 v[148:151], v164 offset:16128
	ds_read_b128 v[152:155], v164 offset:16192
	v_add_f32_e32 v86, v90, v174
	v_add_f32_e32 v87, v91, v174
	v_add_f32_e32 v88, v92, v174
	v_add_f32_e32 v89, v93, v174
	s_cmp_lt_i32 s47, 10
	s_cselect_b64 vcc, -1, s[10:11]
	s_cmp_lt_i32 s47, 2
	s_cselect_b64 vcc, s[6:7], vcc
	v_cndmask_b32_e32 v236, v252, v90, vcc
	v_cndmask_b32_e32 v237, v252, v91, vcc
	v_cndmask_b32_e32 v238, v252, v92, vcc
	v_cndmask_b32_e32 v239, v252, v93, vcc
	s_waitcnt lgkmcnt(2)
	v_mfma_f32_16x16x32_bf16 v[22:25], v[156:159], v[188:191], v[236:239]
	v_mfma_f32_16x16x32_bf16 v[22:25], v[160:163], v[192:195], v[22:25]
	ds_read_b128 v[156:159], v164 offset:18432
	ds_read_b128 v[160:163], v164 offset:18496
	v_add_f32_e32 v90, v86, v174
	v_add_f32_e32 v91, v87, v174
	v_add_f32_e32 v92, v88, v174
	v_add_f32_e32 v93, v89, v174
	s_cmp_lt_i32 s47, 9
	s_cselect_b64 vcc, -1, s[10:11]
	s_cmp_lt_i32 s47, 1
	s_cselect_b64 vcc, s[6:7], vcc
	v_cndmask_b32_e32 v232, v252, v86, vcc
	v_cndmask_b32_e32 v233, v252, v87, vcc
	v_cndmask_b32_e32 v234, v252, v88, vcc
	v_cndmask_b32_e32 v235, v252, v89, vcc
	s_waitcnt lgkmcnt(2)
	v_mfma_f32_16x16x32_bf16 v[26:29], v[148:151], v[188:191], v[232:235]
	v_mfma_f32_16x16x32_bf16 v[26:29], v[152:155], v[192:195], v[26:29]
	ds_read_b128 v[148:151], v164 offset:20736
	ds_read_b128 v[152:155], v164 offset:20800
	s_waitcnt lgkmcnt(2)
	v_mfma_f32_16x16x32_bf16 v[30:33], v[156:159], v[188:191], v[90:93]
	v_mfma_f32_16x16x32_bf16 v[30:33], v[160:163], v[192:195], v[30:33]
	ds_read_b128 v[156:159], v164 offset:23040
	ds_read_b128 v[160:163], v164 offset:23104
	v_sub_f32_e64 v86, -v94, v174
	v_sub_f32_e64 v87, -v95, v174
	v_sub_f32_e64 v88, -v96, v174
	v_sub_f32_e64 v89, -v97, v174
	s_waitcnt lgkmcnt(2)
	v_mfma_f32_16x16x32_bf16 v[34:37], v[148:151], v[188:191], v[98:101]
	v_mfma_f32_16x16x32_bf16 v[34:37], v[152:155], v[192:195], v[34:37]
	ds_read_b128 v[148:151], v164 offset:25344
	ds_read_b128 v[152:155], v164 offset:25408
	v_sub_f32_e32 v90, v86, v174
	v_sub_f32_e32 v91, v87, v174
	v_sub_f32_e32 v92, v88, v174
	v_sub_f32_e32 v93, v89, v174
	s_waitcnt lgkmcnt(2)
	v_mfma_f32_16x16x32_bf16 v[38:41], v[156:159], v[188:191], v[86:89]
	v_mfma_f32_16x16x32_bf16 v[38:41], v[160:163], v[192:195], v[38:41]
	ds_read_b128 v[156:159], v164 offset:27648
	ds_read_b128 v[160:163], v164 offset:27712
	v_sub_f32_e32 v86, v90, v174
	v_sub_f32_e32 v87, v91, v174
	v_sub_f32_e32 v88, v92, v174
	v_sub_f32_e32 v89, v93, v174
	s_waitcnt lgkmcnt(2)
	v_mfma_f32_16x16x32_bf16 v[42:45], v[148:151], v[188:191], v[90:93]
	v_mfma_f32_16x16x32_bf16 v[42:45], v[152:155], v[192:195], v[42:45]
	ds_read_b128 v[148:151], v164 offset:29952
	ds_read_b128 v[152:155], v164 offset:30016
	v_sub_f32_e32 v90, v86, v174
	v_sub_f32_e32 v91, v87, v174
	v_sub_f32_e32 v92, v88, v174
	v_sub_f32_e32 v93, v89, v174
	s_cmp_lt_i32 s47, 4
	s_cselect_b64 vcc, -1, s[10:11]
	s_cmp_lt_i32 s47, -4
	s_cselect_b64 vcc, s[6:7], vcc
	v_cndmask_b32_e32 v236, v252, v86, vcc
	v_cndmask_b32_e32 v237, v252, v87, vcc
	v_cndmask_b32_e32 v238, v252, v88, vcc
	v_cndmask_b32_e32 v239, v252, v89, vcc
	s_waitcnt lgkmcnt(2)
; __device__ __forceinline__ f32x4 mfma16(bf16x8 a, bf16x8 b, f32x4 c) { return __builtin_amdgcn_mfma_f32_16x16x32_bf16(a, b, c, 0, 0, 0); }
; __device__ void att_phase(int wv, const Params& p, unsigned char* lds) {
;     ...
;             f32x4 sc[24];
; #pragma unroll
;             for (int cb = 0; cb < 24; ++cb) { f32x4 a = {0, 0, 0, 0};
; #pragma unroll
;                 for (int kk = 0; kk < 2; ++kk) { const bf16x8 kf = *(const bf16x8*)(KL + (16 * cb + lr) * KP + 32 * kk + 8 * lq); a = mfma16(kf, qf[kk], a); }
;                 sc[cb] = a; }
;             float mx = sink;
; #pragma unroll
;             for (int cb = 0; cb < 24; ++cb) { const int kb = B - 1 + (cb >> 3); const bool bval = (kb >= sb && kb < se);
; #pragma unroll
;                 for (int j = 0; j < 4; ++j) { const int krel = 16 * cb + 4 * lq + j - 128;
;                     int dist = qrow - krel; dist = dist < 0 ? -dist : dist;
;                     const float v = (bval && dist <= 128) ? sc[cb][j] * 0.125f - slope * (float)dist : -1e30f;
;                     sc[cb][j] = v; mx = fmaxf(mx, v); } }
;             mx = fmaxf(mx, __shfl_xor(mx, 16)); mx = fmaxf(mx, __shfl_xor(mx, 32));
	v_mfma_f32_16x16x32_bf16 v[46:49], v[156:159], v[188:191], v[236:239]
	v_mfma_f32_16x16x32_bf16 v[46:49], v[160:163], v[192:195], v[46:49]
	ds_read_b128 v[156:159], v164 offset:32256
	ds_read_b128 v[160:163], v164 offset:32320
	v_sub_f32_e32 v86, v90, v174
	v_sub_f32_e32 v87, v91, v174
	v_sub_f32_e32 v88, v92, v174
	v_sub_f32_e32 v89, v93, v174
	s_cmp_lt_i32 s47, 3
	s_cselect_b64 vcc, -1, s[10:11]
	s_cmp_lt_i32 s47, -5
	s_cselect_b64 vcc, s[6:7], vcc
	v_cndmask_b32_e32 v232, v252, v90, vcc
	v_cndmask_b32_e32 v233, v252, v91, vcc
	v_cndmask_b32_e32 v234, v252, v92, vcc
	v_cndmask_b32_e32 v235, v252, v93, vcc
	s_waitcnt lgkmcnt(2)
	v_mfma_f32_16x16x32_bf16 v[50:53], v[148:151], v[188:191], v[232:235]
	v_mfma_f32_16x16x32_bf16 v[50:53], v[152:155], v[192:195], v[50:53]
	ds_read_b128 v[148:151], v164 offset:34560
	ds_read_b128 v[152:155], v164 offset:34624
	v_sub_f32_e32 v90, v86, v174
	v_sub_f32_e32 v91, v87, v174
	v_sub_f32_e32 v92, v88, v174
	v_sub_f32_e32 v93, v89, v174
	s_cmp_lt_i32 s47, 2
	s_cselect_b64 vcc, -1, s[10:11]
	s_cmp_lt_i32 s47, -6
	s_cselect_b64 vcc, s[6:7], vcc
	v_cndmask_b32_e32 v236, v252, v86, vcc
	v_cndmask_b32_e32 v237, v252, v87, vcc
	v_cndmask_b32_e32 v238, v252, v88, vcc
	v_cndmask_b32_e32 v239, v252, v89, vcc
	s_waitcnt lgkmcnt(2)
	v_mfma_f32_16x16x32_bf16 v[54:57], v[156:159], v[188:191], v[236:239]
	v_mfma_f32_16x16x32_bf16 v[54:57], v[160:163], v[192:195], v[54:57]
	ds_read_b128 v[156:159], v164 offset:36864
	ds_read_b128 v[160:163], v164 offset:36928
	v_sub_f32_e32 v86, v90, v174
	v_sub_f32_e32 v87, v91, v174
	v_sub_f32_e32 v88, v92, v174
	v_sub_f32_e32 v89, v93, v174
	s_cmp_lt_i32 s47, 1
	s_cselect_b64 vcc, -1, s[10:11]
	s_cmp_lt_i32 s47, -7
	s_cselect_b64 vcc, s[6:7], vcc
	v_cndmask_b32_e32 v232, v252, v90, vcc
	v_cndmask_b32_e32 v233, v252, v91, vcc
	v_cndmask_b32_e32 v234, v252, v92, vcc
	v_cndmask_b32_e32 v235, v252, v93, vcc
	s_waitcnt lgkmcnt(2)
	v_mfma_f32_16x16x32_bf16 v[58:61], v[148:151], v[188:191], v[232:235]
	v_mfma_f32_16x16x32_bf16 v[58:61], v[152:155], v[192:195], v[58:61]
	ds_read_b128 v[148:151], v164 offset:39168
	ds_read_b128 v[152:155], v164 offset:39232
	v_sub_f32_e32 v90, v86, v174
	v_sub_f32_e32 v91, v87, v174
	v_sub_f32_e32 v92, v88, v174
	v_sub_f32_e32 v93, v89, v174
	v_cmp_le_i32_e32 vcc, 0, v108
	s_nop 1
	v_cndmask_b32_e32 v212, v252, v90, vcc
	v_cmp_le_i32_e32 vcc, 0, v110
	s_nop 1
	v_cndmask_b32_e32 v213, v252, v91, vcc
	v_cmp_le_i32_e32 vcc, 0, v111
	s_nop 1
	v_cndmask_b32_e32 v214, v252, v92, vcc
	v_cmp_le_i32_e32 vcc, 0, v177
	s_nop 1
	v_cndmask_b32_e32 v215, v252, v93, vcc
	s_cmp_lt_i32 s47, 0
	s_cselect_b64 vcc, -1, s[10:11]
	s_cmp_lt_i32 s47, -8
	s_cselect_b64 vcc, s[6:7], vcc
	v_cndmask_b32_e32 v236, v252, v86, vcc
	v_cndmask_b32_e32 v237, v252, v87, vcc
	v_cndmask_b32_e32 v238, v252, v88, vcc
	v_cndmask_b32_e32 v239, v252, v89, vcc
	s_waitcnt lgkmcnt(2)
	v_mfma_f32_16x16x32_bf16 v[62:65], v[156:159], v[188:191], v[236:239]
	v_mfma_f32_16x16x32_bf16 v[62:65], v[160:163], v[192:195], v[62:65]
	s_cmp_lt_i32 s47, -1
	s_cselect_b64 vcc, -1, s[10:11]
	s_cmp_lt_i32 s47, -9
	s_cselect_b64 vcc, s[6:7], vcc
	v_cndmask_b32_e32 v232, v252, v212, vcc
	v_cndmask_b32_e32 v233, v252, v213, vcc
	v_cndmask_b32_e32 v234, v252, v214, vcc
	v_cndmask_b32_e32 v235, v252, v215, vcc
	s_waitcnt lgkmcnt(0)
	v_mfma_f32_16x16x32_bf16 v[66:69], v[148:151], v[188:191], v[232:235]
	v_mfma_f32_16x16x32_bf16 v[66:69], v[152:155], v[192:195], v[66:69]
	ds_read2_b64 v[216:219], v165 offset0:4 offset1:8
	ds_read2_b64 v[220:223], v166 offset0:4 offset1:8
	ds_read2_b64 v[224:227], v167 offset0:4 offset1:8
	ds_read2_b64 v[228:231], v168 offset0:4 offset1:8
	v_max3_f32 v169, v2, v3, v4
	v_max3_f32 v172, v5, v6, v7
	v_max3_f32 v169, v8, v9, v169
	v_max3_f32 v172, v10, v11, v172
	v_max3_f32 v169, v12, v13, v169
	v_max3_f32 v172, v14, v15, v172
	v_max3_f32 v169, v16, v17, v169
	v_max3_f32 v172, v18, v19, v172
	v_max3_f32 v169, v20, v21, v169
	v_max3_f32 v172, v22, v23, v172
	v_max3_f32 v169, v24, v25, v169
	v_max3_f32 v172, v26, v27, v172
	v_max3_f32 v169, v28, v29, v169
	v_max3_f32 v172, v30, v31, v172
	v_max3_f32 v169, v32, v33, v169
	v_max3_f32 v172, v34, v35, v172
	v_max3_f32 v169, v36, v37, v169
	v_max3_f32 v172, v38, v39, v172
	v_max3_f32 v169, v40, v41, v169
	v_max3_f32 v172, v42, v43, v172
	v_max3_f32 v169, v44, v45, v169
	v_max3_f32 v172, v46, v47, v172
	v_max3_f32 v169, v48, v49, v169
	v_max3_f32 v172, v50, v51, v172
	v_max3_f32 v169, v52, v53, v169
	v_max3_f32 v172, v54, v55, v172
	v_max3_f32 v169, v56, v57, v169
	v_max3_f32 v172, v58, v59, v172
	v_max3_f32 v169, v60, v61, v169
	v_max3_f32 v172, v62, v63, v172
	v_max3_f32 v169, v64, v65, v169
	v_max3_f32 v172, v66, v67, v172
	v_max3_f32 v169, v68, v69, v169
	v_max_f32_e32 v169, v169, v172
	v_mul_f32_e32 v169, 0x3e000000, v169
	v_max_f32_e32 v169, v169, v146
	ds_bpermute_b32 v172, v1, v169
	s_waitcnt lgkmcnt(0)
	v_max_f32_e32 v169, v169, v172
	ds_bpermute_b32 v172, v114, v169
	s_waitcnt lgkmcnt(0)
; __device__ void att_phase(int wv, const Params& p, unsigned char* lds) {
;     ...
;             float sum = 0.f;
; #pragma unroll
;             for (int cb = 0; cb < 24; ++cb)
; #pragma unroll
;                 for (int j = 0; j < 4; ++j) { const float e = __expf(sc[cb][j] - mx); sc[cb][j] = e; sum += e; }
	v_max_f32_e32 v169, v169, v172
	v_mul_f32_e32 v175, 0xbfb8aa3b, v169
	v_mov_b32_e32 v170, 0
	v_mov_b32_e32 v171, 0
	v_fma_f32 v2, v2, s46, v175
	v_fma_f32 v3, v3, s46, v175
	v_fma_f32 v4, v4, s46, v175
	v_fma_f32 v5, v5, s46, v175
	v_exp_f32_e32 v2, v2
	v_exp_f32_e32 v3, v3
	v_exp_f32_e32 v4, v4
	v_exp_f32_e32 v5, v5
	v_fma_f32 v6, v6, s46, v175
	v_fma_f32 v7, v7, s46, v175
	v_fma_f32 v8, v8, s46, v175
	v_fma_f32 v9, v9, s46, v175
	v_exp_f32_e32 v6, v6
	v_exp_f32_e32 v7, v7
	v_exp_f32_e32 v8, v8
	v_exp_f32_e32 v9, v9
	v_add_f32_e32 v171, v171, v2
	v_add_f32_e32 v170, v170, v3
	v_add_f32_e32 v171, v171, v4
	v_add_f32_e32 v170, v170, v5
	v_fma_f32 v10, v10, s46, v175
	v_fma_f32 v11, v11, s46, v175
	v_fma_f32 v12, v12, s46, v175
	v_fma_f32 v13, v13, s46, v175
	v_exp_f32_e32 v10, v10
	v_exp_f32_e32 v11, v11
	v_exp_f32_e32 v12, v12
	v_exp_f32_e32 v13, v13
	v_add_f32_e32 v171, v171, v6
	v_add_f32_e32 v170, v170, v7
	v_add_f32_e32 v171, v171, v8
	v_add_f32_e32 v170, v170, v9
	v_fma_f32 v14, v14, s46, v175
	v_fma_f32 v15, v15, s46, v175
	v_fma_f32 v16, v16, s46, v175
	v_fma_f32 v17, v17, s46, v175
	v_exp_f32_e32 v14, v14
	v_exp_f32_e32 v15, v15
	v_exp_f32_e32 v16, v16
	v_exp_f32_e32 v17, v17
	v_add_f32_e32 v171, v171, v10
	v_add_f32_e32 v170, v170, v11
	v_add_f32_e32 v171, v171, v12
	v_add_f32_e32 v170, v170, v13
	v_fma_f32 v18, v18, s46, v175
	v_fma_f32 v19, v19, s46, v175
	v_fma_f32 v20, v20, s46, v175
	v_fma_f32 v21, v21, s46, v175
	v_exp_f32_e32 v18, v18
	v_exp_f32_e32 v19, v19
	v_exp_f32_e32 v20, v20
	v_exp_f32_e32 v21, v21
	v_add_f32_e32 v171, v171, v14
	v_add_f32_e32 v170, v170, v15
	v_add_f32_e32 v171, v171, v16
	v_add_f32_e32 v170, v170, v17
	v_fma_f32 v22, v22, s46, v175
	v_fma_f32 v23, v23, s46, v175
	v_fma_f32 v24, v24, s46, v175
	v_fma_f32 v25, v25, s46, v175
	v_exp_f32_e32 v22, v22
	v_exp_f32_e32 v23, v23
	v_exp_f32_e32 v24, v24
	v_exp_f32_e32 v25, v25
	v_add_f32_e32 v171, v171, v18
	v_add_f32_e32 v170, v170, v19
	v_add_f32_e32 v171, v171, v20
	v_add_f32_e32 v170, v170, v21
	v_fma_f32 v26, v26, s46, v175
	v_fma_f32 v27, v27, s46, v175
	v_fma_f32 v28, v28, s46, v175
	v_fma_f32 v29, v29, s46, v175
	v_exp_f32_e32 v26, v26
	v_exp_f32_e32 v27, v27
	v_exp_f32_e32 v28, v28
	v_exp_f32_e32 v29, v29
	v_add_f32_e32 v171, v171, v22
	v_add_f32_e32 v170, v170, v23
	v_add_f32_e32 v171, v171, v24
	v_add_f32_e32 v170, v170, v25
	v_fma_f32 v30, v30, s46, v175
	v_fma_f32 v31, v31, s46, v175
	v_fma_f32 v32, v32, s46, v175
	v_fma_f32 v33, v33, s46, v175
	v_exp_f32_e32 v30, v30
	v_exp_f32_e32 v31, v31
	v_exp_f32_e32 v32, v32
	v_exp_f32_e32 v33, v33
	v_add_f32_e32 v171, v171, v26
	v_add_f32_e32 v170, v170, v27
	v_add_f32_e32 v171, v171, v28
	v_add_f32_e32 v170, v170, v29
	v_fma_f32 v34, v34, s46, v175
	v_fma_f32 v35, v35, s46, v175
	v_fma_f32 v36, v36, s46, v175
	v_fma_f32 v37, v37, s46, v175
	v_exp_f32_e32 v34, v34
	v_exp_f32_e32 v35, v35
	v_exp_f32_e32 v36, v36
	v_exp_f32_e32 v37, v37
	v_add_f32_e32 v171, v171, v30
	v_add_f32_e32 v170, v170, v31
	v_add_f32_e32 v171, v171, v32
	v_add_f32_e32 v170, v170, v33
	v_fma_f32 v38, v38, s46, v175
	v_fma_f32 v39, v39, s46, v175
	v_fma_f32 v40, v40, s46, v175
	v_fma_f32 v41, v41, s46, v175
	v_exp_f32_e32 v38, v38
	v_exp_f32_e32 v39, v39
	v_exp_f32_e32 v40, v40
	v_exp_f32_e32 v41, v41
	v_add_f32_e32 v171, v171, v34
	v_add_f32_e32 v170, v170, v35
	v_add_f32_e32 v171, v171, v36
	v_add_f32_e32 v170, v170, v37
	v_fma_f32 v42, v42, s46, v175
	v_fma_f32 v43, v43, s46, v175
	v_fma_f32 v44, v44, s46, v175
	v_fma_f32 v45, v45, s46, v175
	v_exp_f32_e32 v42, v42
	v_exp_f32_e32 v43, v43
	v_exp_f32_e32 v44, v44
	v_exp_f32_e32 v45, v45
	v_add_f32_e32 v171, v171, v38
	v_add_f32_e32 v170, v170, v39
	v_add_f32_e32 v171, v171, v40
	v_add_f32_e32 v170, v170, v41
	v_fma_f32 v46, v46, s46, v175
	v_fma_f32 v47, v47, s46, v175
	v_fma_f32 v48, v48, s46, v175
	v_fma_f32 v49, v49, s46, v175
	v_exp_f32_e32 v46, v46
	v_exp_f32_e32 v47, v47
	v_exp_f32_e32 v48, v48
	v_exp_f32_e32 v49, v49
	v_add_f32_e32 v171, v171, v42
	v_add_f32_e32 v170, v170, v43
	v_add_f32_e32 v171, v171, v44
	v_add_f32_e32 v170, v170, v45
	v_fma_f32 v50, v50, s46, v175
	v_fma_f32 v51, v51, s46, v175
	v_fma_f32 v52, v52, s46, v175
	v_fma_f32 v53, v53, s46, v175
	v_exp_f32_e32 v50, v50
	v_exp_f32_e32 v51, v51
	v_exp_f32_e32 v52, v52
	v_exp_f32_e32 v53, v53
	v_add_f32_e32 v171, v171, v46
	v_add_f32_e32 v170, v170, v47
	v_add_f32_e32 v171, v171, v48
	v_add_f32_e32 v170, v170, v49
	v_fma_f32 v54, v54, s46, v175
	v_fma_f32 v55, v55, s46, v175
	v_fma_f32 v56, v56, s46, v175
	v_fma_f32 v57, v57, s46, v175
	v_exp_f32_e32 v54, v54
	v_exp_f32_e32 v55, v55
	v_exp_f32_e32 v56, v56
	v_exp_f32_e32 v57, v57
	v_add_f32_e32 v171, v171, v50
	v_add_f32_e32 v170, v170, v51
	v_add_f32_e32 v171, v171, v52
	v_add_f32_e32 v170, v170, v53
	v_fma_f32 v58, v58, s46, v175
	v_fma_f32 v59, v59, s46, v175
	v_fma_f32 v60, v60, s46, v175
	v_fma_f32 v61, v61, s46, v175
	v_exp_f32_e32 v58, v58
	v_exp_f32_e32 v59, v59
	v_exp_f32_e32 v60, v60
	v_exp_f32_e32 v61, v61
	v_add_f32_e32 v171, v171, v54
	v_add_f32_e32 v170, v170, v55
	v_add_f32_e32 v171, v171, v56
	v_add_f32_e32 v170, v170, v57
	v_fma_f32 v62, v62, s46, v175
	v_fma_f32 v63, v63, s46, v175
	v_fma_f32 v64, v64, s46, v175
	v_fma_f32 v65, v65, s46, v175
	v_exp_f32_e32 v62, v62
	v_exp_f32_e32 v63, v63
	v_exp_f32_e32 v64, v64
	v_exp_f32_e32 v65, v65
	v_add_f32_e32 v171, v171, v58
	v_add_f32_e32 v170, v170, v59
	v_add_f32_e32 v171, v171, v60
	v_add_f32_e32 v170, v170, v61
	v_fma_f32 v66, v66, s46, v175
	v_fma_f32 v67, v67, s46, v175
	v_fma_f32 v68, v68, s46, v175
	v_fma_f32 v69, v69, s46, v175
	v_exp_f32_e32 v66, v66
	v_exp_f32_e32 v67, v67
; __device__ __forceinline__ unsigned cvt_pk_bf16_asm(float lo, float hi) { unsigned r; asm volatile("v_cvt_pk_bf16_f32 %0, %1, %2" : "=v"(r) : "v"(lo), "v"(hi)); return r; }
; __device__ __forceinline__ f32x4 mfma16(bf16x8 a, bf16x8 b, f32x4 c) { return __builtin_amdgcn_mfma_f32_16x16x32_bf16(a, b, c, 0, 0, 0); }
; __device__ void att_phase(int wv, const Params& p, unsigned char* lds) {
;     ...
; #pragma unroll
;             for (int cb = 0; cb < 24; ++cb)
; #pragma unroll
;                 for (int j = 0; j < 4; ++j) { const float e = __expf(sc[cb][j] - mx); sc[cb][j] = e; sum += e; }
;             sum += __shfl_xor(sum, 16); sum += __shfl_xor(sum, 32);
;             sum += __expf(sink - mx);
;             const float inv = 1.0f / sum;
;             f32x4 oa[4];
; #pragma unroll
;             for (int db = 0; db < 4; ++db) oa[db] = (f32x4){0, 0, 0, 0};
; #pragma unroll
;             for (int ks = 0; ks < 12; ++ks) {
;                 union { bf16x8 v; unsigned u[4]; } pf;
;                 pf.u[0] = cvt_pk_bf16_asm(sc[2 * ks][0], sc[2 * ks][1]); pf.u[1] = cvt_pk_bf16_asm(sc[2 * ks][2], sc[2 * ks][3]);
;                 pf.u[2] = cvt_pk_bf16_asm(sc[2 * ks + 1][0], sc[2 * ks + 1][1]); pf.u[3] = cvt_pk_bf16_asm(sc[2 * ks + 1][2], sc[2 * ks + 1][3]);
; #pragma unroll
;                 for (int db = 0; db < 4; ++db) {
;                     union { bf16x8 v; u32x2 h2[2]; } vf;
;                     const bf16_t* vp = VTL + (16 * db + lr) * VP + 32 * ks + 4 * lq;
;                     vf.h2[0] = *(const u32x2*)vp; vf.h2[1] = *(const u32x2*)(vp + 16);
;                     oa[db] = mfma16(vf.v, pf.v, oa[db]); } }
	v_exp_f32_e32 v68, v68
	v_exp_f32_e32 v69, v69
	v_add_f32_e32 v171, v171, v62
	v_add_f32_e32 v170, v170, v63
	v_add_f32_e32 v171, v171, v64
	v_add_f32_e32 v170, v170, v65
	v_add_f32_e32 v171, v171, v66
	v_add_f32_e32 v170, v170, v67
	v_add_f32_e32 v171, v171, v68
	v_add_f32_e32 v170, v170, v69
	v_add_f32_e32 v170, v170, v171
	v_cvt_pk_bf16_f32 v2, v2, v3
	v_cvt_pk_bf16_f32 v3, v4, v5
	v_cvt_pk_bf16_f32 v4, v6, v7
	v_cvt_pk_bf16_f32 v5, v8, v9
	v_cvt_pk_bf16_f32 v10, v10, v11
	v_cvt_pk_bf16_f32 v11, v12, v13
	v_cvt_pk_bf16_f32 v12, v14, v15
	v_cvt_pk_bf16_f32 v13, v16, v17
	v_cvt_pk_bf16_f32 v18, v18, v19
	v_cvt_pk_bf16_f32 v19, v20, v21
	v_cvt_pk_bf16_f32 v20, v22, v23
	v_cvt_pk_bf16_f32 v21, v24, v25
	v_cvt_pk_bf16_f32 v26, v26, v27
	v_cvt_pk_bf16_f32 v27, v28, v29
	v_cvt_pk_bf16_f32 v28, v30, v31
	v_cvt_pk_bf16_f32 v29, v32, v33
	v_cvt_pk_bf16_f32 v34, v34, v35
	v_cvt_pk_bf16_f32 v35, v36, v37
	v_cvt_pk_bf16_f32 v36, v38, v39
	v_cvt_pk_bf16_f32 v37, v40, v41
	v_cvt_pk_bf16_f32 v42, v42, v43
	v_cvt_pk_bf16_f32 v43, v44, v45
	v_cvt_pk_bf16_f32 v44, v46, v47
	v_cvt_pk_bf16_f32 v45, v48, v49
	v_cvt_pk_bf16_f32 v50, v50, v51
	v_cvt_pk_bf16_f32 v51, v52, v53
	v_cvt_pk_bf16_f32 v52, v54, v55
	v_cvt_pk_bf16_f32 v53, v56, v57
	v_cvt_pk_bf16_f32 v58, v58, v59
	v_cvt_pk_bf16_f32 v59, v60, v61
	v_cvt_pk_bf16_f32 v60, v62, v63
	v_cvt_pk_bf16_f32 v61, v64, v65
	v_cvt_pk_bf16_f32 v66, v66, v67
	v_cvt_pk_bf16_f32 v67, v68, v69
	v_mov_b32_e32 v68, 0
	v_mov_b32_e32 v69, 0
	ds_bpermute_b32 v172, v1, v170
	v_sub_f32_e32 v173, v146, v169
	v_mul_f32_e32 v173, 0x3fb8aa3b, v173
	v_exp_f32_e32 v173, v173
	s_waitcnt lgkmcnt(0)
	v_add_f32_e32 v170, v170, v172
	ds_bpermute_b32 v172, v114, v170
	ds_read2_b64 v[232:235], v165 offset0:12 offset1:16
	ds_read2_b64 v[236:239], v166 offset0:12 offset1:16
	ds_read2_b64 v[240:243], v167 offset0:12 offset1:16
	ds_read2_b64 v[244:247], v168 offset0:12 offset1:16
	s_waitcnt lgkmcnt(4)
	v_mfma_f32_16x16x32_bf16 v[70:73], v[216:219], v[2:5], 0
	v_mfma_f32_16x16x32_bf16 v[74:77], v[220:223], v[2:5], 0
	v_mfma_f32_16x16x32_bf16 v[78:81], v[224:227], v[2:5], 0
	v_mfma_f32_16x16x32_bf16 v[82:85], v[228:231], v[2:5], 0
	v_add_f32_e32 v170, v170, v172
	v_add_f32_e32 v170, v170, v173
	v_rcp_f32_e32 v147, v170
	s_nop 0
	v_fma_f32 v179, -v170, v147, 1.0
	v_fmac_f32_e32 v147, v179, v147
	ds_read2_b64 v[216:219], v165 offset0:20 offset1:24
	ds_read2_b64 v[220:223], v166 offset0:20 offset1:24
	ds_read2_b64 v[224:227], v167 offset0:20 offset1:24
	ds_read2_b64 v[228:231], v168 offset0:20 offset1:24
	s_waitcnt lgkmcnt(4)
	v_mfma_f32_16x16x32_bf16 v[70:73], v[232:235], v[10:13], v[70:73]
	v_mfma_f32_16x16x32_bf16 v[74:77], v[236:239], v[10:13], v[74:77]
	v_mfma_f32_16x16x32_bf16 v[78:81], v[240:243], v[10:13], v[78:81]
	v_mfma_f32_16x16x32_bf16 v[82:85], v[244:247], v[10:13], v[82:85]
	ds_read2_b64 v[232:235], v165 offset0:28 offset1:32
	ds_read2_b64 v[236:239], v166 offset0:28 offset1:32
	ds_read2_b64 v[240:243], v167 offset0:28 offset1:32
	ds_read2_b64 v[244:247], v168 offset0:28 offset1:32
	s_waitcnt lgkmcnt(4)
	v_mfma_f32_16x16x32_bf16 v[70:73], v[216:219], v[18:21], v[70:73]
	v_mfma_f32_16x16x32_bf16 v[74:77], v[220:223], v[18:21], v[74:77]
	v_mfma_f32_16x16x32_bf16 v[78:81], v[224:227], v[18:21], v[78:81]
	v_mfma_f32_16x16x32_bf16 v[82:85], v[228:231], v[18:21], v[82:85]
	ds_read2_b64 v[216:219], v165 offset0:36 offset1:40
	ds_read2_b64 v[220:223], v166 offset0:36 offset1:40
	ds_read2_b64 v[224:227], v167 offset0:36 offset1:40
	ds_read2_b64 v[228:231], v168 offset0:36 offset1:40
	s_waitcnt lgkmcnt(4)
	v_mfma_f32_16x16x32_bf16 v[70:73], v[232:235], v[26:29], v[70:73]
	v_mfma_f32_16x16x32_bf16 v[74:77], v[236:239], v[26:29], v[74:77]
	v_mfma_f32_16x16x32_bf16 v[78:81], v[240:243], v[26:29], v[78:81]
	v_mfma_f32_16x16x32_bf16 v[82:85], v[244:247], v[26:29], v[82:85]
	ds_read2_b64 v[232:235], v165 offset0:44 offset1:48
	ds_read2_b64 v[236:239], v166 offset0:44 offset1:48
	ds_read2_b64 v[240:243], v167 offset0:44 offset1:48
	ds_read2_b64 v[244:247], v168 offset0:44 offset1:48
	s_waitcnt lgkmcnt(4)
	v_mfma_f32_16x16x32_bf16 v[70:73], v[216:219], v[34:37], v[70:73]
	v_mfma_f32_16x16x32_bf16 v[74:77], v[220:223], v[34:37], v[74:77]
	v_mfma_f32_16x16x32_bf16 v[78:81], v[224:227], v[34:37], v[78:81]
	v_mfma_f32_16x16x32_bf16 v[82:85], v[228:231], v[34:37], v[82:85]
	ds_read2_b64 v[216:219], v165 offset0:52 offset1:56
	ds_read2_b64 v[220:223], v166 offset0:52 offset1:56
	ds_read2_b64 v[224:227], v167 offset0:52 offset1:56
	ds_read2_b64 v[228:231], v168 offset0:52 offset1:56
	s_waitcnt lgkmcnt(4)
	v_mfma_f32_16x16x32_bf16 v[70:73], v[232:235], v[42:45], v[70:73]
	v_mfma_f32_16x16x32_bf16 v[74:77], v[236:239], v[42:45], v[74:77]
	v_mfma_f32_16x16x32_bf16 v[78:81], v[240:243], v[42:45], v[78:81]
	v_mfma_f32_16x16x32_bf16 v[82:85], v[244:247], v[42:45], v[82:85]
	ds_read2_b64 v[232:235], v165 offset0:60 offset1:64
	ds_read2_b64 v[236:239], v166 offset0:60 offset1:64
	ds_read2_b64 v[240:243], v167 offset0:60 offset1:64
	ds_read2_b64 v[244:247], v168 offset0:60 offset1:64
	s_waitcnt lgkmcnt(4)
	v_mfma_f32_16x16x32_bf16 v[70:73], v[216:219], v[50:53], v[70:73]
	v_mfma_f32_16x16x32_bf16 v[74:77], v[220:223], v[50:53], v[74:77]
	v_mfma_f32_16x16x32_bf16 v[78:81], v[224:227], v[50:53], v[78:81]
	v_mfma_f32_16x16x32_bf16 v[82:85], v[228:231], v[50:53], v[82:85]
	ds_read2_b64 v[216:219], v165 offset0:68 offset1:68
	ds_read2_b64 v[220:223], v166 offset0:68 offset1:68
	ds_read2_b64 v[224:227], v167 offset0:68 offset1:68
	ds_read2_b64 v[228:231], v168 offset0:68 offset1:68
	s_waitcnt lgkmcnt(4)
; __device__ __forceinline__ unsigned cvt_pk_bf16_asm(float lo, float hi) { unsigned r; asm volatile("v_cvt_pk_bf16_f32 %0, %1, %2" : "=v"(r) : "v"(lo), "v"(hi)); return r; }
; __device__ __forceinline__ f32x4 mfma16(bf16x8 a, bf16x8 b, f32x4 c) { return __builtin_amdgcn_mfma_f32_16x16x32_bf16(a, b, c, 0, 0, 0); }
; __device__ void att_phase(int wv, const Params& p, unsigned char* lds) {
;     ...
;             f32x4 sc[24];
; #pragma unroll
;             for (int cb = 0; cb < 24; ++cb) { f32x4 a = {0, 0, 0, 0};
; #pragma unroll
;                 for (int kk = 0; kk < 2; ++kk) { const bf16x8 kf = *(const bf16x8*)(KL + (16 * cb + lr) * KP + 32 * kk + 8 * lq); a = mfma16(kf, qf[kk], a); }
;                 sc[cb] = a; }
;     ...
;             for (int ks = 0; ks < 12; ++ks) {
;                 union { bf16x8 v; unsigned u[4]; } pf;
;                 pf.u[0] = cvt_pk_bf16_asm(sc[2 * ks][0], sc[2 * ks][1]); pf.u[1] = cvt_pk_bf16_asm(sc[2 * ks][2], sc[2 * ks][3]);
;                 pf.u[2] = cvt_pk_bf16_asm(sc[2 * ks + 1][0], sc[2 * ks + 1][1]); pf.u[3] = cvt_pk_bf16_asm(sc[2 * ks + 1][2], sc[2 * ks + 1][3]);
; #pragma unroll
;                 for (int db = 0; db < 4; ++db) {
;                     union { bf16x8 v; u32x2 h2[2]; } vf;
;                     const bf16_t* vp = VTL + (16 * db + lr) * VP + 32 * ks + 4 * lq;
;                     vf.h2[0] = *(const u32x2*)vp; vf.h2[1] = *(const u32x2*)(vp + 16);
;                     oa[db] = mfma16(vf.v, pf.v, oa[db]); } }
; #pragma unroll
;             for (int db = 0; db < 4; ++db) { const f32x4 o = oa[db] * inv; u32x2 wv; wv.x = cvt_pk_bf16_asm(o[0], o[1]); wv.y = cvt_pk_bf16_asm(o[2], o[3]);
;                 *(u32x2*)(qkv + tokq * 1536 + 64 * h + 16 * db + 4 * lq) = wv; }
	v_mfma_f32_16x16x32_bf16 v[70:73], v[232:235], v[58:61], v[70:73]
	v_mfma_f32_16x16x32_bf16 v[74:77], v[236:239], v[58:61], v[74:77]
	v_mfma_f32_16x16x32_bf16 v[78:81], v[240:243], v[58:61], v[78:81]
	v_mfma_f32_16x16x32_bf16 v[82:85], v[244:247], v[58:61], v[82:85]
	s_waitcnt lgkmcnt(0)
	v_mfma_f32_16x16x32_bf16 v[70:73], v[216:219], v[66:69], v[70:73]
	v_mfma_f32_16x16x32_bf16 v[74:77], v[220:223], v[66:69], v[74:77]
	v_mfma_f32_16x16x32_bf16 v[78:81], v[224:227], v[66:69], v[78:81]
	v_mfma_f32_16x16x32_bf16 v[82:85], v[228:231], v[66:69], v[82:85]
	s_nop 7
	s_nop 1
	v_mul_f32_e32 v70, v70, v147
	v_mul_f32_e32 v71, v71, v147
	v_mul_f32_e32 v72, v72, v147
	v_mul_f32_e32 v73, v73, v147
	v_mul_f32_e32 v74, v74, v147
	v_mul_f32_e32 v75, v75, v147
	v_mul_f32_e32 v76, v76, v147
	v_mul_f32_e32 v77, v77, v147
	v_mul_f32_e32 v78, v78, v147
	v_mul_f32_e32 v79, v79, v147
	v_mul_f32_e32 v80, v80, v147
	v_mul_f32_e32 v81, v81, v147
	v_mul_f32_e32 v82, v82, v147
	v_mul_f32_e32 v83, v83, v147
	v_mul_f32_e32 v84, v84, v147
	v_mul_f32_e32 v85, v85, v147
	v_cvt_pk_bf16_f32 v70, v70, v71
	v_cvt_pk_bf16_f32 v71, v72, v73
	v_cvt_pk_bf16_f32 v74, v74, v75
	v_cvt_pk_bf16_f32 v75, v76, v77
	v_cvt_pk_bf16_f32 v78, v78, v79
	v_cvt_pk_bf16_f32 v79, v80, v81
	v_cvt_pk_bf16_f32 v82, v82, v83
	v_cvt_pk_bf16_f32 v83, v84, v85
	global_store_dwordx2 v[248:249], v[70:71], off offset:-64
	global_store_dwordx2 v[248:249], v[74:75], off offset:-32
	global_store_dwordx2 v[248:249], v[78:79], off
	global_store_dwordx2 v[248:249], v[82:83], off offset:32
	v_lshl_add_u64 v[248:249], v[248:249], 0, s[48:49]
	v_sub_f32_e32 v86, v94, v176
	v_sub_f32_e32 v87, v95, v176
	v_sub_f32_e32 v88, v96, v176
	v_sub_f32_e32 v89, v97, v176
	v_cmp_ge_i32_e32 vcc, 0, v108
	s_nop 1
	v_cndmask_b32_e32 v212, v252, v86, vcc
	v_cmp_ge_i32_e32 vcc, 0, v110
	s_nop 1
	v_cndmask_b32_e32 v213, v252, v87, vcc
	v_cmp_ge_i32_e32 vcc, 0, v111
	s_nop 1
	v_cndmask_b32_e32 v214, v252, v88, vcc
	v_cmp_ge_i32_e32 vcc, 0, v177
	s_nop 1
	v_cndmask_b32_e32 v215, v252, v89, vcc
	ds_read_b128 v[148:151], v164 offset:4608
	ds_read_b128 v[152:155], v164 offset:4672
	ds_read_b128 v[156:159], v164 offset:6912
	ds_read_b128 v[160:163], v164 offset:6976
	v_add_f32_e32 v90, v86, v174
	v_add_f32_e32 v91, v87, v174
	v_add_f32_e32 v92, v88, v174
	v_add_f32_e32 v93, v89, v174
	s_cmp_lt_i32 s47, 14
	s_cselect_b64 vcc, -1, s[10:11]
	s_cmp_lt_i32 s47, 6
	s_cselect_b64 vcc, s[6:7], vcc
	v_cndmask_b32_e32 v232, v252, v212, vcc
	v_cndmask_b32_e32 v233, v252, v213, vcc
	v_cndmask_b32_e32 v234, v252, v214, vcc
	v_cndmask_b32_e32 v235, v252, v215, vcc
	s_waitcnt lgkmcnt(2)
	v_mfma_f32_16x16x32_bf16 v[2:5], v[148:151], v[196:199], v[232:235]
	v_mfma_f32_16x16x32_bf16 v[2:5], v[152:155], v[200:203], v[2:5]
	ds_read_b128 v[148:151], v164 offset:9216
	ds_read_b128 v[152:155], v164 offset:9280
	v_add_f32_e32 v86, v90, v174
	v_add_f32_e32 v87, v91, v174
	v_add_f32_e32 v88, v92, v174
	v_add_f32_e32 v89, v93, v174
	s_cmp_lt_i32 s47, 13
	s_cselect_b64 vcc, -1, s[10:11]
	s_cmp_lt_i32 s47, 5
	s_cselect_b64 vcc, s[6:7], vcc
	v_cndmask_b32_e32 v236, v252, v90, vcc
	v_cndmask_b32_e32 v237, v252, v91, vcc
	v_cndmask_b32_e32 v238, v252, v92, vcc
	v_cndmask_b32_e32 v239, v252, v93, vcc
	s_waitcnt lgkmcnt(2)
	v_mfma_f32_16x16x32_bf16 v[6:9], v[156:159], v[196:199], v[236:239]
	v_mfma_f32_16x16x32_bf16 v[6:9], v[160:163], v[200:203], v[6:9]
	ds_read_b128 v[156:159], v164 offset:11520
	ds_read_b128 v[160:163], v164 offset:11584
	v_add_f32_e32 v90, v86, v174
	v_add_f32_e32 v91, v87, v174
	v_add_f32_e32 v92, v88, v174
	v_add_f32_e32 v93, v89, v174
	s_cmp_lt_i32 s47, 12
	s_cselect_b64 vcc, -1, s[10:11]
	s_cmp_lt_i32 s47, 4
	s_cselect_b64 vcc, s[6:7], vcc
	v_cndmask_b32_e32 v232, v252, v86, vcc
	v_cndmask_b32_e32 v233, v252, v87, vcc
	v_cndmask_b32_e32 v234, v252, v88, vcc
	v_cndmask_b32_e32 v235, v252, v89, vcc
	s_waitcnt lgkmcnt(2)
	v_mfma_f32_16x16x32_bf16 v[10:13], v[148:151], v[196:199], v[232:235]
	v_mfma_f32_16x16x32_bf16 v[10:13], v[152:155], v[200:203], v[10:13]
	ds_read_b128 v[148:151], v164 offset:13824
	ds_read_b128 v[152:155], v164 offset:13888
	v_add_f32_e32 v86, v90, v174
	v_add_f32_e32 v87, v91, v174
	v_add_f32_e32 v88, v92, v174
	v_add_f32_e32 v89, v93, v174
	s_cmp_lt_i32 s47, 11
	s_cselect_b64 vcc, -1, s[10:11]
	s_cmp_lt_i32 s47, 3
	s_cselect_b64 vcc, s[6:7], vcc
	v_cndmask_b32_e32 v236, v252, v90, vcc
	v_cndmask_b32_e32 v237, v252, v91, vcc
	v_cndmask_b32_e32 v238, v252, v92, vcc
	v_cndmask_b32_e32 v239, v252, v93, vcc
	s_waitcnt lgkmcnt(2)
	v_mfma_f32_16x16x32_bf16 v[14:17], v[156:159], v[196:199], v[236:239]
	v_mfma_f32_16x16x32_bf16 v[14:17], v[160:163], v[200:203], v[14:17]
	ds_read_b128 v[156:159], v164 offset:16128
	ds_read_b128 v[160:163], v164 offset:16192
	v_add_f32_e32 v90, v86, v174
	v_add_f32_e32 v91, v87, v174
	v_add_f32_e32 v92, v88, v174
	v_add_f32_e32 v93, v89, v174
	s_cmp_lt_i32 s47, 10
	s_cselect_b64 vcc, -1, s[10:11]
	s_cmp_lt_i32 s47, 2
	s_cselect_b64 vcc, s[6:7], vcc
	v_cndmask_b32_e32 v232, v252, v86, vcc
	v_cndmask_b32_e32 v233, v252, v87, vcc
	v_cndmask_b32_e32 v234, v252, v88, vcc
	v_cndmask_b32_e32 v235, v252, v89, vcc
	s_waitcnt lgkmcnt(2)
	v_mfma_f32_16x16x32_bf16 v[18:21], v[148:151], v[196:199], v[232:235]
	v_mfma_f32_16x16x32_bf16 v[18:21], v[152:155], v[200:203], v[18:21]
	ds_read_b128 v[148:151], v164 offset:18432
	ds_read_b128 v[152:155], v164 offset:18496
	v_add_f32_e32 v86, v90, v174
	v_add_f32_e32 v87, v91, v174
	v_add_f32_e32 v88, v92, v174
	v_add_f32_e32 v89, v93, v174
	s_cmp_lt_i32 s47, 9
	s_cselect_b64 vcc, -1, s[10:11]
	s_cmp_lt_i32 s47, 1
	s_cselect_b64 vcc, s[6:7], vcc
	v_cndmask_b32_e32 v236, v252, v90, vcc
	v_cndmask_b32_e32 v237, v252, v91, vcc
	v_cndmask_b32_e32 v238, v252, v92, vcc
	v_cndmask_b32_e32 v239, v252, v93, vcc
	s_waitcnt lgkmcnt(2)
; __device__ __forceinline__ f32x4 mfma16(bf16x8 a, bf16x8 b, f32x4 c) { return __builtin_amdgcn_mfma_f32_16x16x32_bf16(a, b, c, 0, 0, 0); }
; __device__ void att_phase(int wv, const Params& p, unsigned char* lds) {
;     ...
;             f32x4 sc[24];
; #pragma unroll
;             for (int cb = 0; cb < 24; ++cb) { f32x4 a = {0, 0, 0, 0};
; #pragma unroll
;                 for (int kk = 0; kk < 2; ++kk) { const bf16x8 kf = *(const bf16x8*)(KL + (16 * cb + lr) * KP + 32 * kk + 8 * lq); a = mfma16(kf, qf[kk], a); }
;                 sc[cb] = a; }
;             float mx = sink;
; #pragma unroll
;             for (int cb = 0; cb < 24; ++cb) { const int kb = B - 1 + (cb >> 3); const bool bval = (kb >= sb && kb < se);
; #pragma unroll
;                 for (int j = 0; j < 4; ++j) { const int krel = 16 * cb + 4 * lq + j - 128;
;                     int dist = qrow - krel; dist = dist < 0 ? -dist : dist;
;                     const float v = (bval && dist <= 128) ? sc[cb][j] * 0.125f - slope * (float)dist : -1e30f;
;                     sc[cb][j] = v; mx = fmaxf(mx, v); } }
	v_mfma_f32_16x16x32_bf16 v[22:25], v[156:159], v[196:199], v[236:239]
	v_mfma_f32_16x16x32_bf16 v[22:25], v[160:163], v[200:203], v[22:25]
	ds_read_b128 v[156:159], v164 offset:20736
	ds_read_b128 v[160:163], v164 offset:20800
	v_add_f32_e32 v90, v86, v174
	v_add_f32_e32 v91, v87, v174
	v_add_f32_e32 v92, v88, v174
	v_add_f32_e32 v93, v89, v174
	s_waitcnt lgkmcnt(2)
	v_mfma_f32_16x16x32_bf16 v[26:29], v[148:151], v[196:199], v[86:89]
	v_mfma_f32_16x16x32_bf16 v[26:29], v[152:155], v[200:203], v[26:29]
	ds_read_b128 v[148:151], v164 offset:23040
	ds_read_b128 v[152:155], v164 offset:23104
	s_waitcnt lgkmcnt(2)
	v_mfma_f32_16x16x32_bf16 v[30:33], v[156:159], v[196:199], v[90:93]
	v_mfma_f32_16x16x32_bf16 v[30:33], v[160:163], v[200:203], v[30:33]
	ds_read_b128 v[156:159], v164 offset:25344
	ds_read_b128 v[160:163], v164 offset:25408
	v_sub_f32_e64 v86, -v94, v174
	v_sub_f32_e64 v87, -v95, v174
	v_sub_f32_e64 v88, -v96, v174
	v_sub_f32_e64 v89, -v97, v174
	s_waitcnt lgkmcnt(2)
	v_mfma_f32_16x16x32_bf16 v[34:37], v[148:151], v[196:199], v[98:101]
	v_mfma_f32_16x16x32_bf16 v[34:37], v[152:155], v[200:203], v[34:37]
	ds_read_b128 v[148:151], v164 offset:27648
	ds_read_b128 v[152:155], v164 offset:27712
	v_sub_f32_e32 v90, v86, v174
	v_sub_f32_e32 v91, v87, v174
	v_sub_f32_e32 v92, v88, v174
	v_sub_f32_e32 v93, v89, v174
	s_waitcnt lgkmcnt(2)
	v_mfma_f32_16x16x32_bf16 v[38:41], v[156:159], v[196:199], v[86:89]
	v_mfma_f32_16x16x32_bf16 v[38:41], v[160:163], v[200:203], v[38:41]
	ds_read_b128 v[156:159], v164 offset:29952
	ds_read_b128 v[160:163], v164 offset:30016
	v_sub_f32_e32 v86, v90, v174
	v_sub_f32_e32 v87, v91, v174
	v_sub_f32_e32 v88, v92, v174
	v_sub_f32_e32 v89, v93, v174
	s_cmp_lt_i32 s47, 4
	s_cselect_b64 vcc, -1, s[10:11]
	s_cmp_lt_i32 s47, -4
	s_cselect_b64 vcc, s[6:7], vcc
	v_cndmask_b32_e32 v232, v252, v90, vcc
	v_cndmask_b32_e32 v233, v252, v91, vcc
	v_cndmask_b32_e32 v234, v252, v92, vcc
	v_cndmask_b32_e32 v235, v252, v93, vcc
	s_waitcnt lgkmcnt(2)
	v_mfma_f32_16x16x32_bf16 v[42:45], v[148:151], v[196:199], v[232:235]
	v_mfma_f32_16x16x32_bf16 v[42:45], v[152:155], v[200:203], v[42:45]
	ds_read_b128 v[148:151], v164 offset:32256
	ds_read_b128 v[152:155], v164 offset:32320
	v_sub_f32_e32 v90, v86, v174
	v_sub_f32_e32 v91, v87, v174
	v_sub_f32_e32 v92, v88, v174
	v_sub_f32_e32 v93, v89, v174
	s_cmp_lt_i32 s47, 3
	s_cselect_b64 vcc, -1, s[10:11]
	s_cmp_lt_i32 s47, -5
	s_cselect_b64 vcc, s[6:7], vcc
	v_cndmask_b32_e32 v236, v252, v86, vcc
	v_cndmask_b32_e32 v237, v252, v87, vcc
	v_cndmask_b32_e32 v238, v252, v88, vcc
	v_cndmask_b32_e32 v239, v252, v89, vcc
	s_waitcnt lgkmcnt(2)
	v_mfma_f32_16x16x32_bf16 v[46:49], v[156:159], v[196:199], v[236:239]
	v_mfma_f32_16x16x32_bf16 v[46:49], v[160:163], v[200:203], v[46:49]
	ds_read_b128 v[156:159], v164 offset:34560
	ds_read_b128 v[160:163], v164 offset:34624
	v_sub_f32_e32 v86, v90, v174
	v_sub_f32_e32 v87, v91, v174
	v_sub_f32_e32 v88, v92, v174
	v_sub_f32_e32 v89, v93, v174
	s_cmp_lt_i32 s47, 2
	s_cselect_b64 vcc, -1, s[10:11]
	s_cmp_lt_i32 s47, -6
	s_cselect_b64 vcc, s[6:7], vcc
	v_cndmask_b32_e32 v232, v252, v90, vcc
	v_cndmask_b32_e32 v233, v252, v91, vcc
	v_cndmask_b32_e32 v234, v252, v92, vcc
	v_cndmask_b32_e32 v235, v252, v93, vcc
	s_waitcnt lgkmcnt(2)
	v_mfma_f32_16x16x32_bf16 v[50:53], v[148:151], v[196:199], v[232:235]
	v_mfma_f32_16x16x32_bf16 v[50:53], v[152:155], v[200:203], v[50:53]
	ds_read_b128 v[148:151], v164 offset:36864
	ds_read_b128 v[152:155], v164 offset:36928
	v_sub_f32_e32 v90, v86, v174
	v_sub_f32_e32 v91, v87, v174
	v_sub_f32_e32 v92, v88, v174
	v_sub_f32_e32 v93, v89, v174
	s_cmp_lt_i32 s47, 1
	s_cselect_b64 vcc, -1, s[10:11]
	s_cmp_lt_i32 s47, -7
	s_cselect_b64 vcc, s[6:7], vcc
	v_cndmask_b32_e32 v236, v252, v86, vcc
	v_cndmask_b32_e32 v237, v252, v87, vcc
	v_cndmask_b32_e32 v238, v252, v88, vcc
	v_cndmask_b32_e32 v239, v252, v89, vcc
	s_waitcnt lgkmcnt(2)
	v_mfma_f32_16x16x32_bf16 v[54:57], v[156:159], v[196:199], v[236:239]
	v_mfma_f32_16x16x32_bf16 v[54:57], v[160:163], v[200:203], v[54:57]
	ds_read_b128 v[156:159], v164 offset:39168
	ds_read_b128 v[160:163], v164 offset:39232
	v_sub_f32_e32 v86, v90, v174
	v_sub_f32_e32 v87, v91, v174
	v_sub_f32_e32 v88, v92, v174
	v_sub_f32_e32 v89, v93, v174
	s_cmp_lt_i32 s47, 0
	s_cselect_b64 vcc, -1, s[10:11]
	s_cmp_lt_i32 s47, -8
	s_cselect_b64 vcc, s[6:7], vcc
	v_cndmask_b32_e32 v232, v252, v90, vcc
	v_cndmask_b32_e32 v233, v252, v91, vcc
	v_cndmask_b32_e32 v234, v252, v92, vcc
	v_cndmask_b32_e32 v235, v252, v93, vcc
	s_waitcnt lgkmcnt(2)
	v_mfma_f32_16x16x32_bf16 v[58:61], v[148:151], v[196:199], v[232:235]
	v_mfma_f32_16x16x32_bf16 v[58:61], v[152:155], v[200:203], v[58:61]
	ds_read_b128 v[148:151], v164 offset:41472
	ds_read_b128 v[152:155], v164 offset:41536
	v_sub_f32_e32 v90, v86, v174
	v_sub_f32_e32 v91, v87, v174
	v_sub_f32_e32 v92, v88, v174
	v_sub_f32_e32 v93, v89, v174
	v_cmp_le_i32_e32 vcc, 0, v108
	s_nop 1
	v_cndmask_b32_e32 v212, v252, v90, vcc
	v_cmp_le_i32_e32 vcc, 0, v110
	s_nop 1
	v_cndmask_b32_e32 v213, v252, v91, vcc
	v_cmp_le_i32_e32 vcc, 0, v111
	s_nop 1
	v_cndmask_b32_e32 v214, v252, v92, vcc
	v_cmp_le_i32_e32 vcc, 0, v177
	s_nop 1
	v_cndmask_b32_e32 v215, v252, v93, vcc
	s_cmp_lt_i32 s47, -1
	s_cselect_b64 vcc, -1, s[10:11]
	s_cmp_lt_i32 s47, -9
	s_cselect_b64 vcc, s[6:7], vcc
	v_cndmask_b32_e32 v236, v252, v86, vcc
	v_cndmask_b32_e32 v237, v252, v87, vcc
	v_cndmask_b32_e32 v238, v252, v88, vcc
	v_cndmask_b32_e32 v239, v252, v89, vcc
	s_waitcnt lgkmcnt(2)
; __device__ __forceinline__ f32x4 mfma16(bf16x8 a, bf16x8 b, f32x4 c) { return __builtin_amdgcn_mfma_f32_16x16x32_bf16(a, b, c, 0, 0, 0); }
; __device__ void att_phase(int wv, const Params& p, unsigned char* lds) {
;     ...
;             f32x4 sc[24];
; #pragma unroll
;             for (int cb = 0; cb < 24; ++cb) { f32x4 a = {0, 0, 0, 0};
; #pragma unroll
;                 for (int kk = 0; kk < 2; ++kk) { const bf16x8 kf = *(const bf16x8*)(KL + (16 * cb + lr) * KP + 32 * kk + 8 * lq); a = mfma16(kf, qf[kk], a); }
;                 sc[cb] = a; }
;             float mx = sink;
; #pragma unroll
;             for (int cb = 0; cb < 24; ++cb) { const int kb = B - 1 + (cb >> 3); const bool bval = (kb >= sb && kb < se);
; #pragma unroll
;                 for (int j = 0; j < 4; ++j) { const int krel = 16 * cb + 4 * lq + j - 128;
;                     int dist = qrow - krel; dist = dist < 0 ? -dist : dist;
;                     const float v = (bval && dist <= 128) ? sc[cb][j] * 0.125f - slope * (float)dist : -1e30f;
;                     sc[cb][j] = v; mx = fmaxf(mx, v); } }
;             mx = fmaxf(mx, __shfl_xor(mx, 16)); mx = fmaxf(mx, __shfl_xor(mx, 32));
;             float sum = 0.f;
; #pragma unroll
;             for (int cb = 0; cb < 24; ++cb)
; #pragma unroll
;                 for (int j = 0; j < 4; ++j) { const float e = __expf(sc[cb][j] - mx); sc[cb][j] = e; sum += e; }
	v_mfma_f32_16x16x32_bf16 v[62:65], v[156:159], v[196:199], v[236:239]
	v_mfma_f32_16x16x32_bf16 v[62:65], v[160:163], v[200:203], v[62:65]
	s_cmp_lt_i32 s47, -2
	s_cselect_b64 vcc, -1, s[10:11]
	s_cmp_lt_i32 s47, -10
	s_cselect_b64 vcc, s[6:7], vcc
	v_cndmask_b32_e32 v232, v252, v212, vcc
	v_cndmask_b32_e32 v233, v252, v213, vcc
	v_cndmask_b32_e32 v234, v252, v214, vcc
	v_cndmask_b32_e32 v235, v252, v215, vcc
	s_waitcnt lgkmcnt(0)
	v_mfma_f32_16x16x32_bf16 v[66:69], v[148:151], v[196:199], v[232:235]
	v_mfma_f32_16x16x32_bf16 v[66:69], v[152:155], v[200:203], v[66:69]
	ds_read2_b64 v[216:219], v165 offset0:8 offset1:12
	ds_read2_b64 v[220:223], v166 offset0:8 offset1:12
	ds_read2_b64 v[224:227], v167 offset0:8 offset1:12
	ds_read2_b64 v[228:231], v168 offset0:8 offset1:12
	v_max3_f32 v169, v2, v3, v4
	v_max3_f32 v172, v5, v6, v7
	v_max3_f32 v169, v8, v9, v169
	v_max3_f32 v172, v10, v11, v172
	v_max3_f32 v169, v12, v13, v169
	v_max3_f32 v172, v14, v15, v172
	v_max3_f32 v169, v16, v17, v169
	v_max3_f32 v172, v18, v19, v172
	v_max3_f32 v169, v20, v21, v169
	v_max3_f32 v172, v22, v23, v172
	v_max3_f32 v169, v24, v25, v169
	v_max3_f32 v172, v26, v27, v172
	v_max3_f32 v169, v28, v29, v169
	v_max3_f32 v172, v30, v31, v172
	v_max3_f32 v169, v32, v33, v169
	v_max3_f32 v172, v34, v35, v172
	v_max3_f32 v169, v36, v37, v169
	v_max3_f32 v172, v38, v39, v172
	v_max3_f32 v169, v40, v41, v169
	v_max3_f32 v172, v42, v43, v172
	v_max3_f32 v169, v44, v45, v169
	v_max3_f32 v172, v46, v47, v172
	v_max3_f32 v169, v48, v49, v169
	v_max3_f32 v172, v50, v51, v172
	v_max3_f32 v169, v52, v53, v169
	v_max3_f32 v172, v54, v55, v172
	v_max3_f32 v169, v56, v57, v169
	v_max3_f32 v172, v58, v59, v172
	v_max3_f32 v169, v60, v61, v169
	v_max3_f32 v172, v62, v63, v172
	v_max3_f32 v169, v64, v65, v169
	v_max3_f32 v172, v66, v67, v172
	v_max3_f32 v169, v68, v69, v169
	v_max_f32_e32 v169, v169, v172
	v_mul_f32_e32 v169, 0x3e000000, v169
	v_max_f32_e32 v169, v169, v146
	ds_bpermute_b32 v172, v1, v169
	s_waitcnt lgkmcnt(0)
	v_max_f32_e32 v169, v169, v172
	ds_bpermute_b32 v172, v114, v169
	s_waitcnt lgkmcnt(0)
	v_max_f32_e32 v169, v169, v172
	v_mul_f32_e32 v175, 0xbfb8aa3b, v169
	v_mov_b32_e32 v170, 0
	v_mov_b32_e32 v171, 0
	v_fma_f32 v2, v2, s46, v175
	v_fma_f32 v3, v3, s46, v175
	v_fma_f32 v4, v4, s46, v175
	v_fma_f32 v5, v5, s46, v175
	v_exp_f32_e32 v2, v2
	v_exp_f32_e32 v3, v3
	v_exp_f32_e32 v4, v4
	v_exp_f32_e32 v5, v5
	v_fma_f32 v6, v6, s46, v175
	v_fma_f32 v7, v7, s46, v175
	v_fma_f32 v8, v8, s46, v175
	v_fma_f32 v9, v9, s46, v175
	v_exp_f32_e32 v6, v6
	v_exp_f32_e32 v7, v7
	v_exp_f32_e32 v8, v8
	v_exp_f32_e32 v9, v9
	v_add_f32_e32 v171, v171, v2
	v_add_f32_e32 v170, v170, v3
	v_add_f32_e32 v171, v171, v4
	v_add_f32_e32 v170, v170, v5
	v_fma_f32 v10, v10, s46, v175
	v_fma_f32 v11, v11, s46, v175
	v_fma_f32 v12, v12, s46, v175
	v_fma_f32 v13, v13, s46, v175
	v_exp_f32_e32 v10, v10
	v_exp_f32_e32 v11, v11
	v_exp_f32_e32 v12, v12
	v_exp_f32_e32 v13, v13
	v_add_f32_e32 v171, v171, v6
	v_add_f32_e32 v170, v170, v7
	v_add_f32_e32 v171, v171, v8
	v_add_f32_e32 v170, v170, v9
	v_fma_f32 v14, v14, s46, v175
	v_fma_f32 v15, v15, s46, v175
	v_fma_f32 v16, v16, s46, v175
	v_fma_f32 v17, v17, s46, v175
	v_exp_f32_e32 v14, v14
	v_exp_f32_e32 v15, v15
	v_exp_f32_e32 v16, v16
	v_exp_f32_e32 v17, v17
	v_add_f32_e32 v171, v171, v10
	v_add_f32_e32 v170, v170, v11
	v_add_f32_e32 v171, v171, v12
	v_add_f32_e32 v170, v170, v13
	v_fma_f32 v18, v18, s46, v175
	v_fma_f32 v19, v19, s46, v175
	v_fma_f32 v20, v20, s46, v175
	v_fma_f32 v21, v21, s46, v175
	v_exp_f32_e32 v18, v18
	v_exp_f32_e32 v19, v19
	v_exp_f32_e32 v20, v20
	v_exp_f32_e32 v21, v21
	v_add_f32_e32 v171, v171, v14
	v_add_f32_e32 v170, v170, v15
	v_add_f32_e32 v171, v171, v16
	v_add_f32_e32 v170, v170, v17
	v_fma_f32 v22, v22, s46, v175
	v_fma_f32 v23, v23, s46, v175
	v_fma_f32 v24, v24, s46, v175
	v_fma_f32 v25, v25, s46, v175
	v_exp_f32_e32 v22, v22
	v_exp_f32_e32 v23, v23
	v_exp_f32_e32 v24, v24
	v_exp_f32_e32 v25, v25
	v_add_f32_e32 v171, v171, v18
	v_add_f32_e32 v170, v170, v19
	v_add_f32_e32 v171, v171, v20
	v_add_f32_e32 v170, v170, v21
	v_fma_f32 v26, v26, s46, v175
	v_fma_f32 v27, v27, s46, v175
	v_fma_f32 v28, v28, s46, v175
	v_fma_f32 v29, v29, s46, v175
	v_exp_f32_e32 v26, v26
	v_exp_f32_e32 v27, v27
	v_exp_f32_e32 v28, v28
	v_exp_f32_e32 v29, v29
	v_add_f32_e32 v171, v171, v22
	v_add_f32_e32 v170, v170, v23
	v_add_f32_e32 v171, v171, v24
	v_add_f32_e32 v170, v170, v25
	v_fma_f32 v30, v30, s46, v175
	v_fma_f32 v31, v31, s46, v175
	v_fma_f32 v32, v32, s46, v175
	v_fma_f32 v33, v33, s46, v175
	v_exp_f32_e32 v30, v30
	v_exp_f32_e32 v31, v31
	v_exp_f32_e32 v32, v32
	v_exp_f32_e32 v33, v33
	v_add_f32_e32 v171, v171, v26
	v_add_f32_e32 v170, v170, v27
	v_add_f32_e32 v171, v171, v28
	v_add_f32_e32 v170, v170, v29
	v_fma_f32 v34, v34, s46, v175
	v_fma_f32 v35, v35, s46, v175
	v_fma_f32 v36, v36, s46, v175
	v_fma_f32 v37, v37, s46, v175
	v_exp_f32_e32 v34, v34
	v_exp_f32_e32 v35, v35
	v_exp_f32_e32 v36, v36
	v_exp_f32_e32 v37, v37
	v_add_f32_e32 v171, v171, v30
	v_add_f32_e32 v170, v170, v31
	v_add_f32_e32 v171, v171, v32
	v_add_f32_e32 v170, v170, v33
	v_fma_f32 v38, v38, s46, v175
	v_fma_f32 v39, v39, s46, v175
	v_fma_f32 v40, v40, s46, v175
	v_fma_f32 v41, v41, s46, v175
	v_exp_f32_e32 v38, v38
	v_exp_f32_e32 v39, v39
	v_exp_f32_e32 v40, v40
	v_exp_f32_e32 v41, v41
	v_add_f32_e32 v171, v171, v34
	v_add_f32_e32 v170, v170, v35
	v_add_f32_e32 v171, v171, v36
	v_add_f32_e32 v170, v170, v37
	v_fma_f32 v42, v42, s46, v175
	v_fma_f32 v43, v43, s46, v175
	v_fma_f32 v44, v44, s46, v175
	v_fma_f32 v45, v45, s46, v175
	v_exp_f32_e32 v42, v42
; __device__ __forceinline__ unsigned cvt_pk_bf16_asm(float lo, float hi) { unsigned r; asm volatile("v_cvt_pk_bf16_f32 %0, %1, %2" : "=v"(r) : "v"(lo), "v"(hi)); return r; }
; __device__ __forceinline__ f32x4 mfma16(bf16x8 a, bf16x8 b, f32x4 c) { return __builtin_amdgcn_mfma_f32_16x16x32_bf16(a, b, c, 0, 0, 0); }
; __device__ void att_phase(int wv, const Params& p, unsigned char* lds) {
;     ...
;             for (int cb = 0; cb < 24; ++cb)
; #pragma unroll
;                 for (int j = 0; j < 4; ++j) { const float e = __expf(sc[cb][j] - mx); sc[cb][j] = e; sum += e; }
;             sum += __shfl_xor(sum, 16); sum += __shfl_xor(sum, 32);
;             sum += __expf(sink - mx);
;             const float inv = 1.0f / sum;
;             f32x4 oa[4];
; #pragma unroll
;             for (int db = 0; db < 4; ++db) oa[db] = (f32x4){0, 0, 0, 0};
; #pragma unroll
;             for (int ks = 0; ks < 12; ++ks) {
;                 union { bf16x8 v; unsigned u[4]; } pf;
;                 pf.u[0] = cvt_pk_bf16_asm(sc[2 * ks][0], sc[2 * ks][1]); pf.u[1] = cvt_pk_bf16_asm(sc[2 * ks][2], sc[2 * ks][3]);
;                 pf.u[2] = cvt_pk_bf16_asm(sc[2 * ks + 1][0], sc[2 * ks + 1][1]); pf.u[3] = cvt_pk_bf16_asm(sc[2 * ks + 1][2], sc[2 * ks + 1][3]);
; #pragma unroll
;                 for (int db = 0; db < 4; ++db) {
;                     union { bf16x8 v; u32x2 h2[2]; } vf;
;                     const bf16_t* vp = VTL + (16 * db + lr) * VP + 32 * ks + 4 * lq;
;                     vf.h2[0] = *(const u32x2*)vp; vf.h2[1] = *(const u32x2*)(vp + 16);
;                     oa[db] = mfma16(vf.v, pf.v, oa[db]); } }
	v_exp_f32_e32 v43, v43
	v_exp_f32_e32 v44, v44
	v_exp_f32_e32 v45, v45
	v_add_f32_e32 v171, v171, v38
	v_add_f32_e32 v170, v170, v39
	v_add_f32_e32 v171, v171, v40
	v_add_f32_e32 v170, v170, v41
	v_fma_f32 v46, v46, s46, v175
	v_fma_f32 v47, v47, s46, v175
	v_fma_f32 v48, v48, s46, v175
	v_fma_f32 v49, v49, s46, v175
	v_exp_f32_e32 v46, v46
	v_exp_f32_e32 v47, v47
	v_exp_f32_e32 v48, v48
	v_exp_f32_e32 v49, v49
	v_add_f32_e32 v171, v171, v42
	v_add_f32_e32 v170, v170, v43
	v_add_f32_e32 v171, v171, v44
	v_add_f32_e32 v170, v170, v45
	v_fma_f32 v50, v50, s46, v175
	v_fma_f32 v51, v51, s46, v175
	v_fma_f32 v52, v52, s46, v175
	v_fma_f32 v53, v53, s46, v175
	v_exp_f32_e32 v50, v50
	v_exp_f32_e32 v51, v51
	v_exp_f32_e32 v52, v52
	v_exp_f32_e32 v53, v53
	v_add_f32_e32 v171, v171, v46
	v_add_f32_e32 v170, v170, v47
	v_add_f32_e32 v171, v171, v48
	v_add_f32_e32 v170, v170, v49
	v_fma_f32 v54, v54, s46, v175
	v_fma_f32 v55, v55, s46, v175
	v_fma_f32 v56, v56, s46, v175
	v_fma_f32 v57, v57, s46, v175
	v_exp_f32_e32 v54, v54
	v_exp_f32_e32 v55, v55
	v_exp_f32_e32 v56, v56
	v_exp_f32_e32 v57, v57
	v_add_f32_e32 v171, v171, v50
	v_add_f32_e32 v170, v170, v51
	v_add_f32_e32 v171, v171, v52
	v_add_f32_e32 v170, v170, v53
	v_fma_f32 v58, v58, s46, v175
	v_fma_f32 v59, v59, s46, v175
	v_fma_f32 v60, v60, s46, v175
	v_fma_f32 v61, v61, s46, v175
	v_exp_f32_e32 v58, v58
	v_exp_f32_e32 v59, v59
	v_exp_f32_e32 v60, v60
	v_exp_f32_e32 v61, v61
	v_add_f32_e32 v171, v171, v54
	v_add_f32_e32 v170, v170, v55
	v_add_f32_e32 v171, v171, v56
	v_add_f32_e32 v170, v170, v57
	v_fma_f32 v62, v62, s46, v175
	v_fma_f32 v63, v63, s46, v175
	v_fma_f32 v64, v64, s46, v175
	v_fma_f32 v65, v65, s46, v175
	v_exp_f32_e32 v62, v62
	v_exp_f32_e32 v63, v63
	v_exp_f32_e32 v64, v64
	v_exp_f32_e32 v65, v65
	v_add_f32_e32 v171, v171, v58
	v_add_f32_e32 v170, v170, v59
	v_add_f32_e32 v171, v171, v60
	v_add_f32_e32 v170, v170, v61
	v_fma_f32 v66, v66, s46, v175
	v_fma_f32 v67, v67, s46, v175
	v_fma_f32 v68, v68, s46, v175
	v_fma_f32 v69, v69, s46, v175
	v_exp_f32_e32 v66, v66
	v_exp_f32_e32 v67, v67
	v_exp_f32_e32 v68, v68
	v_exp_f32_e32 v69, v69
	v_add_f32_e32 v171, v171, v62
	v_add_f32_e32 v170, v170, v63
	v_add_f32_e32 v171, v171, v64
	v_add_f32_e32 v170, v170, v65
	v_add_f32_e32 v171, v171, v66
	v_add_f32_e32 v170, v170, v67
	v_add_f32_e32 v171, v171, v68
	v_add_f32_e32 v170, v170, v69
	v_add_f32_e32 v170, v170, v171
	v_cvt_pk_bf16_f32 v2, v2, v3
	v_cvt_pk_bf16_f32 v3, v4, v5
	v_cvt_pk_bf16_f32 v4, v6, v7
	v_cvt_pk_bf16_f32 v5, v8, v9
	v_cvt_pk_bf16_f32 v10, v10, v11
	v_cvt_pk_bf16_f32 v11, v12, v13
	v_cvt_pk_bf16_f32 v12, v14, v15
	v_cvt_pk_bf16_f32 v13, v16, v17
	v_cvt_pk_bf16_f32 v18, v18, v19
	v_cvt_pk_bf16_f32 v19, v20, v21
	v_cvt_pk_bf16_f32 v20, v22, v23
	v_cvt_pk_bf16_f32 v21, v24, v25
	v_cvt_pk_bf16_f32 v26, v26, v27
	v_cvt_pk_bf16_f32 v27, v28, v29
	v_cvt_pk_bf16_f32 v28, v30, v31
	v_cvt_pk_bf16_f32 v29, v32, v33
	v_cvt_pk_bf16_f32 v34, v34, v35
	v_cvt_pk_bf16_f32 v35, v36, v37
	v_cvt_pk_bf16_f32 v36, v38, v39
	v_cvt_pk_bf16_f32 v37, v40, v41
	v_cvt_pk_bf16_f32 v42, v42, v43
	v_cvt_pk_bf16_f32 v43, v44, v45
	v_cvt_pk_bf16_f32 v44, v46, v47
	v_cvt_pk_bf16_f32 v45, v48, v49
	v_cvt_pk_bf16_f32 v50, v50, v51
	v_cvt_pk_bf16_f32 v51, v52, v53
	v_cvt_pk_bf16_f32 v52, v54, v55
	v_cvt_pk_bf16_f32 v53, v56, v57
	v_cvt_pk_bf16_f32 v58, v58, v59
	v_cvt_pk_bf16_f32 v59, v60, v61
	v_cvt_pk_bf16_f32 v60, v62, v63
	v_cvt_pk_bf16_f32 v61, v64, v65
	v_cvt_pk_bf16_f32 v66, v66, v67
	v_cvt_pk_bf16_f32 v67, v68, v69
	v_mov_b32_e32 v68, 0
	v_mov_b32_e32 v69, 0
	ds_bpermute_b32 v172, v1, v170
	v_sub_f32_e32 v173, v146, v169
	v_mul_f32_e32 v173, 0x3fb8aa3b, v173
	v_exp_f32_e32 v173, v173
	s_waitcnt lgkmcnt(0)
	v_add_f32_e32 v170, v170, v172
	ds_bpermute_b32 v172, v114, v170
	ds_read2_b64 v[232:235], v165 offset0:16 offset1:20
	ds_read2_b64 v[236:239], v166 offset0:16 offset1:20
	ds_read2_b64 v[240:243], v167 offset0:16 offset1:20
	ds_read2_b64 v[244:247], v168 offset0:16 offset1:20
	s_waitcnt lgkmcnt(4)
	v_mfma_f32_16x16x32_bf16 v[70:73], v[216:219], v[2:5], 0
	v_mfma_f32_16x16x32_bf16 v[74:77], v[220:223], v[2:5], 0
	v_mfma_f32_16x16x32_bf16 v[78:81], v[224:227], v[2:5], 0
	v_mfma_f32_16x16x32_bf16 v[82:85], v[228:231], v[2:5], 0
	v_add_f32_e32 v170, v170, v172
	v_add_f32_e32 v170, v170, v173
	v_rcp_f32_e32 v147, v170
	s_nop 0
	v_fma_f32 v179, -v170, v147, 1.0
	v_fmac_f32_e32 v147, v179, v147
	ds_read2_b64 v[216:219], v165 offset0:24 offset1:28
	ds_read2_b64 v[220:223], v166 offset0:24 offset1:28
	ds_read2_b64 v[224:227], v167 offset0:24 offset1:28
	ds_read2_b64 v[228:231], v168 offset0:24 offset1:28
	s_waitcnt lgkmcnt(4)
	v_mfma_f32_16x16x32_bf16 v[70:73], v[232:235], v[10:13], v[70:73]
	v_mfma_f32_16x16x32_bf16 v[74:77], v[236:239], v[10:13], v[74:77]
	v_mfma_f32_16x16x32_bf16 v[78:81], v[240:243], v[10:13], v[78:81]
	v_mfma_f32_16x16x32_bf16 v[82:85], v[244:247], v[10:13], v[82:85]
	ds_read2_b64 v[232:235], v165 offset0:32 offset1:36
	ds_read2_b64 v[236:239], v166 offset0:32 offset1:36
	ds_read2_b64 v[240:243], v167 offset0:32 offset1:36
	ds_read2_b64 v[244:247], v168 offset0:32 offset1:36
	s_waitcnt lgkmcnt(4)
	v_mfma_f32_16x16x32_bf16 v[70:73], v[216:219], v[18:21], v[70:73]
	v_mfma_f32_16x16x32_bf16 v[74:77], v[220:223], v[18:21], v[74:77]
	v_mfma_f32_16x16x32_bf16 v[78:81], v[224:227], v[18:21], v[78:81]
	v_mfma_f32_16x16x32_bf16 v[82:85], v[228:231], v[18:21], v[82:85]
	ds_read2_b64 v[216:219], v165 offset0:40 offset1:44
	ds_read2_b64 v[220:223], v166 offset0:40 offset1:44
	ds_read2_b64 v[224:227], v167 offset0:40 offset1:44
	ds_read2_b64 v[228:231], v168 offset0:40 offset1:44
	s_waitcnt lgkmcnt(4)
; __device__ __forceinline__ unsigned cvt_pk_bf16_asm(float lo, float hi) { unsigned r; asm volatile("v_cvt_pk_bf16_f32 %0, %1, %2" : "=v"(r) : "v"(lo), "v"(hi)); return r; }
; __device__ __forceinline__ f32x4 mfma16(bf16x8 a, bf16x8 b, f32x4 c) { return __builtin_amdgcn_mfma_f32_16x16x32_bf16(a, b, c, 0, 0, 0); }
; __device__ void att_phase(int wv, const Params& p, unsigned char* lds) {
;     ...
;             f32x4 sc[24];
; #pragma unroll
;             for (int cb = 0; cb < 24; ++cb) { f32x4 a = {0, 0, 0, 0};
; #pragma unroll
;                 for (int kk = 0; kk < 2; ++kk) { const bf16x8 kf = *(const bf16x8*)(KL + (16 * cb + lr) * KP + 32 * kk + 8 * lq); a = mfma16(kf, qf[kk], a); }
;                 sc[cb] = a; }
;     ...
;             for (int ks = 0; ks < 12; ++ks) {
;                 union { bf16x8 v; unsigned u[4]; } pf;
;                 pf.u[0] = cvt_pk_bf16_asm(sc[2 * ks][0], sc[2 * ks][1]); pf.u[1] = cvt_pk_bf16_asm(sc[2 * ks][2], sc[2 * ks][3]);
;                 pf.u[2] = cvt_pk_bf16_asm(sc[2 * ks + 1][0], sc[2 * ks + 1][1]); pf.u[3] = cvt_pk_bf16_asm(sc[2 * ks + 1][2], sc[2 * ks + 1][3]);
; #pragma unroll
;                 for (int db = 0; db < 4; ++db) {
;                     union { bf16x8 v; u32x2 h2[2]; } vf;
;                     const bf16_t* vp = VTL + (16 * db + lr) * VP + 32 * ks + 4 * lq;
;                     vf.h2[0] = *(const u32x2*)vp; vf.h2[1] = *(const u32x2*)(vp + 16);
;                     oa[db] = mfma16(vf.v, pf.v, oa[db]); } }
; #pragma unroll
;             for (int db = 0; db < 4; ++db) { const f32x4 o = oa[db] * inv; u32x2 wv; wv.x = cvt_pk_bf16_asm(o[0], o[1]); wv.y = cvt_pk_bf16_asm(o[2], o[3]);
;                 *(u32x2*)(qkv + tokq * 1536 + 64 * h + 16 * db + 4 * lq) = wv; }
	v_mfma_f32_16x16x32_bf16 v[70:73], v[232:235], v[26:29], v[70:73]
	v_mfma_f32_16x16x32_bf16 v[74:77], v[236:239], v[26:29], v[74:77]
	v_mfma_f32_16x16x32_bf16 v[78:81], v[240:243], v[26:29], v[78:81]
	v_mfma_f32_16x16x32_bf16 v[82:85], v[244:247], v[26:29], v[82:85]
	ds_read2_b64 v[232:235], v165 offset0:48 offset1:52
	ds_read2_b64 v[236:239], v166 offset0:48 offset1:52
	ds_read2_b64 v[240:243], v167 offset0:48 offset1:52
	ds_read2_b64 v[244:247], v168 offset0:48 offset1:52
	s_waitcnt lgkmcnt(4)
	v_mfma_f32_16x16x32_bf16 v[70:73], v[216:219], v[34:37], v[70:73]
	v_mfma_f32_16x16x32_bf16 v[74:77], v[220:223], v[34:37], v[74:77]
	v_mfma_f32_16x16x32_bf16 v[78:81], v[224:227], v[34:37], v[78:81]
	v_mfma_f32_16x16x32_bf16 v[82:85], v[228:231], v[34:37], v[82:85]
	ds_read2_b64 v[216:219], v165 offset0:56 offset1:60
	ds_read2_b64 v[220:223], v166 offset0:56 offset1:60
	ds_read2_b64 v[224:227], v167 offset0:56 offset1:60
	ds_read2_b64 v[228:231], v168 offset0:56 offset1:60
	s_waitcnt lgkmcnt(4)
	v_mfma_f32_16x16x32_bf16 v[70:73], v[232:235], v[42:45], v[70:73]
	v_mfma_f32_16x16x32_bf16 v[74:77], v[236:239], v[42:45], v[74:77]
	v_mfma_f32_16x16x32_bf16 v[78:81], v[240:243], v[42:45], v[78:81]
	v_mfma_f32_16x16x32_bf16 v[82:85], v[244:247], v[42:45], v[82:85]
	ds_read2_b64 v[232:235], v165 offset0:64 offset1:68
	ds_read2_b64 v[236:239], v166 offset0:64 offset1:68
	ds_read2_b64 v[240:243], v167 offset0:64 offset1:68
	ds_read2_b64 v[244:247], v168 offset0:64 offset1:68
	s_waitcnt lgkmcnt(4)
	v_mfma_f32_16x16x32_bf16 v[70:73], v[216:219], v[50:53], v[70:73]
	v_mfma_f32_16x16x32_bf16 v[74:77], v[220:223], v[50:53], v[74:77]
	v_mfma_f32_16x16x32_bf16 v[78:81], v[224:227], v[50:53], v[78:81]
	v_mfma_f32_16x16x32_bf16 v[82:85], v[228:231], v[50:53], v[82:85]
	ds_read2_b64 v[216:219], v165 offset0:72 offset1:72
	ds_read2_b64 v[220:223], v166 offset0:72 offset1:72
	ds_read2_b64 v[224:227], v167 offset0:72 offset1:72
	ds_read2_b64 v[228:231], v168 offset0:72 offset1:72
	s_waitcnt lgkmcnt(4)
	v_mfma_f32_16x16x32_bf16 v[70:73], v[232:235], v[58:61], v[70:73]
	v_mfma_f32_16x16x32_bf16 v[74:77], v[236:239], v[58:61], v[74:77]
	v_mfma_f32_16x16x32_bf16 v[78:81], v[240:243], v[58:61], v[78:81]
	v_mfma_f32_16x16x32_bf16 v[82:85], v[244:247], v[58:61], v[82:85]
	s_waitcnt lgkmcnt(0)
	v_mfma_f32_16x16x32_bf16 v[70:73], v[216:219], v[66:69], v[70:73]
	v_mfma_f32_16x16x32_bf16 v[74:77], v[220:223], v[66:69], v[74:77]
	v_mfma_f32_16x16x32_bf16 v[78:81], v[224:227], v[66:69], v[78:81]
	v_mfma_f32_16x16x32_bf16 v[82:85], v[228:231], v[66:69], v[82:85]
	s_nop 7
	s_nop 1
	v_mul_f32_e32 v70, v70, v147
	v_mul_f32_e32 v71, v71, v147
	v_mul_f32_e32 v72, v72, v147
	v_mul_f32_e32 v73, v73, v147
	v_mul_f32_e32 v74, v74, v147
	v_mul_f32_e32 v75, v75, v147
	v_mul_f32_e32 v76, v76, v147
	v_mul_f32_e32 v77, v77, v147
	v_mul_f32_e32 v78, v78, v147
	v_mul_f32_e32 v79, v79, v147
	v_mul_f32_e32 v80, v80, v147
	v_mul_f32_e32 v81, v81, v147
	v_mul_f32_e32 v82, v82, v147
	v_mul_f32_e32 v83, v83, v147
	v_mul_f32_e32 v84, v84, v147
	v_mul_f32_e32 v85, v85, v147
	v_cvt_pk_bf16_f32 v70, v70, v71
	v_cvt_pk_bf16_f32 v71, v72, v73
	v_cvt_pk_bf16_f32 v74, v74, v75
	v_cvt_pk_bf16_f32 v75, v76, v77
	v_cvt_pk_bf16_f32 v78, v78, v79
	v_cvt_pk_bf16_f32 v79, v80, v81
	v_cvt_pk_bf16_f32 v82, v82, v83
	v_cvt_pk_bf16_f32 v83, v84, v85
	global_store_dwordx2 v[248:249], v[70:71], off offset:-64
	global_store_dwordx2 v[248:249], v[74:75], off offset:-32
	global_store_dwordx2 v[248:249], v[78:79], off
	global_store_dwordx2 v[248:249], v[82:83], off offset:32
	v_lshl_add_u64 v[248:249], v[248:249], 0, s[48:49]
	v_sub_f32_e32 v86, v94, v176
	v_sub_f32_e32 v87, v95, v176
	v_sub_f32_e32 v88, v96, v176
	v_sub_f32_e32 v89, v97, v176
	v_cmp_ge_i32_e32 vcc, 0, v108
	s_nop 1
	v_cndmask_b32_e32 v212, v252, v86, vcc
	v_cmp_ge_i32_e32 vcc, 0, v110
	s_nop 1
	v_cndmask_b32_e32 v213, v252, v87, vcc
	v_cmp_ge_i32_e32 vcc, 0, v111
	s_nop 1
	v_cndmask_b32_e32 v214, v252, v88, vcc
	v_cmp_ge_i32_e32 vcc, 0, v177
	s_nop 1
	v_cndmask_b32_e32 v215, v252, v89, vcc
	ds_read_b128 v[148:151], v164 offset:6912
	ds_read_b128 v[152:155], v164 offset:6976
	ds_read_b128 v[156:159], v164 offset:9216
	ds_read_b128 v[160:163], v164 offset:9280
	v_add_f32_e32 v90, v86, v174
	v_add_f32_e32 v91, v87, v174
	v_add_f32_e32 v92, v88, v174
	v_add_f32_e32 v93, v89, v174
	s_cmp_lt_i32 s47, 13
	s_cselect_b64 vcc, -1, s[10:11]
	s_cmp_lt_i32 s47, 5
	s_cselect_b64 vcc, s[6:7], vcc
	v_cndmask_b32_e32 v232, v252, v212, vcc
	v_cndmask_b32_e32 v233, v252, v213, vcc
	v_cndmask_b32_e32 v234, v252, v214, vcc
	v_cndmask_b32_e32 v235, v252, v215, vcc
	s_waitcnt lgkmcnt(2)
	v_mfma_f32_16x16x32_bf16 v[2:5], v[148:151], v[204:207], v[232:235]
	v_mfma_f32_16x16x32_bf16 v[2:5], v[152:155], v[208:211], v[2:5]
	ds_read_b128 v[148:151], v164 offset:11520
	ds_read_b128 v[152:155], v164 offset:11584
	v_add_f32_e32 v86, v90, v174
	v_add_f32_e32 v87, v91, v174
	v_add_f32_e32 v88, v92, v174
	v_add_f32_e32 v89, v93, v174
	s_cmp_lt_i32 s47, 12
	s_cselect_b64 vcc, -1, s[10:11]
	s_cmp_lt_i32 s47, 4
	s_cselect_b64 vcc, s[6:7], vcc
	v_cndmask_b32_e32 v236, v252, v90, vcc
	v_cndmask_b32_e32 v237, v252, v91, vcc
	v_cndmask_b32_e32 v238, v252, v92, vcc
	v_cndmask_b32_e32 v239, v252, v93, vcc
	s_waitcnt lgkmcnt(2)
	v_mfma_f32_16x16x32_bf16 v[6:9], v[156:159], v[204:207], v[236:239]
	v_mfma_f32_16x16x32_bf16 v[6:9], v[160:163], v[208:211], v[6:9]
	ds_read_b128 v[156:159], v164 offset:13824
	ds_read_b128 v[160:163], v164 offset:13888
	v_add_f32_e32 v90, v86, v174
	v_add_f32_e32 v91, v87, v174
	v_add_f32_e32 v92, v88, v174
	v_add_f32_e32 v93, v89, v174
	s_cmp_lt_i32 s47, 11
	s_cselect_b64 vcc, -1, s[10:11]
	s_cmp_lt_i32 s47, 3
	s_cselect_b64 vcc, s[6:7], vcc
	v_cndmask_b32_e32 v232, v252, v86, vcc
	v_cndmask_b32_e32 v233, v252, v87, vcc
	v_cndmask_b32_e32 v234, v252, v88, vcc
	v_cndmask_b32_e32 v235, v252, v89, vcc
	s_waitcnt lgkmcnt(2)
; __device__ __forceinline__ f32x4 mfma16(bf16x8 a, bf16x8 b, f32x4 c) { return __builtin_amdgcn_mfma_f32_16x16x32_bf16(a, b, c, 0, 0, 0); }
; __device__ void att_phase(int wv, const Params& p, unsigned char* lds) {
;     ...
;             f32x4 sc[24];
; #pragma unroll
;             for (int cb = 0; cb < 24; ++cb) { f32x4 a = {0, 0, 0, 0};
; #pragma unroll
;                 for (int kk = 0; kk < 2; ++kk) { const bf16x8 kf = *(const bf16x8*)(KL + (16 * cb + lr) * KP + 32 * kk + 8 * lq); a = mfma16(kf, qf[kk], a); }
;                 sc[cb] = a; }
;             float mx = sink;
; #pragma unroll
;             for (int cb = 0; cb < 24; ++cb) { const int kb = B - 1 + (cb >> 3); const bool bval = (kb >= sb && kb < se);
; #pragma unroll
;                 for (int j = 0; j < 4; ++j) { const int krel = 16 * cb + 4 * lq + j - 128;
;                     int dist = qrow - krel; dist = dist < 0 ? -dist : dist;
;                     const float v = (bval && dist <= 128) ? sc[cb][j] * 0.125f - slope * (float)dist : -1e30f;
;                     sc[cb][j] = v; mx = fmaxf(mx, v); } }
	v_mfma_f32_16x16x32_bf16 v[10:13], v[148:151], v[204:207], v[232:235]
	v_mfma_f32_16x16x32_bf16 v[10:13], v[152:155], v[208:211], v[10:13]
	ds_read_b128 v[148:151], v164 offset:16128
	ds_read_b128 v[152:155], v164 offset:16192
	v_add_f32_e32 v86, v90, v174
	v_add_f32_e32 v87, v91, v174
	v_add_f32_e32 v88, v92, v174
	v_add_f32_e32 v89, v93, v174
	s_cmp_lt_i32 s47, 10
	s_cselect_b64 vcc, -1, s[10:11]
	s_cmp_lt_i32 s47, 2
	s_cselect_b64 vcc, s[6:7], vcc
	v_cndmask_b32_e32 v236, v252, v90, vcc
	v_cndmask_b32_e32 v237, v252, v91, vcc
	v_cndmask_b32_e32 v238, v252, v92, vcc
	v_cndmask_b32_e32 v239, v252, v93, vcc
	s_waitcnt lgkmcnt(2)
	v_mfma_f32_16x16x32_bf16 v[14:17], v[156:159], v[204:207], v[236:239]
	v_mfma_f32_16x16x32_bf16 v[14:17], v[160:163], v[208:211], v[14:17]
	ds_read_b128 v[156:159], v164 offset:18432
	ds_read_b128 v[160:163], v164 offset:18496
	v_add_f32_e32 v90, v86, v174
	v_add_f32_e32 v91, v87, v174
	v_add_f32_e32 v92, v88, v174
	v_add_f32_e32 v93, v89, v174
	s_cmp_lt_i32 s47, 9
	s_cselect_b64 vcc, -1, s[10:11]
	s_cmp_lt_i32 s47, 1
	s_cselect_b64 vcc, s[6:7], vcc
	v_cndmask_b32_e32 v232, v252, v86, vcc
	v_cndmask_b32_e32 v233, v252, v87, vcc
	v_cndmask_b32_e32 v234, v252, v88, vcc
	v_cndmask_b32_e32 v235, v252, v89, vcc
	s_waitcnt lgkmcnt(2)
	v_mfma_f32_16x16x32_bf16 v[18:21], v[148:151], v[204:207], v[232:235]
	v_mfma_f32_16x16x32_bf16 v[18:21], v[152:155], v[208:211], v[18:21]
	ds_read_b128 v[148:151], v164 offset:20736
	ds_read_b128 v[152:155], v164 offset:20800
	v_add_f32_e32 v86, v90, v174
	v_add_f32_e32 v87, v91, v174
	v_add_f32_e32 v88, v92, v174
	v_add_f32_e32 v89, v93, v174
	s_waitcnt lgkmcnt(2)
	v_mfma_f32_16x16x32_bf16 v[22:25], v[156:159], v[204:207], v[90:93]
	v_mfma_f32_16x16x32_bf16 v[22:25], v[160:163], v[208:211], v[22:25]
	ds_read_b128 v[156:159], v164 offset:23040
	ds_read_b128 v[160:163], v164 offset:23104
	v_add_f32_e32 v90, v86, v174
	v_add_f32_e32 v91, v87, v174
	v_add_f32_e32 v92, v88, v174
	v_add_f32_e32 v93, v89, v174
	s_waitcnt lgkmcnt(2)
	v_mfma_f32_16x16x32_bf16 v[26:29], v[148:151], v[204:207], v[86:89]
	v_mfma_f32_16x16x32_bf16 v[26:29], v[152:155], v[208:211], v[26:29]
	ds_read_b128 v[148:151], v164 offset:25344
	ds_read_b128 v[152:155], v164 offset:25408
	s_waitcnt lgkmcnt(2)
	v_mfma_f32_16x16x32_bf16 v[30:33], v[156:159], v[204:207], v[90:93]
	v_mfma_f32_16x16x32_bf16 v[30:33], v[160:163], v[208:211], v[30:33]
	ds_read_b128 v[156:159], v164 offset:27648
	ds_read_b128 v[160:163], v164 offset:27712
	v_sub_f32_e64 v86, -v94, v174
	v_sub_f32_e64 v87, -v95, v174
	v_sub_f32_e64 v88, -v96, v174
	v_sub_f32_e64 v89, -v97, v174
	s_waitcnt lgkmcnt(2)
	v_mfma_f32_16x16x32_bf16 v[34:37], v[148:151], v[204:207], v[98:101]
	v_mfma_f32_16x16x32_bf16 v[34:37], v[152:155], v[208:211], v[34:37]
	ds_read_b128 v[148:151], v164 offset:29952
	ds_read_b128 v[152:155], v164 offset:30016
	v_sub_f32_e32 v90, v86, v174
	v_sub_f32_e32 v91, v87, v174
	v_sub_f32_e32 v92, v88, v174
	v_sub_f32_e32 v93, v89, v174
	s_cmp_lt_i32 s47, 4
	s_cselect_b64 vcc, -1, s[10:11]
	s_cmp_lt_i32 s47, -4
	s_cselect_b64 vcc, s[6:7], vcc
	v_cndmask_b32_e32 v236, v252, v86, vcc
	v_cndmask_b32_e32 v237, v252, v87, vcc
	v_cndmask_b32_e32 v238, v252, v88, vcc
	v_cndmask_b32_e32 v239, v252, v89, vcc
	s_waitcnt lgkmcnt(2)
	v_mfma_f32_16x16x32_bf16 v[38:41], v[156:159], v[204:207], v[236:239]
	v_mfma_f32_16x16x32_bf16 v[38:41], v[160:163], v[208:211], v[38:41]
	ds_read_b128 v[156:159], v164 offset:32256
	ds_read_b128 v[160:163], v164 offset:32320
	v_sub_f32_e32 v86, v90, v174
	v_sub_f32_e32 v87, v91, v174
	v_sub_f32_e32 v88, v92, v174
	v_sub_f32_e32 v89, v93, v174
	s_cmp_lt_i32 s47, 3
	s_cselect_b64 vcc, -1, s[10:11]
	s_cmp_lt_i32 s47, -5
	s_cselect_b64 vcc, s[6:7], vcc
	v_cndmask_b32_e32 v232, v252, v90, vcc
	v_cndmask_b32_e32 v233, v252, v91, vcc
	v_cndmask_b32_e32 v234, v252, v92, vcc
	v_cndmask_b32_e32 v235, v252, v93, vcc
	s_waitcnt lgkmcnt(2)
	v_mfma_f32_16x16x32_bf16 v[42:45], v[148:151], v[204:207], v[232:235]
	v_mfma_f32_16x16x32_bf16 v[42:45], v[152:155], v[208:211], v[42:45]
	ds_read_b128 v[148:151], v164 offset:34560
	ds_read_b128 v[152:155], v164 offset:34624
	v_sub_f32_e32 v90, v86, v174
	v_sub_f32_e32 v91, v87, v174
	v_sub_f32_e32 v92, v88, v174
	v_sub_f32_e32 v93, v89, v174
	s_cmp_lt_i32 s47, 2
	s_cselect_b64 vcc, -1, s[10:11]
	s_cmp_lt_i32 s47, -6
	s_cselect_b64 vcc, s[6:7], vcc
	v_cndmask_b32_e32 v236, v252, v86, vcc
	v_cndmask_b32_e32 v237, v252, v87, vcc
	v_cndmask_b32_e32 v238, v252, v88, vcc
	v_cndmask_b32_e32 v239, v252, v89, vcc
	s_waitcnt lgkmcnt(2)
	v_mfma_f32_16x16x32_bf16 v[46:49], v[156:159], v[204:207], v[236:239]
	v_mfma_f32_16x16x32_bf16 v[46:49], v[160:163], v[208:211], v[46:49]
	ds_read_b128 v[156:159], v164 offset:36864
	ds_read_b128 v[160:163], v164 offset:36928
	v_sub_f32_e32 v86, v90, v174
	v_sub_f32_e32 v87, v91, v174
	v_sub_f32_e32 v88, v92, v174
	v_sub_f32_e32 v89, v93, v174
	s_cmp_lt_i32 s47, 1
	s_cselect_b64 vcc, -1, s[10:11]
	s_cmp_lt_i32 s47, -7
	s_cselect_b64 vcc, s[6:7], vcc
	v_cndmask_b32_e32 v232, v252, v90, vcc
	v_cndmask_b32_e32 v233, v252, v91, vcc
	v_cndmask_b32_e32 v234, v252, v92, vcc
	v_cndmask_b32_e32 v235, v252, v93, vcc
	s_waitcnt lgkmcnt(2)
	v_mfma_f32_16x16x32_bf16 v[50:53], v[148:151], v[204:207], v[232:235]
	v_mfma_f32_16x16x32_bf16 v[50:53], v[152:155], v[208:211], v[50:53]
	ds_read_b128 v[148:151], v164 offset:39168
	ds_read_b128 v[152:155], v164 offset:39232
	v_sub_f32_e32 v90, v86, v174
	v_sub_f32_e32 v91, v87, v174
	v_sub_f32_e32 v92, v88, v174
	v_sub_f32_e32 v93, v89, v174
	s_cmp_lt_i32 s47, 0
	s_cselect_b64 vcc, -1, s[10:11]
	s_cmp_lt_i32 s47, -8
	s_cselect_b64 vcc, s[6:7], vcc
	v_cndmask_b32_e32 v236, v252, v86, vcc
	v_cndmask_b32_e32 v237, v252, v87, vcc
	v_cndmask_b32_e32 v238, v252, v88, vcc
	v_cndmask_b32_e32 v239, v252, v89, vcc
	s_waitcnt lgkmcnt(2)
; __device__ __forceinline__ f32x4 mfma16(bf16x8 a, bf16x8 b, f32x4 c) { return __builtin_amdgcn_mfma_f32_16x16x32_bf16(a, b, c, 0, 0, 0); }
; __device__ void att_phase(int wv, const Params& p, unsigned char* lds) {
;     ...
;             f32x4 sc[24];
; #pragma unroll
;             for (int cb = 0; cb < 24; ++cb) { f32x4 a = {0, 0, 0, 0};
; #pragma unroll
;                 for (int kk = 0; kk < 2; ++kk) { const bf16x8 kf = *(const bf16x8*)(KL + (16 * cb + lr) * KP + 32 * kk + 8 * lq); a = mfma16(kf, qf[kk], a); }
;                 sc[cb] = a; }
;             float mx = sink;
; #pragma unroll
;             for (int cb = 0; cb < 24; ++cb) { const int kb = B - 1 + (cb >> 3); const bool bval = (kb >= sb && kb < se);
; #pragma unroll
;                 for (int j = 0; j < 4; ++j) { const int krel = 16 * cb + 4 * lq + j - 128;
;                     int dist = qrow - krel; dist = dist < 0 ? -dist : dist;
;                     const float v = (bval && dist <= 128) ? sc[cb][j] * 0.125f - slope * (float)dist : -1e30f;
;                     sc[cb][j] = v; mx = fmaxf(mx, v); } }
;             mx = fmaxf(mx, __shfl_xor(mx, 16)); mx = fmaxf(mx, __shfl_xor(mx, 32));
;             float sum = 0.f;
; #pragma unroll
;             for (int cb = 0; cb < 24; ++cb)
; #pragma unroll
;                 for (int j = 0; j < 4; ++j) { const float e = __expf(sc[cb][j] - mx); sc[cb][j] = e; sum += e; }
	v_mfma_f32_16x16x32_bf16 v[54:57], v[156:159], v[204:207], v[236:239]
	v_mfma_f32_16x16x32_bf16 v[54:57], v[160:163], v[208:211], v[54:57]
	ds_read_b128 v[156:159], v164 offset:41472
	ds_read_b128 v[160:163], v164 offset:41536
	v_sub_f32_e32 v86, v90, v174
	v_sub_f32_e32 v87, v91, v174
	v_sub_f32_e32 v88, v92, v174
	v_sub_f32_e32 v89, v93, v174
	s_cmp_lt_i32 s47, -1
	s_cselect_b64 vcc, -1, s[10:11]
	s_cmp_lt_i32 s47, -9
	s_cselect_b64 vcc, s[6:7], vcc
	v_cndmask_b32_e32 v232, v252, v90, vcc
	v_cndmask_b32_e32 v233, v252, v91, vcc
	v_cndmask_b32_e32 v234, v252, v92, vcc
	v_cndmask_b32_e32 v235, v252, v93, vcc
	s_waitcnt lgkmcnt(2)
	v_mfma_f32_16x16x32_bf16 v[58:61], v[148:151], v[204:207], v[232:235]
	v_mfma_f32_16x16x32_bf16 v[58:61], v[152:155], v[208:211], v[58:61]
	ds_read_b128 v[148:151], v164 offset:43776
	ds_read_b128 v[152:155], v164 offset:43840
	v_sub_f32_e32 v90, v86, v174
	v_sub_f32_e32 v91, v87, v174
	v_sub_f32_e32 v92, v88, v174
	v_sub_f32_e32 v93, v89, v174
	v_cmp_le_i32_e32 vcc, 0, v108
	s_nop 1
	v_cndmask_b32_e32 v212, v252, v90, vcc
	v_cmp_le_i32_e32 vcc, 0, v110
	s_nop 1
	v_cndmask_b32_e32 v213, v252, v91, vcc
	v_cmp_le_i32_e32 vcc, 0, v111
	s_nop 1
	v_cndmask_b32_e32 v214, v252, v92, vcc
	v_cmp_le_i32_e32 vcc, 0, v177
	s_nop 1
	v_cndmask_b32_e32 v215, v252, v93, vcc
	s_cmp_lt_i32 s47, -2
	s_cselect_b64 vcc, -1, s[10:11]
	s_cmp_lt_i32 s47, -10
	s_cselect_b64 vcc, s[6:7], vcc
	v_cndmask_b32_e32 v236, v252, v86, vcc
	v_cndmask_b32_e32 v237, v252, v87, vcc
	v_cndmask_b32_e32 v238, v252, v88, vcc
	v_cndmask_b32_e32 v239, v252, v89, vcc
	s_waitcnt lgkmcnt(2)
	v_mfma_f32_16x16x32_bf16 v[62:65], v[156:159], v[204:207], v[236:239]
	v_mfma_f32_16x16x32_bf16 v[62:65], v[160:163], v[208:211], v[62:65]
	s_cmp_lt_i32 s47, -3
	s_cselect_b64 vcc, -1, s[10:11]
	s_cmp_lt_i32 s47, -11
	s_cselect_b64 vcc, s[6:7], vcc
	v_cndmask_b32_e32 v232, v252, v212, vcc
	v_cndmask_b32_e32 v233, v252, v213, vcc
	v_cndmask_b32_e32 v234, v252, v214, vcc
	v_cndmask_b32_e32 v235, v252, v215, vcc
	s_waitcnt lgkmcnt(0)
	v_mfma_f32_16x16x32_bf16 v[66:69], v[148:151], v[204:207], v[232:235]
	v_mfma_f32_16x16x32_bf16 v[66:69], v[152:155], v[208:211], v[66:69]
	ds_read2_b64 v[216:219], v165 offset0:12 offset1:16
	ds_read2_b64 v[220:223], v166 offset0:12 offset1:16
	ds_read2_b64 v[224:227], v167 offset0:12 offset1:16
	ds_read2_b64 v[228:231], v168 offset0:12 offset1:16
	v_max3_f32 v169, v2, v3, v4
	v_max3_f32 v172, v5, v6, v7
	v_max3_f32 v169, v8, v9, v169
	v_max3_f32 v172, v10, v11, v172
	v_max3_f32 v169, v12, v13, v169
	v_max3_f32 v172, v14, v15, v172
	v_max3_f32 v169, v16, v17, v169
	v_max3_f32 v172, v18, v19, v172
	v_max3_f32 v169, v20, v21, v169
	v_max3_f32 v172, v22, v23, v172
	v_max3_f32 v169, v24, v25, v169
	v_max3_f32 v172, v26, v27, v172
	v_max3_f32 v169, v28, v29, v169
	v_max3_f32 v172, v30, v31, v172
	v_max3_f32 v169, v32, v33, v169
	v_max3_f32 v172, v34, v35, v172
	v_max3_f32 v169, v36, v37, v169
	v_max3_f32 v172, v38, v39, v172
	v_max3_f32 v169, v40, v41, v169
	v_max3_f32 v172, v42, v43, v172
	v_max3_f32 v169, v44, v45, v169
	v_max3_f32 v172, v46, v47, v172
	v_max3_f32 v169, v48, v49, v169
	v_max3_f32 v172, v50, v51, v172
	v_max3_f32 v169, v52, v53, v169
	v_max3_f32 v172, v54, v55, v172
	v_max3_f32 v169, v56, v57, v169
	v_max3_f32 v172, v58, v59, v172
	v_max3_f32 v169, v60, v61, v169
	v_max3_f32 v172, v62, v63, v172
	v_max3_f32 v169, v64, v65, v169
	v_max3_f32 v172, v66, v67, v172
	v_max3_f32 v169, v68, v69, v169
	v_max_f32_e32 v169, v169, v172
	v_mul_f32_e32 v169, 0x3e000000, v169
	v_max_f32_e32 v169, v169, v146
	ds_bpermute_b32 v172, v1, v169
	s_waitcnt lgkmcnt(0)
	v_max_f32_e32 v169, v169, v172
	ds_bpermute_b32 v172, v114, v169
	s_waitcnt lgkmcnt(0)
	v_max_f32_e32 v169, v169, v172
	v_mul_f32_e32 v175, 0xbfb8aa3b, v169
	v_mov_b32_e32 v170, 0
	v_mov_b32_e32 v171, 0
	v_fma_f32 v2, v2, s46, v175
	v_fma_f32 v3, v3, s46, v175
	v_fma_f32 v4, v4, s46, v175
	v_fma_f32 v5, v5, s46, v175
	v_exp_f32_e32 v2, v2
	v_exp_f32_e32 v3, v3
	v_exp_f32_e32 v4, v4
	v_exp_f32_e32 v5, v5
	v_fma_f32 v6, v6, s46, v175
	v_fma_f32 v7, v7, s46, v175
	v_fma_f32 v8, v8, s46, v175
	v_fma_f32 v9, v9, s46, v175
	v_exp_f32_e32 v6, v6
	v_exp_f32_e32 v7, v7
	v_exp_f32_e32 v8, v8
	v_exp_f32_e32 v9, v9
	v_add_f32_e32 v171, v171, v2
	v_add_f32_e32 v170, v170, v3
	v_add_f32_e32 v171, v171, v4
	v_add_f32_e32 v170, v170, v5
	v_fma_f32 v10, v10, s46, v175
	v_fma_f32 v11, v11, s46, v175
	v_fma_f32 v12, v12, s46, v175
	v_fma_f32 v13, v13, s46, v175
	v_exp_f32_e32 v10, v10
	v_exp_f32_e32 v11, v11
	v_exp_f32_e32 v12, v12
	v_exp_f32_e32 v13, v13
	v_add_f32_e32 v171, v171, v6
	v_add_f32_e32 v170, v170, v7
	v_add_f32_e32 v171, v171, v8
	v_add_f32_e32 v170, v170, v9
	v_fma_f32 v14, v14, s46, v175
	v_fma_f32 v15, v15, s46, v175
	v_fma_f32 v16, v16, s46, v175
	v_fma_f32 v17, v17, s46, v175
	v_exp_f32_e32 v14, v14
	v_exp_f32_e32 v15, v15
	v_exp_f32_e32 v16, v16
	v_exp_f32_e32 v17, v17
	v_add_f32_e32 v171, v171, v10
	v_add_f32_e32 v170, v170, v11
	v_add_f32_e32 v171, v171, v12
	v_add_f32_e32 v170, v170, v13
	v_fma_f32 v18, v18, s46, v175
	v_fma_f32 v19, v19, s46, v175
	v_fma_f32 v20, v20, s46, v175
	v_fma_f32 v21, v21, s46, v175
	v_exp_f32_e32 v18, v18
	v_exp_f32_e32 v19, v19
	v_exp_f32_e32 v20, v20
	v_exp_f32_e32 v21, v21
	v_add_f32_e32 v171, v171, v14
	v_add_f32_e32 v170, v170, v15
	v_add_f32_e32 v171, v171, v16
	v_add_f32_e32 v170, v170, v17
	v_fma_f32 v22, v22, s46, v175
	v_fma_f32 v23, v23, s46, v175
	v_fma_f32 v24, v24, s46, v175
	v_fma_f32 v25, v25, s46, v175
	v_exp_f32_e32 v22, v22
	v_exp_f32_e32 v23, v23
	v_exp_f32_e32 v24, v24
	v_exp_f32_e32 v25, v25
	v_add_f32_e32 v171, v171, v18
; __device__ __forceinline__ unsigned cvt_pk_bf16_asm(float lo, float hi) { unsigned r; asm volatile("v_cvt_pk_bf16_f32 %0, %1, %2" : "=v"(r) : "v"(lo), "v"(hi)); return r; }
; __device__ void att_phase(int wv, const Params& p, unsigned char* lds) {
;     ...
;             for (int cb = 0; cb < 24; ++cb)
; #pragma unroll
;                 for (int j = 0; j < 4; ++j) { const float e = __expf(sc[cb][j] - mx); sc[cb][j] = e; sum += e; }
;             sum += __shfl_xor(sum, 16); sum += __shfl_xor(sum, 32);
;             sum += __expf(sink - mx);
;             const float inv = 1.0f / sum;
;             f32x4 oa[4];
; #pragma unroll
;             for (int db = 0; db < 4; ++db) oa[db] = (f32x4){0, 0, 0, 0};
; #pragma unroll
;             for (int ks = 0; ks < 12; ++ks) {
;                 union { bf16x8 v; unsigned u[4]; } pf;
;                 pf.u[0] = cvt_pk_bf16_asm(sc[2 * ks][0], sc[2 * ks][1]); pf.u[1] = cvt_pk_bf16_asm(sc[2 * ks][2], sc[2 * ks][3]);
;                 pf.u[2] = cvt_pk_bf16_asm(sc[2 * ks + 1][0], sc[2 * ks + 1][1]); pf.u[3] = cvt_pk_bf16_asm(sc[2 * ks + 1][2], sc[2 * ks + 1][3]);
	v_add_f32_e32 v170, v170, v19
	v_add_f32_e32 v171, v171, v20
	v_add_f32_e32 v170, v170, v21
	v_fma_f32 v26, v26, s46, v175
	v_fma_f32 v27, v27, s46, v175
	v_fma_f32 v28, v28, s46, v175
	v_fma_f32 v29, v29, s46, v175
	v_exp_f32_e32 v26, v26
	v_exp_f32_e32 v27, v27
	v_exp_f32_e32 v28, v28
	v_exp_f32_e32 v29, v29
	v_add_f32_e32 v171, v171, v22
	v_add_f32_e32 v170, v170, v23
	v_add_f32_e32 v171, v171, v24
	v_add_f32_e32 v170, v170, v25
	v_fma_f32 v30, v30, s46, v175
	v_fma_f32 v31, v31, s46, v175
	v_fma_f32 v32, v32, s46, v175
	v_fma_f32 v33, v33, s46, v175
	v_exp_f32_e32 v30, v30
	v_exp_f32_e32 v31, v31
	v_exp_f32_e32 v32, v32
	v_exp_f32_e32 v33, v33
	v_add_f32_e32 v171, v171, v26
	v_add_f32_e32 v170, v170, v27
	v_add_f32_e32 v171, v171, v28
	v_add_f32_e32 v170, v170, v29
	v_fma_f32 v34, v34, s46, v175
	v_fma_f32 v35, v35, s46, v175
	v_fma_f32 v36, v36, s46, v175
	v_fma_f32 v37, v37, s46, v175
	v_exp_f32_e32 v34, v34
	v_exp_f32_e32 v35, v35
	v_exp_f32_e32 v36, v36
	v_exp_f32_e32 v37, v37
	v_add_f32_e32 v171, v171, v30
	v_add_f32_e32 v170, v170, v31
	v_add_f32_e32 v171, v171, v32
	v_add_f32_e32 v170, v170, v33
	v_fma_f32 v38, v38, s46, v175
	v_fma_f32 v39, v39, s46, v175
	v_fma_f32 v40, v40, s46, v175
	v_fma_f32 v41, v41, s46, v175
	v_exp_f32_e32 v38, v38
	v_exp_f32_e32 v39, v39
	v_exp_f32_e32 v40, v40
	v_exp_f32_e32 v41, v41
	v_add_f32_e32 v171, v171, v34
	v_add_f32_e32 v170, v170, v35
	v_add_f32_e32 v171, v171, v36
	v_add_f32_e32 v170, v170, v37
	v_fma_f32 v42, v42, s46, v175
	v_fma_f32 v43, v43, s46, v175
	v_fma_f32 v44, v44, s46, v175
	v_fma_f32 v45, v45, s46, v175
	v_exp_f32_e32 v42, v42
	v_exp_f32_e32 v43, v43
	v_exp_f32_e32 v44, v44
	v_exp_f32_e32 v45, v45
	v_add_f32_e32 v171, v171, v38
	v_add_f32_e32 v170, v170, v39
	v_add_f32_e32 v171, v171, v40
	v_add_f32_e32 v170, v170, v41
	v_fma_f32 v46, v46, s46, v175
	v_fma_f32 v47, v47, s46, v175
	v_fma_f32 v48, v48, s46, v175
	v_fma_f32 v49, v49, s46, v175
	v_exp_f32_e32 v46, v46
	v_exp_f32_e32 v47, v47
	v_exp_f32_e32 v48, v48
	v_exp_f32_e32 v49, v49
	v_add_f32_e32 v171, v171, v42
	v_add_f32_e32 v170, v170, v43
	v_add_f32_e32 v171, v171, v44
	v_add_f32_e32 v170, v170, v45
	v_fma_f32 v50, v50, s46, v175
	v_fma_f32 v51, v51, s46, v175
	v_fma_f32 v52, v52, s46, v175
	v_fma_f32 v53, v53, s46, v175
	v_exp_f32_e32 v50, v50
	v_exp_f32_e32 v51, v51
	v_exp_f32_e32 v52, v52
	v_exp_f32_e32 v53, v53
	v_add_f32_e32 v171, v171, v46
	v_add_f32_e32 v170, v170, v47
	v_add_f32_e32 v171, v171, v48
	v_add_f32_e32 v170, v170, v49
	v_fma_f32 v54, v54, s46, v175
	v_fma_f32 v55, v55, s46, v175
	v_fma_f32 v56, v56, s46, v175
	v_fma_f32 v57, v57, s46, v175
	v_exp_f32_e32 v54, v54
	v_exp_f32_e32 v55, v55
	v_exp_f32_e32 v56, v56
	v_exp_f32_e32 v57, v57
	v_add_f32_e32 v171, v171, v50
	v_add_f32_e32 v170, v170, v51
	v_add_f32_e32 v171, v171, v52
	v_add_f32_e32 v170, v170, v53
	v_fma_f32 v58, v58, s46, v175
	v_fma_f32 v59, v59, s46, v175
	v_fma_f32 v60, v60, s46, v175
	v_fma_f32 v61, v61, s46, v175
	v_exp_f32_e32 v58, v58
	v_exp_f32_e32 v59, v59
	v_exp_f32_e32 v60, v60
	v_exp_f32_e32 v61, v61
	v_add_f32_e32 v171, v171, v54
	v_add_f32_e32 v170, v170, v55
	v_add_f32_e32 v171, v171, v56
	v_add_f32_e32 v170, v170, v57
	v_fma_f32 v62, v62, s46, v175
	v_fma_f32 v63, v63, s46, v175
	v_fma_f32 v64, v64, s46, v175
	v_fma_f32 v65, v65, s46, v175
	v_exp_f32_e32 v62, v62
	v_exp_f32_e32 v63, v63
	v_exp_f32_e32 v64, v64
	v_exp_f32_e32 v65, v65
	v_add_f32_e32 v171, v171, v58
	v_add_f32_e32 v170, v170, v59
	v_add_f32_e32 v171, v171, v60
	v_add_f32_e32 v170, v170, v61
	v_fma_f32 v66, v66, s46, v175
	v_fma_f32 v67, v67, s46, v175
	v_fma_f32 v68, v68, s46, v175
	v_fma_f32 v69, v69, s46, v175
	v_exp_f32_e32 v66, v66
	v_exp_f32_e32 v67, v67
	v_exp_f32_e32 v68, v68
	v_exp_f32_e32 v69, v69
	v_add_f32_e32 v171, v171, v62
	v_add_f32_e32 v170, v170, v63
	v_add_f32_e32 v171, v171, v64
	v_add_f32_e32 v170, v170, v65
	v_add_f32_e32 v171, v171, v66
	v_add_f32_e32 v170, v170, v67
	v_add_f32_e32 v171, v171, v68
	v_add_f32_e32 v170, v170, v69
	v_add_f32_e32 v170, v170, v171
	v_cvt_pk_bf16_f32 v2, v2, v3
	v_cvt_pk_bf16_f32 v3, v4, v5
	v_cvt_pk_bf16_f32 v4, v6, v7
	v_cvt_pk_bf16_f32 v5, v8, v9
	v_cvt_pk_bf16_f32 v10, v10, v11
	v_cvt_pk_bf16_f32 v11, v12, v13
	v_cvt_pk_bf16_f32 v12, v14, v15
	v_cvt_pk_bf16_f32 v13, v16, v17
	v_cvt_pk_bf16_f32 v18, v18, v19
	v_cvt_pk_bf16_f32 v19, v20, v21
	v_cvt_pk_bf16_f32 v20, v22, v23
	v_cvt_pk_bf16_f32 v21, v24, v25
	v_cvt_pk_bf16_f32 v26, v26, v27
	v_cvt_pk_bf16_f32 v27, v28, v29
	v_cvt_pk_bf16_f32 v28, v30, v31
	v_cvt_pk_bf16_f32 v29, v32, v33
	v_cvt_pk_bf16_f32 v34, v34, v35
	v_cvt_pk_bf16_f32 v35, v36, v37
	v_cvt_pk_bf16_f32 v36, v38, v39
	v_cvt_pk_bf16_f32 v37, v40, v41
	v_cvt_pk_bf16_f32 v42, v42, v43
	v_cvt_pk_bf16_f32 v43, v44, v45
	v_cvt_pk_bf16_f32 v44, v46, v47
	v_cvt_pk_bf16_f32 v45, v48, v49
	v_cvt_pk_bf16_f32 v50, v50, v51
	v_cvt_pk_bf16_f32 v51, v52, v53
	v_cvt_pk_bf16_f32 v52, v54, v55
	v_cvt_pk_bf16_f32 v53, v56, v57
	v_cvt_pk_bf16_f32 v58, v58, v59
	v_cvt_pk_bf16_f32 v59, v60, v61
	v_cvt_pk_bf16_f32 v60, v62, v63
	v_cvt_pk_bf16_f32 v61, v64, v65
	v_cvt_pk_bf16_f32 v66, v66, v67
	v_cvt_pk_bf16_f32 v67, v68, v69
	v_mov_b32_e32 v68, 0
	v_mov_b32_e32 v69, 0
	ds_bpermute_b32 v172, v1, v170
	v_sub_f32_e32 v173, v146, v169
	v_mul_f32_e32 v173, 0x3fb8aa3b, v173
	v_exp_f32_e32 v173, v173
	s_waitcnt lgkmcnt(0)
; __device__ __forceinline__ unsigned cvt_pk_bf16_asm(float lo, float hi) { unsigned r; asm volatile("v_cvt_pk_bf16_f32 %0, %1, %2" : "=v"(r) : "v"(lo), "v"(hi)); return r; }
; __device__ __forceinline__ f32x4 mfma16(bf16x8 a, bf16x8 b, f32x4 c) { return __builtin_amdgcn_mfma_f32_16x16x32_bf16(a, b, c, 0, 0, 0); }
; __device__ void att_phase(int wv, const Params& p, unsigned char* lds) {
;     ...
;             sum += __shfl_xor(sum, 16); sum += __shfl_xor(sum, 32);
;             sum += __expf(sink - mx);
;             const float inv = 1.0f / sum;
;             f32x4 oa[4];
; #pragma unroll
;             for (int db = 0; db < 4; ++db) oa[db] = (f32x4){0, 0, 0, 0};
; #pragma unroll
;             for (int ks = 0; ks < 12; ++ks) {
;                 union { bf16x8 v; unsigned u[4]; } pf;
;                 pf.u[0] = cvt_pk_bf16_asm(sc[2 * ks][0], sc[2 * ks][1]); pf.u[1] = cvt_pk_bf16_asm(sc[2 * ks][2], sc[2 * ks][3]);
;                 pf.u[2] = cvt_pk_bf16_asm(sc[2 * ks + 1][0], sc[2 * ks + 1][1]); pf.u[3] = cvt_pk_bf16_asm(sc[2 * ks + 1][2], sc[2 * ks + 1][3]);
; #pragma unroll
;                 for (int db = 0; db < 4; ++db) {
;                     union { bf16x8 v; u32x2 h2[2]; } vf;
;                     const bf16_t* vp = VTL + (16 * db + lr) * VP + 32 * ks + 4 * lq;
;                     vf.h2[0] = *(const u32x2*)vp; vf.h2[1] = *(const u32x2*)(vp + 16);
;                     oa[db] = mfma16(vf.v, pf.v, oa[db]); } }
; #pragma unroll
;             for (int db = 0; db < 4; ++db) { const f32x4 o = oa[db] * inv; u32x2 wv; wv.x = cvt_pk_bf16_asm(o[0], o[1]); wv.y = cvt_pk_bf16_asm(o[2], o[3]);
;                 *(u32x2*)(qkv + tokq * 1536 + 64 * h + 16 * db + 4 * lq) = wv; }
	v_add_f32_e32 v170, v170, v172
	ds_bpermute_b32 v172, v114, v170
	ds_read2_b64 v[232:235], v165 offset0:20 offset1:24
	ds_read2_b64 v[236:239], v166 offset0:20 offset1:24
	ds_read2_b64 v[240:243], v167 offset0:20 offset1:24
	ds_read2_b64 v[244:247], v168 offset0:20 offset1:24
	s_waitcnt lgkmcnt(4)
	v_mfma_f32_16x16x32_bf16 v[70:73], v[216:219], v[2:5], 0
	v_mfma_f32_16x16x32_bf16 v[74:77], v[220:223], v[2:5], 0
	v_mfma_f32_16x16x32_bf16 v[78:81], v[224:227], v[2:5], 0
	v_mfma_f32_16x16x32_bf16 v[82:85], v[228:231], v[2:5], 0
	v_add_f32_e32 v170, v170, v172
	v_add_f32_e32 v170, v170, v173
	v_rcp_f32_e32 v147, v170
	s_nop 0
	v_fma_f32 v179, -v170, v147, 1.0
	v_fmac_f32_e32 v147, v179, v147
	ds_read2_b64 v[216:219], v165 offset0:28 offset1:32
	ds_read2_b64 v[220:223], v166 offset0:28 offset1:32
	ds_read2_b64 v[224:227], v167 offset0:28 offset1:32
	ds_read2_b64 v[228:231], v168 offset0:28 offset1:32
	s_waitcnt lgkmcnt(4)
	v_mfma_f32_16x16x32_bf16 v[70:73], v[232:235], v[10:13], v[70:73]
	v_mfma_f32_16x16x32_bf16 v[74:77], v[236:239], v[10:13], v[74:77]
	v_mfma_f32_16x16x32_bf16 v[78:81], v[240:243], v[10:13], v[78:81]
	v_mfma_f32_16x16x32_bf16 v[82:85], v[244:247], v[10:13], v[82:85]
	ds_read2_b64 v[232:235], v165 offset0:36 offset1:40
	ds_read2_b64 v[236:239], v166 offset0:36 offset1:40
	ds_read2_b64 v[240:243], v167 offset0:36 offset1:40
	ds_read2_b64 v[244:247], v168 offset0:36 offset1:40
	s_waitcnt lgkmcnt(4)
	v_mfma_f32_16x16x32_bf16 v[70:73], v[216:219], v[18:21], v[70:73]
	v_mfma_f32_16x16x32_bf16 v[74:77], v[220:223], v[18:21], v[74:77]
	v_mfma_f32_16x16x32_bf16 v[78:81], v[224:227], v[18:21], v[78:81]
	v_mfma_f32_16x16x32_bf16 v[82:85], v[228:231], v[18:21], v[82:85]
	ds_read2_b64 v[216:219], v165 offset0:44 offset1:48
	ds_read2_b64 v[220:223], v166 offset0:44 offset1:48
	ds_read2_b64 v[224:227], v167 offset0:44 offset1:48
	ds_read2_b64 v[228:231], v168 offset0:44 offset1:48
	s_waitcnt lgkmcnt(4)
	v_mfma_f32_16x16x32_bf16 v[70:73], v[232:235], v[26:29], v[70:73]
	v_mfma_f32_16x16x32_bf16 v[74:77], v[236:239], v[26:29], v[74:77]
	v_mfma_f32_16x16x32_bf16 v[78:81], v[240:243], v[26:29], v[78:81]
	v_mfma_f32_16x16x32_bf16 v[82:85], v[244:247], v[26:29], v[82:85]
	ds_read2_b64 v[232:235], v165 offset0:52 offset1:56
	ds_read2_b64 v[236:239], v166 offset0:52 offset1:56
	ds_read2_b64 v[240:243], v167 offset0:52 offset1:56
	ds_read2_b64 v[244:247], v168 offset0:52 offset1:56
	s_waitcnt lgkmcnt(4)
	v_mfma_f32_16x16x32_bf16 v[70:73], v[216:219], v[34:37], v[70:73]
	v_mfma_f32_16x16x32_bf16 v[74:77], v[220:223], v[34:37], v[74:77]
	v_mfma_f32_16x16x32_bf16 v[78:81], v[224:227], v[34:37], v[78:81]
	v_mfma_f32_16x16x32_bf16 v[82:85], v[228:231], v[34:37], v[82:85]
	ds_read2_b64 v[216:219], v165 offset0:60 offset1:64
	ds_read2_b64 v[220:223], v166 offset0:60 offset1:64
	ds_read2_b64 v[224:227], v167 offset0:60 offset1:64
	ds_read2_b64 v[228:231], v168 offset0:60 offset1:64
	s_waitcnt lgkmcnt(4)
	v_mfma_f32_16x16x32_bf16 v[70:73], v[232:235], v[42:45], v[70:73]
	v_mfma_f32_16x16x32_bf16 v[74:77], v[236:239], v[42:45], v[74:77]
	v_mfma_f32_16x16x32_bf16 v[78:81], v[240:243], v[42:45], v[78:81]
	v_mfma_f32_16x16x32_bf16 v[82:85], v[244:247], v[42:45], v[82:85]
	ds_read2_b64 v[232:235], v165 offset0:68 offset1:72
	ds_read2_b64 v[236:239], v166 offset0:68 offset1:72
	ds_read2_b64 v[240:243], v167 offset0:68 offset1:72
	ds_read2_b64 v[244:247], v168 offset0:68 offset1:72
	s_waitcnt lgkmcnt(4)
	v_mfma_f32_16x16x32_bf16 v[70:73], v[216:219], v[50:53], v[70:73]
	v_mfma_f32_16x16x32_bf16 v[74:77], v[220:223], v[50:53], v[74:77]
	v_mfma_f32_16x16x32_bf16 v[78:81], v[224:227], v[50:53], v[78:81]
	v_mfma_f32_16x16x32_bf16 v[82:85], v[228:231], v[50:53], v[82:85]
	ds_read2_b64 v[216:219], v165 offset0:76 offset1:76
	ds_read2_b64 v[220:223], v166 offset0:76 offset1:76
	ds_read2_b64 v[224:227], v167 offset0:76 offset1:76
	ds_read2_b64 v[228:231], v168 offset0:76 offset1:76
	s_waitcnt lgkmcnt(4)
	v_mfma_f32_16x16x32_bf16 v[70:73], v[232:235], v[58:61], v[70:73]
	v_mfma_f32_16x16x32_bf16 v[74:77], v[236:239], v[58:61], v[74:77]
	v_mfma_f32_16x16x32_bf16 v[78:81], v[240:243], v[58:61], v[78:81]
	v_mfma_f32_16x16x32_bf16 v[82:85], v[244:247], v[58:61], v[82:85]
	s_waitcnt lgkmcnt(0)
	v_mfma_f32_16x16x32_bf16 v[70:73], v[216:219], v[66:69], v[70:73]
	v_mfma_f32_16x16x32_bf16 v[74:77], v[220:223], v[66:69], v[74:77]
	v_mfma_f32_16x16x32_bf16 v[78:81], v[224:227], v[66:69], v[78:81]
	v_mfma_f32_16x16x32_bf16 v[82:85], v[228:231], v[66:69], v[82:85]
	s_nop 7
	s_nop 1
	v_mul_f32_e32 v70, v70, v147
	v_mul_f32_e32 v71, v71, v147
	v_mul_f32_e32 v72, v72, v147
	v_mul_f32_e32 v73, v73, v147
	v_mul_f32_e32 v74, v74, v147
	v_mul_f32_e32 v75, v75, v147
	v_mul_f32_e32 v76, v76, v147
	v_mul_f32_e32 v77, v77, v147
	v_mul_f32_e32 v78, v78, v147
	v_mul_f32_e32 v79, v79, v147
	v_mul_f32_e32 v80, v80, v147
	v_mul_f32_e32 v81, v81, v147
	v_mul_f32_e32 v82, v82, v147
	v_mul_f32_e32 v83, v83, v147
	v_mul_f32_e32 v84, v84, v147
	v_mul_f32_e32 v85, v85, v147
	v_cvt_pk_bf16_f32 v70, v70, v71
	v_cvt_pk_bf16_f32 v71, v72, v73
	v_cvt_pk_bf16_f32 v74, v74, v75
	v_cvt_pk_bf16_f32 v75, v76, v77
	v_cvt_pk_bf16_f32 v78, v78, v79
	v_cvt_pk_bf16_f32 v79, v80, v81
	v_cvt_pk_bf16_f32 v82, v82, v83
	v_cvt_pk_bf16_f32 v83, v84, v85
	global_store_dwordx2 v[248:249], v[70:71], off offset:-64
	global_store_dwordx2 v[248:249], v[74:75], off offset:-32
	global_store_dwordx2 v[248:249], v[78:79], off
	global_store_dwordx2 v[248:249], v[82:83], off offset:32
	s_branch .Latt_done
